# MFMA issue order inside each K-half changed to a snake (every consecutive MFMA pair shares one source fragment) in w_in, w_out, down, up loops
# speedup vs baseline: 1.0045x; 1.0045x over previous
; #define PG8_STAGE(bufoff, gbase, voff) do { _Pragma("unroll") for (int _i = 0; _i < 2; ++_i) \
;         __builtin_amdgcn_global_load_lds((const unsigned*)((const char*)(gbase) + (voff)[_i]), (PG8_LAS unsigned*)(lds + (bufoff) + ldsw + _i * 8192), 16, 0, 0); } while (0)
; #define PG8_LDA(dst, b, h) do { _Pragma("unroll") for (int m = 0; m < 4; ++m) _Pragma("unroll") for (int k = 0; k < 2; ++k) dst[m][k] = *(const PG8_LAS bf16x8*)(lds + PG8_SA(b, h) + aoff + m * 2048 + k * 1024); } while (0)
; #define PG8_LDB(dst, b, h) do { _Pragma("unroll") for (int n = 0; n < 2; ++n) _Pragma("unroll") for (int k = 0; k < 2; ++k) dst[n][k] = *(const PG8_LAS bf16x8*)(lds + PG8_SB(b, h) + boff + n * 2048 + k * 1024); } while (0)
; #define PG8_MMA(ai, bj, At, Bt) do { __builtin_amdgcn_s_setprio(1); _Pragma("unroll") for (int m = 0; m < 4; ++m) _Pragma("unroll") for (int n = 0; n < 2; ++n) _Pragma("unroll") for (int k = 0; k < 2; ++k) \
;         acc[ai][bj][m][n] = __builtin_amdgcn_mfma_f32_16x16x32_bf16(Bt[n][k], At[m][k], acc[ai][bj][m][n], 0, 0, 0); __builtin_amdgcn_s_setprio(0); } while (0)
; #define PG8_WAIT_V(n) asm volatile("s_waitcnt vmcnt(" #n ")" ::: "memory")
; #define PG8_WAIT_L(n) asm volatile("s_waitcnt lgkmcnt(" #n ")" ::: "memory")
; #define PG8_BAR __builtin_amdgcn_s_barrier()
; template <class Epi, class Sched, bool ALIGN_EPI = false, bool SP2 = false>
; __device__ __forceinline__ void gemm_phase(PG8_LAS unsigned char* lds, const Gemm g, const Sched& S, const Epi& E) {
;     ...
;         const bool has_next = S.next(ui + 1, nxt);
;         const char* nA = has_next ? (const char*)g.A + (size_t)nxt.pm * tstep : cA; const char* nB = has_next ? (const char*)g.Bt + (size_t)nxt.pn * tstep : cB;
;         for (int t = 0; t < nt; t += 2) {
;             const bool last = (t == nt - 2);
;             const char* a1 = cA + (size_t)(t + 1) * kstep;
;             const char* a2 = last ? nA : cA + (size_t)(t + 2) * kstep; const char* b2 = last ? nB : cB + (size_t)(t + 2) * kstep;
;             const char* a3 = a2 + kstep; const char* b3 = b2 + kstep;
;             if (last && has_next) S.a_ready(nxt);
;             if constexpr (SP2) {
;             PG8_LDB(B0, 0, 0); PG8_LDB(B1, 0, 1); PG8_SCHED; PG8_LDA(At, 0, 0); PG8_STAGE(PG8_SA(1, 1), a1 + hstep, voffA);
;             PG8_WAIT_V(8); PG8_WAIT_L(0); PG8_BAR; PG8_MMA(0, 0, At, B0); PG8_MMA(0, 1, At, B1); PG8_BAR; PG8_SCHED;
.LBB0_169:
	s_add_u32 s93, s46, 0x100
	s_addc_u32 s94, s47, 0
	s_ashr_i32 s69, s68, 31
	s_lshl_b64 s[4:5], s[68:69], 20
	s_add_u32 s76, s52, s4
	s_addc_u32 s77, s53, s5
	s_and_b64 s[4:5], s[38:39], exec
	s_cselect_b32 s4, s77, s71
	s_cselect_b32 s5, s76, s70
	s_ashr_i32 s63, s62, 31
	s_lshl_b64 s[6:7], s[62:63], 20
	v_readlane_b32 s8, v249, 19
	v_readlane_b32 s9, v249, 20
	s_add_u32 s72, s8, s6
	s_addc_u32 s73, s9, s7
	s_and_b64 s[6:7], s[38:39], exec
	s_cselect_b32 s6, s73, s47
	s_cselect_b32 s7, s72, s46
	s_add_u32 s8, s70, 0x80080
	s_addc_u32 s9, s71, 0
	v_lshl_add_u64 v[144:145], s[8:9], 0, v[140:141]
	v_lshl_add_u64 v[146:147], s[8:9], 0, v[142:143]
	s_mov_b32 s8, -2
	s_mov_b64 s[46:47], 0
	v_add_u32_e32 v186, 0x10000, v139
	v_add_u32_e32 v187, 0x14000, v139
	v_add_u32_e32 v198, 0x18000, v139
	v_add_u32_e32 v199, 0x1c000, v139
	s_add_u32 s9, s70, s46
	s_addc_u32 s10, s71, s47
	s_add_u32 s9, s9, 0x100
	s_addc_u32 s10, s10, 0
	s_add_u32 s100, s9, 0x7ff80
	s_addc_u32 s101, s10, 0
	s_add_u32 s11, s93, s46
	s_addc_u32 s12, s94, s47
	s_add_i32 s13, 0, 0x10000
	s_cmpk_eq_i32 s46, 0xf00
	s_cselect_b32 s85, s4, s10
	s_cselect_b32 s84, s5, s9
	s_cselect_b32 s81, s6, s12
	s_cselect_b32 s80, s7, s11
	s_add_i32 s9, 0, 0x14000
	ds_read_b128 v[148:151], v186
	ds_read_b128 v[152:155], v186 offset:1024
	ds_read_b128 v[156:159], v186 offset:2048
	ds_read_b128 v[160:163], v186 offset:3072
	ds_read_b128 v[166:169], v187
	ds_read_b128 v[170:173], v187 offset:1024
	ds_read_b128 v[174:177], v187 offset:2048
	ds_read_b128 v[178:181], v187 offset:3072
	s_add_i32 m0, s1, 0xc000
	ds_read_b128 v[182:185], v165
	ds_read_b128 v[206:209], v165 offset:1024
	ds_read_b128 v[210:213], v165 offset:2048
	ds_read_b128 v[214:217], v165 offset:3072
	ds_read_b128 v[218:221], v165 offset:4096
	ds_read_b128 v[236:239], v165 offset:5120
	ds_read_b128 v[240:243], v165 offset:6144
	ds_read_b128 v[244:247], v165 offset:7168
	global_load_lds_dwordx4 v140, s[100:101]
	s_add_i32 m0, s1, 0xe000
	s_nop 0
	global_load_lds_dwordx4 v142, s[100:101]
	s_waitcnt vmcnt(8)
	s_waitcnt lgkmcnt(0)
	s_barrier
	v_mfma_f32_16x16x32_bf16 v[126:129], v[148:151], v[182:185], 0
	v_mfma_f32_16x16x32_bf16 v[122:125], v[156:159], v[182:185], 0
	v_mfma_f32_16x16x32_bf16 v[114:117], v[156:159], v[210:213], 0
	v_mfma_f32_16x16x32_bf16 v[118:121], v[148:151], v[210:213], 0
	v_mfma_f32_16x16x32_bf16 v[110:113], v[148:151], v[218:221], 0
	v_mfma_f32_16x16x32_bf16 v[106:109], v[156:159], v[218:221], 0
	v_mfma_f32_16x16x32_bf16 v[98:101], v[156:159], v[240:243], 0
	v_mfma_f32_16x16x32_bf16 v[102:105], v[148:151], v[240:243], 0
	v_mfma_f32_16x16x32_bf16 v[126:129], v[152:155], v[206:209], v[126:129]
	v_mfma_f32_16x16x32_bf16 v[122:125], v[160:163], v[206:209], v[122:125]
	v_mfma_f32_16x16x32_bf16 v[114:117], v[160:163], v[214:217], v[114:117]
	v_mfma_f32_16x16x32_bf16 v[118:121], v[152:155], v[214:217], v[118:121]
	v_mfma_f32_16x16x32_bf16 v[110:113], v[152:155], v[236:239], v[110:113]
	v_mfma_f32_16x16x32_bf16 v[106:109], v[160:163], v[236:239], v[106:109]
	v_mfma_f32_16x16x32_bf16 v[98:101], v[160:163], v[244:247], v[98:101]
	v_mfma_f32_16x16x32_bf16 v[102:105], v[152:155], v[244:247], v[102:105]
	v_mfma_f32_16x16x32_bf16 v[94:97], v[166:169], v[182:185], 0
	v_mfma_f32_16x16x32_bf16 v[90:93], v[174:177], v[182:185], 0
	v_mfma_f32_16x16x32_bf16 v[82:85], v[174:177], v[210:213], 0
	v_mfma_f32_16x16x32_bf16 v[86:89], v[166:169], v[210:213], 0
	v_mfma_f32_16x16x32_bf16 v[78:81], v[166:169], v[218:221], 0
	v_mfma_f32_16x16x32_bf16 v[74:77], v[174:177], v[218:221], 0
	v_mfma_f32_16x16x32_bf16 v[66:69], v[174:177], v[240:243], 0
	v_mfma_f32_16x16x32_bf16 v[70:73], v[166:169], v[240:243], 0
	v_mfma_f32_16x16x32_bf16 v[94:97], v[170:173], v[206:209], v[94:97]
	v_mfma_f32_16x16x32_bf16 v[90:93], v[178:181], v[206:209], v[90:93]
	v_mfma_f32_16x16x32_bf16 v[82:85], v[178:181], v[214:217], v[82:85]
	v_mfma_f32_16x16x32_bf16 v[86:89], v[170:173], v[214:217], v[86:89]
	v_mfma_f32_16x16x32_bf16 v[78:81], v[170:173], v[236:239], v[78:81]
	v_mfma_f32_16x16x32_bf16 v[74:77], v[178:181], v[236:239], v[74:77]
	v_mfma_f32_16x16x32_bf16 v[66:69], v[178:181], v[244:247], v[66:69]
	v_mfma_f32_16x16x32_bf16 v[70:73], v[170:173], v[244:247], v[70:73]
	s_barrier
	s_add_i32 s10, s13, s0
	s_mov_b32 m0, s10
	ds_read_b128 v[182:185], v165 offset:16384
	ds_read_b128 v[206:209], v165 offset:17408
	ds_read_b128 v[210:213], v165 offset:18432
	ds_read_b128 v[214:217], v165 offset:19456
	ds_read_b128 v[218:221], v165 offset:20480
	ds_read_b128 v[236:239], v165 offset:21504
	ds_read_b128 v[240:243], v165 offset:22528
	ds_read_b128 v[244:247], v165 offset:23552
	global_load_lds_dwordx4 v132, s[80:81]
	s_add_i32 m0, s10, 0x2000
	s_add_u32 s10, s80, 0x20000
	s_addc_u32 s11, s81, 0
	s_add_i32 s9, s9, s0
	global_load_lds_dwordx4 v136, s[80:81]
	s_mov_b32 m0, s9
	s_nop 0
	global_load_lds_dwordx4 v132, s[10:11]
	s_add_i32 m0, s9, 0x2000
	s_nop 0
	global_load_lds_dwordx4 v136, s[10:11]
	s_mov_b32 m0, s1
	s_nop 0
	global_load_lds_dwordx4 v130, s[84:85]
	s_mov_b32 m0, s25
	s_nop 0
	global_load_lds_dwordx4 v134, s[84:85]
	s_waitcnt vmcnt(8)
	s_waitcnt lgkmcnt(0)
	s_barrier
; #define PG8_STAGE(bufoff, gbase, voff) do { _Pragma("unroll") for (int _i = 0; _i < 2; ++_i) \
;         __builtin_amdgcn_global_load_lds((const unsigned*)((const char*)(gbase) + (voff)[_i]), (PG8_LAS unsigned*)(lds + (bufoff) + ldsw + _i * 8192), 16, 0, 0); } while (0)
; #define PG8_LDA(dst, b, h) do { _Pragma("unroll") for (int m = 0; m < 4; ++m) _Pragma("unroll") for (int k = 0; k < 2; ++k) dst[m][k] = *(const PG8_LAS bf16x8*)(lds + PG8_SA(b, h) + aoff + m * 2048 + k * 1024); } while (0)
; #define PG8_LDB(dst, b, h) do { _Pragma("unroll") for (int n = 0; n < 2; ++n) _Pragma("unroll") for (int k = 0; k < 2; ++k) dst[n][k] = *(const PG8_LAS bf16x8*)(lds + PG8_SB(b, h) + boff + n * 2048 + k * 1024); } while (0)
; #define PG8_MMA(ai, bj, At, Bt) do { __builtin_amdgcn_s_setprio(1); _Pragma("unroll") for (int m = 0; m < 4; ++m) _Pragma("unroll") for (int n = 0; n < 2; ++n) _Pragma("unroll") for (int k = 0; k < 2; ++k) \
;         acc[ai][bj][m][n] = __builtin_amdgcn_mfma_f32_16x16x32_bf16(Bt[n][k], At[m][k], acc[ai][bj][m][n], 0, 0, 0); __builtin_amdgcn_s_setprio(0); } while (0)
; #define PG8_WAIT_V(n) asm volatile("s_waitcnt vmcnt(" #n ")" ::: "memory")
; #define PG8_WAIT_L(n) asm volatile("s_waitcnt lgkmcnt(" #n ")" ::: "memory")
; #define PG8_BAR __builtin_amdgcn_s_barrier()
; #define PG8_SCHED __builtin_amdgcn_sched_barrier(0)
; template <class Epi, class Sched, bool ALIGN_EPI = false, bool SP2 = false>
; __device__ __forceinline__ void gemm_phase(PG8_LAS unsigned char* lds, const Gemm g, const Sched& S, const Epi& E) {
;     ...
;             PG8_LDA(At, 0, 1); PG8_STAGE(PG8_SB(0, 0), b2, voffB); PG8_STAGE(PG8_SB(0, 1), b2 + hstepB, voffB); PG8_STAGE(PG8_SA(0, 0), a2, voffA);
;             PG8_WAIT_V(8); PG8_WAIT_L(0); PG8_BAR; PG8_MMA(1, 0, At, B0); PG8_MMA(1, 1, At, B1); PG8_BAR; PG8_SCHED;
;             PG8_LDB(B0, 1, 0); PG8_LDB(B1, 1, 1); PG8_SCHED; PG8_LDA(At, 1, 0); PG8_STAGE(PG8_SA(0, 1), a2 + hstep, voffA);
;             PG8_WAIT_V(8); PG8_WAIT_L(0); PG8_BAR; PG8_MMA(0, 0, At, B0); PG8_MMA(0, 1, At, B1); PG8_BAR; PG8_SCHED;
	v_mfma_f32_16x16x32_bf16 v[62:65], v[148:151], v[182:185], 0
	v_mfma_f32_16x16x32_bf16 v[58:61], v[156:159], v[182:185], 0
	v_mfma_f32_16x16x32_bf16 v[50:53], v[156:159], v[210:213], 0
	v_mfma_f32_16x16x32_bf16 v[54:57], v[148:151], v[210:213], 0
	v_mfma_f32_16x16x32_bf16 v[46:49], v[148:151], v[218:221], 0
	v_mfma_f32_16x16x32_bf16 v[42:45], v[156:159], v[218:221], 0
	v_mfma_f32_16x16x32_bf16 v[34:37], v[156:159], v[240:243], 0
	v_mfma_f32_16x16x32_bf16 v[38:41], v[148:151], v[240:243], 0
	v_mfma_f32_16x16x32_bf16 v[62:65], v[152:155], v[206:209], v[62:65]
	v_mfma_f32_16x16x32_bf16 v[58:61], v[160:163], v[206:209], v[58:61]
	v_mfma_f32_16x16x32_bf16 v[50:53], v[160:163], v[214:217], v[50:53]
	v_mfma_f32_16x16x32_bf16 v[54:57], v[152:155], v[214:217], v[54:57]
	v_mfma_f32_16x16x32_bf16 v[46:49], v[152:155], v[236:239], v[46:49]
	v_mfma_f32_16x16x32_bf16 v[42:45], v[160:163], v[236:239], v[42:45]
	v_mfma_f32_16x16x32_bf16 v[34:37], v[160:163], v[244:247], v[34:37]
	v_mfma_f32_16x16x32_bf16 v[38:41], v[152:155], v[244:247], v[38:41]
	v_mfma_f32_16x16x32_bf16 v[30:33], v[166:169], v[182:185], 0
	v_mfma_f32_16x16x32_bf16 v[26:29], v[174:177], v[182:185], 0
	v_mfma_f32_16x16x32_bf16 v[18:21], v[174:177], v[210:213], 0
	v_mfma_f32_16x16x32_bf16 v[22:25], v[166:169], v[210:213], 0
	v_mfma_f32_16x16x32_bf16 v[14:17], v[166:169], v[218:221], 0
	v_mfma_f32_16x16x32_bf16 v[10:13], v[174:177], v[218:221], 0
	v_mfma_f32_16x16x32_bf16 v[2:5], v[174:177], v[240:243], 0
	v_mfma_f32_16x16x32_bf16 v[6:9], v[166:169], v[240:243], 0
	v_mfma_f32_16x16x32_bf16 v[30:33], v[170:173], v[206:209], v[30:33]
	v_mfma_f32_16x16x32_bf16 v[26:29], v[178:181], v[206:209], v[26:29]
	v_mfma_f32_16x16x32_bf16 v[18:21], v[178:181], v[214:217], v[18:21]
	v_mfma_f32_16x16x32_bf16 v[22:25], v[170:173], v[214:217], v[22:25]
	v_mfma_f32_16x16x32_bf16 v[14:17], v[170:173], v[236:239], v[14:17]
	v_mfma_f32_16x16x32_bf16 v[10:13], v[178:181], v[236:239], v[10:13]
	v_mfma_f32_16x16x32_bf16 v[2:5], v[178:181], v[244:247], v[2:5]
	v_mfma_f32_16x16x32_bf16 v[6:9], v[170:173], v[244:247], v[6:9]
	s_barrier
	s_add_i32 s9, 0, 0x18000
	s_add_i32 s12, 0, 0x1c000
	ds_read_b128 v[148:151], v198
	ds_read_b128 v[152:155], v198 offset:1024
	ds_read_b128 v[156:159], v198 offset:2048
	ds_read_b128 v[160:163], v198 offset:3072
	ds_read_b128 v[166:169], v199
	ds_read_b128 v[170:173], v199 offset:1024
	ds_read_b128 v[174:177], v199 offset:2048
	ds_read_b128 v[178:181], v199 offset:3072
	s_add_u32 s10, s84, 0x80000
	s_addc_u32 s11, s85, 0
	s_mov_b32 m0, s42
	ds_read_b128 v[182:185], v165 offset:32768
	ds_read_b128 v[206:209], v165 offset:33792
	ds_read_b128 v[210:213], v165 offset:34816
	ds_read_b128 v[214:217], v165 offset:35840
	ds_read_b128 v[218:221], v165 offset:36864
	ds_read_b128 v[236:239], v165 offset:37888
	ds_read_b128 v[240:243], v165 offset:38912
	ds_read_b128 v[244:247], v165 offset:39936
	global_load_lds_dwordx4 v130, s[10:11]
	s_mov_b32 m0, s51
	s_nop 0
	global_load_lds_dwordx4 v134, s[10:11]
	s_waitcnt vmcnt(8)
	s_waitcnt lgkmcnt(0)
	s_barrier
	v_mfma_f32_16x16x32_bf16 v[126:129], v[148:151], v[182:185], v[126:129]
	v_mfma_f32_16x16x32_bf16 v[122:125], v[156:159], v[182:185], v[122:125]
	v_mfma_f32_16x16x32_bf16 v[114:117], v[156:159], v[210:213], v[114:117]
	v_mfma_f32_16x16x32_bf16 v[118:121], v[148:151], v[210:213], v[118:121]
	v_mfma_f32_16x16x32_bf16 v[110:113], v[148:151], v[218:221], v[110:113]
	v_mfma_f32_16x16x32_bf16 v[106:109], v[156:159], v[218:221], v[106:109]
	v_mfma_f32_16x16x32_bf16 v[98:101], v[156:159], v[240:243], v[98:101]
	v_mfma_f32_16x16x32_bf16 v[102:105], v[148:151], v[240:243], v[102:105]
	v_mfma_f32_16x16x32_bf16 v[126:129], v[152:155], v[206:209], v[126:129]
	v_mfma_f32_16x16x32_bf16 v[122:125], v[160:163], v[206:209], v[122:125]
	v_mfma_f32_16x16x32_bf16 v[114:117], v[160:163], v[214:217], v[114:117]
	v_mfma_f32_16x16x32_bf16 v[118:121], v[152:155], v[214:217], v[118:121]
	v_mfma_f32_16x16x32_bf16 v[110:113], v[152:155], v[236:239], v[110:113]
	v_mfma_f32_16x16x32_bf16 v[106:109], v[160:163], v[236:239], v[106:109]
	v_mfma_f32_16x16x32_bf16 v[98:101], v[160:163], v[244:247], v[98:101]
	v_mfma_f32_16x16x32_bf16 v[102:105], v[152:155], v[244:247], v[102:105]
	v_mfma_f32_16x16x32_bf16 v[94:97], v[166:169], v[182:185], v[94:97]
	v_mfma_f32_16x16x32_bf16 v[90:93], v[174:177], v[182:185], v[90:93]
	v_mfma_f32_16x16x32_bf16 v[82:85], v[174:177], v[210:213], v[82:85]
	v_mfma_f32_16x16x32_bf16 v[86:89], v[166:169], v[210:213], v[86:89]
	v_mfma_f32_16x16x32_bf16 v[78:81], v[166:169], v[218:221], v[78:81]
	v_mfma_f32_16x16x32_bf16 v[74:77], v[174:177], v[218:221], v[74:77]
	v_mfma_f32_16x16x32_bf16 v[66:69], v[174:177], v[240:243], v[66:69]
	v_mfma_f32_16x16x32_bf16 v[70:73], v[166:169], v[240:243], v[70:73]
	v_mfma_f32_16x16x32_bf16 v[94:97], v[170:173], v[206:209], v[94:97]
	v_mfma_f32_16x16x32_bf16 v[90:93], v[178:181], v[206:209], v[90:93]
	v_mfma_f32_16x16x32_bf16 v[82:85], v[178:181], v[214:217], v[82:85]
	v_mfma_f32_16x16x32_bf16 v[86:89], v[170:173], v[214:217], v[86:89]
	v_mfma_f32_16x16x32_bf16 v[78:81], v[170:173], v[236:239], v[78:81]
	v_mfma_f32_16x16x32_bf16 v[74:77], v[178:181], v[236:239], v[74:77]
	v_mfma_f32_16x16x32_bf16 v[66:69], v[178:181], v[244:247], v[66:69]
	v_mfma_f32_16x16x32_bf16 v[70:73], v[170:173], v[244:247], v[70:73]
	s_barrier
; #define PG8_STAGE(bufoff, gbase, voff) do { _Pragma("unroll") for (int _i = 0; _i < 2; ++_i) \
;         __builtin_amdgcn_global_load_lds((const unsigned*)((const char*)(gbase) + (voff)[_i]), (PG8_LAS unsigned*)(lds + (bufoff) + ldsw + _i * 8192), 16, 0, 0); } while (0)
; #define PG8_LDA(dst, b, h) do { _Pragma("unroll") for (int m = 0; m < 4; ++m) _Pragma("unroll") for (int k = 0; k < 2; ++k) dst[m][k] = *(const PG8_LAS bf16x8*)(lds + PG8_SA(b, h) + aoff + m * 2048 + k * 1024); } while (0)
; #define PG8_LDB(dst, b, h) do { _Pragma("unroll") for (int n = 0; n < 2; ++n) _Pragma("unroll") for (int k = 0; k < 2; ++k) dst[n][k] = *(const PG8_LAS bf16x8*)(lds + PG8_SB(b, h) + boff + n * 2048 + k * 1024); } while (0)
; #define PG8_MMA(ai, bj, At, Bt) do { __builtin_amdgcn_s_setprio(1); _Pragma("unroll") for (int m = 0; m < 4; ++m) _Pragma("unroll") for (int n = 0; n < 2; ++n) _Pragma("unroll") for (int k = 0; k < 2; ++k) \
;         acc[ai][bj][m][n] = __builtin_amdgcn_mfma_f32_16x16x32_bf16(Bt[n][k], At[m][k], acc[ai][bj][m][n], 0, 0, 0); __builtin_amdgcn_s_setprio(0); } while (0)
; #define PG8_WAIT_V(n) asm volatile("s_waitcnt vmcnt(" #n ")" ::: "memory")
; #define PG8_WAIT_L(n) asm volatile("s_waitcnt lgkmcnt(" #n ")" ::: "memory")
; #define PG8_BAR __builtin_amdgcn_s_barrier()
; #define PG8_SCHED __builtin_amdgcn_sched_barrier(0)
; template <class Epi, class Sched, bool ALIGN_EPI = false, bool SP2 = false>
; __device__ __forceinline__ void gemm_phase(PG8_LAS unsigned char* lds, const Gemm g, const Sched& S, const Epi& E) {
;     ...
;         for (int t = 0; t < nt; t += 2) {
;             const bool last = (t == nt - 2);
;             const char* a1 = cA + (size_t)(t + 1) * kstep;
;             const char* a2 = last ? nA : cA + (size_t)(t + 2) * kstep; const char* b2 = last ? nB : cB + (size_t)(t + 2) * kstep;
;             const char* a3 = a2 + kstep; const char* b3 = b2 + kstep;
;             if (last && has_next) S.a_ready(nxt);
;             if constexpr (SP2) {
;             PG8_LDB(B0, 0, 0); PG8_LDB(B1, 0, 1); PG8_SCHED; PG8_LDA(At, 0, 0); PG8_STAGE(PG8_SA(1, 1), a1 + hstep, voffA);
;     ...
;             PG8_LDA(At, 1, 1); PG8_STAGE(PG8_SB(1, 0), b3, voffB); PG8_STAGE(PG8_SB(1, 1), b3 + hstepB, voffB); PG8_STAGE(PG8_SA(1, 0), a3, voffA);
;             PG8_WAIT_V(8); PG8_WAIT_L(0); PG8_BAR; PG8_MMA(1, 0, At, B0); PG8_MMA(1, 1, At, B1); PG8_BAR; PG8_SCHED;
	s_add_i32 s9, s9, s0
	s_mov_b32 m0, s9
	ds_read_b128 v[182:185], v165 offset:49152
	ds_read_b128 v[206:209], v165 offset:50176
	ds_read_b128 v[210:213], v165 offset:51200
	ds_read_b128 v[214:217], v165 offset:52224
	ds_read_b128 v[218:221], v165 offset:53248
	ds_read_b128 v[236:239], v165 offset:54272
	ds_read_b128 v[240:243], v165 offset:55296
	ds_read_b128 v[244:247], v165 offset:56320
	s_add_u32 s100, s80, s60
	s_addc_u32 s101, s81, s61
	global_load_lds_dwordx4 v132, s[100:101]
	s_add_i32 m0, s9, 0x2000
	s_add_u32 s10, s80, 0x20080
	s_addc_u32 s11, s81, 0
	s_add_i32 s9, s12, s0
	global_load_lds_dwordx4 v136, s[100:101]
	s_mov_b32 m0, s9
	s_nop 0
	global_load_lds_dwordx4 v132, s[10:11]
	s_add_i32 m0, s9, 0x2000
	s_nop 0
	global_load_lds_dwordx4 v136, s[10:11]
	s_mov_b32 m0, s66
	s_add_u32 s100, s84, s60
	s_addc_u32 s101, s85, s61
	global_load_lds_dwordx4 v130, s[100:101]
	s_mov_b32 m0, s67
	s_nop 0
	global_load_lds_dwordx4 v134, s[100:101]
	s_waitcnt vmcnt(8)
	s_waitcnt lgkmcnt(0)
	s_barrier
	v_mfma_f32_16x16x32_bf16 v[62:65], v[148:151], v[182:185], v[62:65]
	v_mfma_f32_16x16x32_bf16 v[58:61], v[156:159], v[182:185], v[58:61]
	v_mfma_f32_16x16x32_bf16 v[50:53], v[156:159], v[210:213], v[50:53]
	v_mfma_f32_16x16x32_bf16 v[54:57], v[148:151], v[210:213], v[54:57]
	v_mfma_f32_16x16x32_bf16 v[46:49], v[148:151], v[218:221], v[46:49]
	v_mfma_f32_16x16x32_bf16 v[42:45], v[156:159], v[218:221], v[42:45]
	v_mfma_f32_16x16x32_bf16 v[34:37], v[156:159], v[240:243], v[34:37]
	v_mfma_f32_16x16x32_bf16 v[38:41], v[148:151], v[240:243], v[38:41]
	v_mfma_f32_16x16x32_bf16 v[62:65], v[152:155], v[206:209], v[62:65]
	v_mfma_f32_16x16x32_bf16 v[58:61], v[160:163], v[206:209], v[58:61]
	v_mfma_f32_16x16x32_bf16 v[50:53], v[160:163], v[214:217], v[50:53]
	v_mfma_f32_16x16x32_bf16 v[54:57], v[152:155], v[214:217], v[54:57]
	v_mfma_f32_16x16x32_bf16 v[46:49], v[152:155], v[236:239], v[46:49]
	v_mfma_f32_16x16x32_bf16 v[42:45], v[160:163], v[236:239], v[42:45]
	v_mfma_f32_16x16x32_bf16 v[34:37], v[160:163], v[244:247], v[34:37]
	v_mfma_f32_16x16x32_bf16 v[38:41], v[152:155], v[244:247], v[38:41]
	v_mfma_f32_16x16x32_bf16 v[30:33], v[166:169], v[182:185], v[30:33]
	v_mfma_f32_16x16x32_bf16 v[26:29], v[174:177], v[182:185], v[26:29]
	v_mfma_f32_16x16x32_bf16 v[18:21], v[174:177], v[210:213], v[18:21]
	v_mfma_f32_16x16x32_bf16 v[22:25], v[166:169], v[210:213], v[22:25]
	v_mfma_f32_16x16x32_bf16 v[14:17], v[166:169], v[218:221], v[14:17]
	v_mfma_f32_16x16x32_bf16 v[10:13], v[174:177], v[218:221], v[10:13]
	v_mfma_f32_16x16x32_bf16 v[2:5], v[174:177], v[240:243], v[2:5]
	v_mfma_f32_16x16x32_bf16 v[6:9], v[166:169], v[240:243], v[6:9]
	v_mfma_f32_16x16x32_bf16 v[30:33], v[170:173], v[206:209], v[30:33]
	v_mfma_f32_16x16x32_bf16 v[26:29], v[178:181], v[206:209], v[26:29]
	v_mfma_f32_16x16x32_bf16 v[18:21], v[178:181], v[214:217], v[18:21]
	v_mfma_f32_16x16x32_bf16 v[22:25], v[170:173], v[214:217], v[22:25]
	v_mfma_f32_16x16x32_bf16 v[14:17], v[170:173], v[236:239], v[14:17]
	v_mfma_f32_16x16x32_bf16 v[10:13], v[178:181], v[236:239], v[10:13]
	v_mfma_f32_16x16x32_bf16 v[2:5], v[178:181], v[244:247], v[2:5]
	v_mfma_f32_16x16x32_bf16 v[6:9], v[170:173], v[244:247], v[6:9]
	s_barrier
	s_add_i32 s8, s8, 2
	s_add_u32 s46, s46, 0x100
	s_addc_u32 s47, s47, 0
	s_cmp_gt_u32 s8, 29
.LBB0_170:
	s_add_u32 s9, s70, s46
	s_addc_u32 s10, s71, s47
	s_add_u32 s9, s9, 0x100
	s_addc_u32 s10, s10, 0
	s_add_u32 s100, s9, 0x7ff80
	s_addc_u32 s101, s10, 0
	s_add_u32 s11, s93, s46
	s_addc_u32 s12, s94, s47
	s_add_i32 s13, 0, 0x10000
	s_cmpk_eq_i32 s46, 0xf00
	s_cselect_b32 s85, s4, s10
	s_cselect_b32 s84, s5, s9
	s_cselect_b32 s81, s6, s12
	s_cselect_b32 s80, s7, s11
	s_add_i32 s9, 0, 0x14000
	ds_read_b128 v[148:151], v186
	ds_read_b128 v[152:155], v186 offset:1024
	ds_read_b128 v[156:159], v186 offset:2048
	ds_read_b128 v[160:163], v186 offset:3072
	ds_read_b128 v[166:169], v187
	ds_read_b128 v[170:173], v187 offset:1024
	ds_read_b128 v[174:177], v187 offset:2048
	ds_read_b128 v[178:181], v187 offset:3072
	s_add_i32 m0, s1, 0xc000
	ds_read_b128 v[182:185], v165
	ds_read_b128 v[206:209], v165 offset:1024
	ds_read_b128 v[210:213], v165 offset:2048
	ds_read_b128 v[214:217], v165 offset:3072
	ds_read_b128 v[218:221], v165 offset:4096
	ds_read_b128 v[236:239], v165 offset:5120
	ds_read_b128 v[240:243], v165 offset:6144
	ds_read_b128 v[244:247], v165 offset:7168
	global_load_lds_dwordx4 v140, s[100:101]
	s_add_i32 m0, s1, 0xe000
	s_nop 0
	global_load_lds_dwordx4 v142, s[100:101]
	s_waitcnt vmcnt(8)
	s_waitcnt lgkmcnt(0)
	s_barrier
; #define PG8_STAGE(bufoff, gbase, voff) do { _Pragma("unroll") for (int _i = 0; _i < 2; ++_i) \
;         __builtin_amdgcn_global_load_lds((const unsigned*)((const char*)(gbase) + (voff)[_i]), (PG8_LAS unsigned*)(lds + (bufoff) + ldsw + _i * 8192), 16, 0, 0); } while (0)
; #define PG8_LDA(dst, b, h) do { _Pragma("unroll") for (int m = 0; m < 4; ++m) _Pragma("unroll") for (int k = 0; k < 2; ++k) dst[m][k] = *(const PG8_LAS bf16x8*)(lds + PG8_SA(b, h) + aoff + m * 2048 + k * 1024); } while (0)
; #define PG8_MMA(ai, bj, At, Bt) do { __builtin_amdgcn_s_setprio(1); _Pragma("unroll") for (int m = 0; m < 4; ++m) _Pragma("unroll") for (int n = 0; n < 2; ++n) _Pragma("unroll") for (int k = 0; k < 2; ++k) \
;         acc[ai][bj][m][n] = __builtin_amdgcn_mfma_f32_16x16x32_bf16(Bt[n][k], At[m][k], acc[ai][bj][m][n], 0, 0, 0); __builtin_amdgcn_s_setprio(0); } while (0)
; #define PG8_WAIT_V(n) asm volatile("s_waitcnt vmcnt(" #n ")" ::: "memory")
; #define PG8_WAIT_L(n) asm volatile("s_waitcnt lgkmcnt(" #n ")" ::: "memory")
; #define PG8_BAR __builtin_amdgcn_s_barrier()
; #define PG8_SCHED __builtin_amdgcn_sched_barrier(0)
; template <class Epi, class Sched, bool ALIGN_EPI = false, bool SP2 = false>
; __device__ __forceinline__ void gemm_phase(PG8_LAS unsigned char* lds, const Gemm g, const Sched& S, const Epi& E) {
;     ...
;             PG8_WAIT_V(8); PG8_WAIT_L(0); PG8_BAR; PG8_MMA(0, 0, At, B0); PG8_MMA(0, 1, At, B1); PG8_BAR; PG8_SCHED;
;             PG8_LDA(At, 0, 1); PG8_STAGE(PG8_SB(0, 0), b2, voffB); PG8_STAGE(PG8_SB(0, 1), b2 + hstepB, voffB); PG8_STAGE(PG8_SA(0, 0), a2, voffA);
;             PG8_WAIT_V(8); PG8_WAIT_L(0); PG8_BAR; PG8_MMA(1, 0, At, B0); PG8_MMA(1, 1, At, B1); PG8_BAR; PG8_SCHED;
	v_mfma_f32_16x16x32_bf16 v[126:129], v[148:151], v[182:185], v[126:129]
	v_mfma_f32_16x16x32_bf16 v[122:125], v[156:159], v[182:185], v[122:125]
	v_mfma_f32_16x16x32_bf16 v[114:117], v[156:159], v[210:213], v[114:117]
	v_mfma_f32_16x16x32_bf16 v[118:121], v[148:151], v[210:213], v[118:121]
	v_mfma_f32_16x16x32_bf16 v[110:113], v[148:151], v[218:221], v[110:113]
	v_mfma_f32_16x16x32_bf16 v[106:109], v[156:159], v[218:221], v[106:109]
	v_mfma_f32_16x16x32_bf16 v[98:101], v[156:159], v[240:243], v[98:101]
	v_mfma_f32_16x16x32_bf16 v[102:105], v[148:151], v[240:243], v[102:105]
	v_mfma_f32_16x16x32_bf16 v[126:129], v[152:155], v[206:209], v[126:129]
	v_mfma_f32_16x16x32_bf16 v[122:125], v[160:163], v[206:209], v[122:125]
	v_mfma_f32_16x16x32_bf16 v[114:117], v[160:163], v[214:217], v[114:117]
	v_mfma_f32_16x16x32_bf16 v[118:121], v[152:155], v[214:217], v[118:121]
	v_mfma_f32_16x16x32_bf16 v[110:113], v[152:155], v[236:239], v[110:113]
	v_mfma_f32_16x16x32_bf16 v[106:109], v[160:163], v[236:239], v[106:109]
	v_mfma_f32_16x16x32_bf16 v[98:101], v[160:163], v[244:247], v[98:101]
	v_mfma_f32_16x16x32_bf16 v[102:105], v[152:155], v[244:247], v[102:105]
	v_mfma_f32_16x16x32_bf16 v[94:97], v[166:169], v[182:185], v[94:97]
	v_mfma_f32_16x16x32_bf16 v[90:93], v[174:177], v[182:185], v[90:93]
	v_mfma_f32_16x16x32_bf16 v[82:85], v[174:177], v[210:213], v[82:85]
	v_mfma_f32_16x16x32_bf16 v[86:89], v[166:169], v[210:213], v[86:89]
	v_mfma_f32_16x16x32_bf16 v[78:81], v[166:169], v[218:221], v[78:81]
	v_mfma_f32_16x16x32_bf16 v[74:77], v[174:177], v[218:221], v[74:77]
	v_mfma_f32_16x16x32_bf16 v[66:69], v[174:177], v[240:243], v[66:69]
	v_mfma_f32_16x16x32_bf16 v[70:73], v[166:169], v[240:243], v[70:73]
	v_mfma_f32_16x16x32_bf16 v[94:97], v[170:173], v[206:209], v[94:97]
	v_mfma_f32_16x16x32_bf16 v[90:93], v[178:181], v[206:209], v[90:93]
	v_mfma_f32_16x16x32_bf16 v[82:85], v[178:181], v[214:217], v[82:85]
	v_mfma_f32_16x16x32_bf16 v[86:89], v[170:173], v[214:217], v[86:89]
	v_mfma_f32_16x16x32_bf16 v[78:81], v[170:173], v[236:239], v[78:81]
	v_mfma_f32_16x16x32_bf16 v[74:77], v[178:181], v[236:239], v[74:77]
	v_mfma_f32_16x16x32_bf16 v[66:69], v[178:181], v[244:247], v[66:69]
	v_mfma_f32_16x16x32_bf16 v[70:73], v[170:173], v[244:247], v[70:73]
	s_barrier
	s_add_i32 s10, s13, s0
	s_mov_b32 m0, s10
	ds_read_b128 v[182:185], v165 offset:16384
	ds_read_b128 v[206:209], v165 offset:17408
	ds_read_b128 v[210:213], v165 offset:18432
	ds_read_b128 v[214:217], v165 offset:19456
	ds_read_b128 v[218:221], v165 offset:20480
	ds_read_b128 v[236:239], v165 offset:21504
	ds_read_b128 v[240:243], v165 offset:22528
	ds_read_b128 v[244:247], v165 offset:23552
	global_load_lds_dwordx4 v132, s[80:81]
	s_add_i32 m0, s10, 0x2000
	s_add_u32 s10, s80, 0x20000
	s_addc_u32 s11, s81, 0
	s_add_i32 s9, s9, s0
	global_load_lds_dwordx4 v136, s[80:81]
	s_mov_b32 m0, s9
	s_nop 0
	global_load_lds_dwordx4 v132, s[10:11]
	s_add_i32 m0, s9, 0x2000
	s_nop 0
	global_load_lds_dwordx4 v136, s[10:11]
	s_mov_b32 m0, s1
	s_nop 0
	global_load_lds_dwordx4 v130, s[84:85]
	s_mov_b32 m0, s25
	s_nop 0
	global_load_lds_dwordx4 v134, s[84:85]
	s_waitcnt vmcnt(8)
	s_waitcnt lgkmcnt(0)
	s_barrier
	v_mfma_f32_16x16x32_bf16 v[62:65], v[148:151], v[182:185], v[62:65]
	v_mfma_f32_16x16x32_bf16 v[58:61], v[156:159], v[182:185], v[58:61]
	v_mfma_f32_16x16x32_bf16 v[50:53], v[156:159], v[210:213], v[50:53]
	v_mfma_f32_16x16x32_bf16 v[54:57], v[148:151], v[210:213], v[54:57]
	v_mfma_f32_16x16x32_bf16 v[46:49], v[148:151], v[218:221], v[46:49]
	v_mfma_f32_16x16x32_bf16 v[42:45], v[156:159], v[218:221], v[42:45]
	v_mfma_f32_16x16x32_bf16 v[34:37], v[156:159], v[240:243], v[34:37]
	v_mfma_f32_16x16x32_bf16 v[38:41], v[148:151], v[240:243], v[38:41]
	v_mfma_f32_16x16x32_bf16 v[62:65], v[152:155], v[206:209], v[62:65]
	v_mfma_f32_16x16x32_bf16 v[58:61], v[160:163], v[206:209], v[58:61]
	v_mfma_f32_16x16x32_bf16 v[50:53], v[160:163], v[214:217], v[50:53]
	v_mfma_f32_16x16x32_bf16 v[54:57], v[152:155], v[214:217], v[54:57]
	v_mfma_f32_16x16x32_bf16 v[46:49], v[152:155], v[236:239], v[46:49]
	v_mfma_f32_16x16x32_bf16 v[42:45], v[160:163], v[236:239], v[42:45]
	v_mfma_f32_16x16x32_bf16 v[34:37], v[160:163], v[244:247], v[34:37]
	v_mfma_f32_16x16x32_bf16 v[38:41], v[152:155], v[244:247], v[38:41]
	v_mfma_f32_16x16x32_bf16 v[30:33], v[166:169], v[182:185], v[30:33]
	v_mfma_f32_16x16x32_bf16 v[26:29], v[174:177], v[182:185], v[26:29]
	v_mfma_f32_16x16x32_bf16 v[18:21], v[174:177], v[210:213], v[18:21]
	v_mfma_f32_16x16x32_bf16 v[22:25], v[166:169], v[210:213], v[22:25]
	v_mfma_f32_16x16x32_bf16 v[14:17], v[166:169], v[218:221], v[14:17]
	v_mfma_f32_16x16x32_bf16 v[10:13], v[174:177], v[218:221], v[10:13]
	v_mfma_f32_16x16x32_bf16 v[2:5], v[174:177], v[240:243], v[2:5]
	v_mfma_f32_16x16x32_bf16 v[6:9], v[166:169], v[240:243], v[6:9]
	v_mfma_f32_16x16x32_bf16 v[30:33], v[170:173], v[206:209], v[30:33]
	v_mfma_f32_16x16x32_bf16 v[26:29], v[178:181], v[206:209], v[26:29]
	v_mfma_f32_16x16x32_bf16 v[18:21], v[178:181], v[214:217], v[18:21]
	v_mfma_f32_16x16x32_bf16 v[22:25], v[170:173], v[214:217], v[22:25]
	v_mfma_f32_16x16x32_bf16 v[14:17], v[170:173], v[236:239], v[14:17]
	v_mfma_f32_16x16x32_bf16 v[10:13], v[178:181], v[236:239], v[10:13]
	v_mfma_f32_16x16x32_bf16 v[2:5], v[178:181], v[244:247], v[2:5]
	v_mfma_f32_16x16x32_bf16 v[6:9], v[170:173], v[244:247], v[6:9]
	s_barrier
; #define PG8_STAGE(bufoff, gbase, voff) do { _Pragma("unroll") for (int _i = 0; _i < 2; ++_i) \
;         __builtin_amdgcn_global_load_lds((const unsigned*)((const char*)(gbase) + (voff)[_i]), (PG8_LAS unsigned*)(lds + (bufoff) + ldsw + _i * 8192), 16, 0, 0); } while (0)
; #define PG8_LDA(dst, b, h) do { _Pragma("unroll") for (int m = 0; m < 4; ++m) _Pragma("unroll") for (int k = 0; k < 2; ++k) dst[m][k] = *(const PG8_LAS bf16x8*)(lds + PG8_SA(b, h) + aoff + m * 2048 + k * 1024); } while (0)
; #define PG8_LDB(dst, b, h) do { _Pragma("unroll") for (int n = 0; n < 2; ++n) _Pragma("unroll") for (int k = 0; k < 2; ++k) dst[n][k] = *(const PG8_LAS bf16x8*)(lds + PG8_SB(b, h) + boff + n * 2048 + k * 1024); } while (0)
; #define PG8_MMA(ai, bj, At, Bt) do { __builtin_amdgcn_s_setprio(1); _Pragma("unroll") for (int m = 0; m < 4; ++m) _Pragma("unroll") for (int n = 0; n < 2; ++n) _Pragma("unroll") for (int k = 0; k < 2; ++k) \
;         acc[ai][bj][m][n] = __builtin_amdgcn_mfma_f32_16x16x32_bf16(Bt[n][k], At[m][k], acc[ai][bj][m][n], 0, 0, 0); __builtin_amdgcn_s_setprio(0); } while (0)
; #define PG8_WAIT_V(n) asm volatile("s_waitcnt vmcnt(" #n ")" ::: "memory")
; #define PG8_WAIT_L(n) asm volatile("s_waitcnt lgkmcnt(" #n ")" ::: "memory")
; #define PG8_BAR __builtin_amdgcn_s_barrier()
; #define PG8_SCHED __builtin_amdgcn_sched_barrier(0)
; template <class Epi, class Sched, bool ALIGN_EPI = false, bool SP2 = false>
; __device__ __forceinline__ void gemm_phase(PG8_LAS unsigned char* lds, const Gemm g, const Sched& S, const Epi& E) {
;     ...
;             PG8_LDB(B0, 1, 0); PG8_LDB(B1, 1, 1); PG8_SCHED; PG8_LDA(At, 1, 0); PG8_STAGE(PG8_SA(0, 1), a2 + hstep, voffA);
;             PG8_WAIT_V(8); PG8_WAIT_L(0); PG8_BAR; PG8_MMA(0, 0, At, B0); PG8_MMA(0, 1, At, B1); PG8_BAR; PG8_SCHED;
;             PG8_LDA(At, 1, 1); PG8_STAGE(PG8_SB(1, 0), b3, voffB); PG8_STAGE(PG8_SB(1, 1), b3 + hstepB, voffB); PG8_STAGE(PG8_SA(1, 0), a3, voffA);
;             PG8_WAIT_V(8); PG8_WAIT_L(0); PG8_BAR; PG8_MMA(1, 0, At, B0); PG8_MMA(1, 1, At, B1); PG8_BAR; PG8_SCHED;
;     ...
;         if constexpr (ALIGN_EPI) { if (wr == 0) PG8_BAR; }
;         if constexpr (!Epi::AFTER_DRAIN) { E(acc, cur, wr, wc, fr, fq, ui); S.done(cur); }
;         if (!has_next) break;
	s_add_i32 s9, 0, 0x18000
	s_add_i32 s12, 0, 0x1c000
	ds_read_b128 v[148:151], v198
	ds_read_b128 v[152:155], v198 offset:1024
	ds_read_b128 v[156:159], v198 offset:2048
	ds_read_b128 v[160:163], v198 offset:3072
	ds_read_b128 v[166:169], v199
	ds_read_b128 v[170:173], v199 offset:1024
	ds_read_b128 v[174:177], v199 offset:2048
	ds_read_b128 v[178:181], v199 offset:3072
	s_add_u32 s10, s84, 0x80000
	s_addc_u32 s11, s85, 0
	s_mov_b32 m0, s42
	ds_read_b128 v[182:185], v165 offset:32768
	ds_read_b128 v[206:209], v165 offset:33792
	ds_read_b128 v[210:213], v165 offset:34816
	ds_read_b128 v[214:217], v165 offset:35840
	ds_read_b128 v[218:221], v165 offset:36864
	ds_read_b128 v[236:239], v165 offset:37888
	ds_read_b128 v[240:243], v165 offset:38912
	ds_read_b128 v[244:247], v165 offset:39936
	global_load_lds_dwordx4 v130, s[10:11]
	s_mov_b32 m0, s51
	s_nop 0
	global_load_lds_dwordx4 v134, s[10:11]
	s_waitcnt vmcnt(8)
	s_waitcnt lgkmcnt(0)
	s_barrier
	v_mfma_f32_16x16x32_bf16 v[126:129], v[148:151], v[182:185], v[126:129]
	v_mfma_f32_16x16x32_bf16 v[122:125], v[156:159], v[182:185], v[122:125]
	v_mfma_f32_16x16x32_bf16 v[114:117], v[156:159], v[210:213], v[114:117]
	v_mfma_f32_16x16x32_bf16 v[118:121], v[148:151], v[210:213], v[118:121]
	v_mfma_f32_16x16x32_bf16 v[110:113], v[148:151], v[218:221], v[110:113]
	v_mfma_f32_16x16x32_bf16 v[106:109], v[156:159], v[218:221], v[106:109]
	v_mfma_f32_16x16x32_bf16 v[98:101], v[156:159], v[240:243], v[98:101]
	v_mfma_f32_16x16x32_bf16 v[102:105], v[148:151], v[240:243], v[102:105]
	v_mfma_f32_16x16x32_bf16 v[126:129], v[152:155], v[206:209], v[126:129]
	v_mfma_f32_16x16x32_bf16 v[122:125], v[160:163], v[206:209], v[122:125]
	v_mfma_f32_16x16x32_bf16 v[114:117], v[160:163], v[214:217], v[114:117]
	v_mfma_f32_16x16x32_bf16 v[118:121], v[152:155], v[214:217], v[118:121]
	v_mfma_f32_16x16x32_bf16 v[110:113], v[152:155], v[236:239], v[110:113]
	v_mfma_f32_16x16x32_bf16 v[106:109], v[160:163], v[236:239], v[106:109]
	v_mfma_f32_16x16x32_bf16 v[98:101], v[160:163], v[244:247], v[98:101]
	v_mfma_f32_16x16x32_bf16 v[102:105], v[152:155], v[244:247], v[102:105]
	v_mfma_f32_16x16x32_bf16 v[94:97], v[166:169], v[182:185], v[94:97]
	v_mfma_f32_16x16x32_bf16 v[90:93], v[174:177], v[182:185], v[90:93]
	v_mfma_f32_16x16x32_bf16 v[82:85], v[174:177], v[210:213], v[82:85]
	v_mfma_f32_16x16x32_bf16 v[86:89], v[166:169], v[210:213], v[86:89]
	v_mfma_f32_16x16x32_bf16 v[78:81], v[166:169], v[218:221], v[78:81]
	v_mfma_f32_16x16x32_bf16 v[74:77], v[174:177], v[218:221], v[74:77]
	v_mfma_f32_16x16x32_bf16 v[66:69], v[174:177], v[240:243], v[66:69]
	v_mfma_f32_16x16x32_bf16 v[70:73], v[166:169], v[240:243], v[70:73]
	v_mfma_f32_16x16x32_bf16 v[94:97], v[170:173], v[206:209], v[94:97]
	v_mfma_f32_16x16x32_bf16 v[90:93], v[178:181], v[206:209], v[90:93]
	v_mfma_f32_16x16x32_bf16 v[82:85], v[178:181], v[214:217], v[82:85]
	v_mfma_f32_16x16x32_bf16 v[86:89], v[170:173], v[214:217], v[86:89]
	v_mfma_f32_16x16x32_bf16 v[78:81], v[170:173], v[236:239], v[78:81]
	v_mfma_f32_16x16x32_bf16 v[74:77], v[178:181], v[236:239], v[74:77]
	v_mfma_f32_16x16x32_bf16 v[66:69], v[178:181], v[244:247], v[66:69]
	v_mfma_f32_16x16x32_bf16 v[70:73], v[170:173], v[244:247], v[70:73]
	s_barrier
	s_add_i32 s9, s9, s0
	s_mov_b32 m0, s9
	ds_read_b128 v[182:185], v165 offset:49152
	ds_read_b128 v[206:209], v165 offset:50176
	ds_read_b128 v[210:213], v165 offset:51200
	ds_read_b128 v[214:217], v165 offset:52224
	ds_read_b128 v[218:221], v165 offset:53248
	ds_read_b128 v[236:239], v165 offset:54272
	ds_read_b128 v[240:243], v165 offset:55296
	ds_read_b128 v[244:247], v165 offset:56320
	s_add_u32 s100, s80, s60
	s_addc_u32 s101, s81, s61
	global_load_lds_dwordx4 v132, s[100:101]
	s_add_i32 m0, s9, 0x2000
	s_add_u32 s10, s80, 0x20080
	s_addc_u32 s11, s81, 0
	s_add_i32 s9, s12, s0
	global_load_lds_dwordx4 v136, s[100:101]
	s_mov_b32 m0, s9
	s_nop 0
	global_load_lds_dwordx4 v132, s[10:11]
	s_add_i32 m0, s9, 0x2000
	s_nop 0
	global_load_lds_dwordx4 v136, s[10:11]
	s_mov_b32 m0, s66
	s_add_u32 s100, s84, s60
	s_addc_u32 s101, s85, s61
	global_load_lds_dwordx4 v130, s[100:101]
	s_mov_b32 m0, s67
	s_nop 0
	global_load_lds_dwordx4 v134, s[100:101]
	s_waitcnt vmcnt(8)
	s_waitcnt lgkmcnt(0)
	s_barrier
	v_mfma_f32_16x16x32_bf16 v[62:65], v[148:151], v[182:185], v[62:65]
	v_mfma_f32_16x16x32_bf16 v[58:61], v[156:159], v[182:185], v[58:61]
	v_mfma_f32_16x16x32_bf16 v[50:53], v[156:159], v[210:213], v[50:53]
	v_mfma_f32_16x16x32_bf16 v[54:57], v[148:151], v[210:213], v[54:57]
	v_mfma_f32_16x16x32_bf16 v[46:49], v[148:151], v[218:221], v[46:49]
	v_mfma_f32_16x16x32_bf16 v[42:45], v[156:159], v[218:221], v[42:45]
	v_mfma_f32_16x16x32_bf16 v[34:37], v[156:159], v[240:243], v[34:37]
	v_mfma_f32_16x16x32_bf16 v[38:41], v[148:151], v[240:243], v[38:41]
	v_mfma_f32_16x16x32_bf16 v[62:65], v[152:155], v[206:209], v[62:65]
	v_mfma_f32_16x16x32_bf16 v[58:61], v[160:163], v[206:209], v[58:61]
	v_mfma_f32_16x16x32_bf16 v[50:53], v[160:163], v[214:217], v[50:53]
	v_mfma_f32_16x16x32_bf16 v[54:57], v[152:155], v[214:217], v[54:57]
	v_mfma_f32_16x16x32_bf16 v[46:49], v[152:155], v[236:239], v[46:49]
	v_mfma_f32_16x16x32_bf16 v[42:45], v[160:163], v[236:239], v[42:45]
	v_mfma_f32_16x16x32_bf16 v[34:37], v[160:163], v[244:247], v[34:37]
	v_mfma_f32_16x16x32_bf16 v[38:41], v[152:155], v[244:247], v[38:41]
	v_mfma_f32_16x16x32_bf16 v[30:33], v[166:169], v[182:185], v[30:33]
	v_mfma_f32_16x16x32_bf16 v[26:29], v[174:177], v[182:185], v[26:29]
	v_mfma_f32_16x16x32_bf16 v[18:21], v[174:177], v[210:213], v[18:21]
	v_mfma_f32_16x16x32_bf16 v[22:25], v[166:169], v[210:213], v[22:25]
	v_mfma_f32_16x16x32_bf16 v[14:17], v[166:169], v[218:221], v[14:17]
	v_mfma_f32_16x16x32_bf16 v[10:13], v[174:177], v[218:221], v[10:13]
	v_mfma_f32_16x16x32_bf16 v[2:5], v[174:177], v[240:243], v[2:5]
	v_mfma_f32_16x16x32_bf16 v[6:9], v[166:169], v[240:243], v[6:9]
	v_mfma_f32_16x16x32_bf16 v[30:33], v[170:173], v[206:209], v[30:33]
	v_mfma_f32_16x16x32_bf16 v[26:29], v[178:181], v[206:209], v[26:29]
	v_mfma_f32_16x16x32_bf16 v[18:21], v[178:181], v[214:217], v[18:21]
	v_mfma_f32_16x16x32_bf16 v[22:25], v[170:173], v[214:217], v[22:25]
	v_mfma_f32_16x16x32_bf16 v[14:17], v[170:173], v[236:239], v[14:17]
	v_mfma_f32_16x16x32_bf16 v[10:13], v[178:181], v[236:239], v[10:13]
	v_mfma_f32_16x16x32_bf16 v[2:5], v[178:181], v[244:247], v[2:5]
	v_mfma_f32_16x16x32_bf16 v[6:9], v[170:173], v[244:247], v[6:9]
	s_barrier
	s_add_i32 s8, s8, 2
	s_add_u32 s46, s46, 0x100
	s_addc_u32 s47, s47, 0
	s_cmp_gt_u32 s8, 29
	s_cbranch_scc0 .LBB0_170
	s_and_b64 vcc, exec, s[54:55]
	s_cbranch_vccz .LBB0_173
	s_barrier

; #define PG8_STAGE(bufoff, gbase, voff) do { _Pragma("unroll") for (int _i = 0; _i < 2; ++_i) \
;         __builtin_amdgcn_global_load_lds((const unsigned*)((const char*)(gbase) + (voff)[_i]), (PG8_LAS unsigned*)(lds + (bufoff) + ldsw + _i * 8192), 16, 0, 0); } while (0)
; #define PG8_LDA(dst, b, h) do { _Pragma("unroll") for (int m = 0; m < 4; ++m) _Pragma("unroll") for (int k = 0; k < 2; ++k) dst[m][k] = *(const PG8_LAS bf16x8*)(lds + PG8_SA(b, h) + aoff + m * 2048 + k * 1024); } while (0)
; #define PG8_LDB(dst, b, h) do { _Pragma("unroll") for (int n = 0; n < 2; ++n) _Pragma("unroll") for (int k = 0; k < 2; ++k) dst[n][k] = *(const PG8_LAS bf16x8*)(lds + PG8_SB(b, h) + boff + n * 2048 + k * 1024); } while (0)
; #define PG8_MMA(ai, bj, At, Bt) do { __builtin_amdgcn_s_setprio(1); _Pragma("unroll") for (int m = 0; m < 4; ++m) _Pragma("unroll") for (int n = 0; n < 2; ++n) _Pragma("unroll") for (int k = 0; k < 2; ++k) \
;         acc[ai][bj][m][n] = __builtin_amdgcn_mfma_f32_16x16x32_bf16(Bt[n][k], At[m][k], acc[ai][bj][m][n], 0, 0, 0); __builtin_amdgcn_s_setprio(0); } while (0)
; #define PG8_WAIT_V(n) asm volatile("s_waitcnt vmcnt(" #n ")" ::: "memory")
; #define PG8_WAIT_L(n) asm volatile("s_waitcnt lgkmcnt(" #n ")" ::: "memory")
; #define PG8_BAR __builtin_amdgcn_s_barrier()
; template <class Epi, class Sched, bool ALIGN_EPI = false, bool SP2 = false>
; __device__ __forceinline__ void gemm_phase(PG8_LAS unsigned char* lds, const Gemm g, const Sched& S, const Epi& E) {
;     ...
;         const bool has_next = S.next(ui + 1, nxt);
;         const char* nA = has_next ? (const char*)g.A + (size_t)nxt.pm * tstep : cA; const char* nB = has_next ? (const char*)g.Bt + (size_t)nxt.pn * tstep : cB;
;         for (int t = 0; t < nt; t += 2) {
;             const bool last = (t == nt - 2);
;             const char* a1 = cA + (size_t)(t + 1) * kstep;
;             const char* a2 = last ? nA : cA + (size_t)(t + 2) * kstep; const char* b2 = last ? nB : cB + (size_t)(t + 2) * kstep;
;             const char* a3 = a2 + kstep; const char* b3 = b2 + kstep;
;             if (last && has_next) S.a_ready(nxt);
;             if constexpr (SP2) {
;             PG8_LDB(B0, 0, 0); PG8_LDB(B1, 0, 1); PG8_SCHED; PG8_LDA(At, 0, 0); PG8_STAGE(PG8_SA(1, 1), a1 + hstep, voffA);
;             PG8_WAIT_V(8); PG8_WAIT_L(0); PG8_BAR; PG8_MMA(0, 0, At, B0); PG8_MMA(0, 1, At, B1); PG8_BAR; PG8_SCHED;
.LBB0_926:
	s_ashr_i32 s73, s72, 31
	s_lshl_b64 s[4:5], s[72:73], 20
	v_readlane_b32 s6, v249, 9
	v_readlane_b32 s7, v249, 10
	s_add_u32 s76, s6, s4
	s_addc_u32 s77, s7, s5
	s_and_b64 s[4:5], s[92:93], exec
	s_cselect_b32 s36, s77, s39
	s_cselect_b32 s37, s76, s38
	s_ashr_i32 s69, s68, 31
	s_lshl_b64 s[4:5], s[68:69], 20
	v_readlane_b32 s6, v249, 17
	v_readlane_b32 s7, v249, 18
	s_add_u32 s80, s6, s4
	s_addc_u32 s81, s7, s5
	s_and_b64 s[4:5], s[92:93], exec
	s_cselect_b32 s4, s81, s47
	s_cselect_b32 s5, s80, s46
	s_add_u32 s38, s38, 0x80080
	s_addc_u32 s39, s39, 0
	s_add_u32 s6, s46, 0x100
	v_mov_b32_e32 v2, 0
	s_addc_u32 s7, s47, 0
	s_mov_b32 s8, -2
	v_mov_b32_e32 v3, v2
	v_mov_b32_e32 v4, v2
	v_mov_b32_e32 v5, v2
	v_mov_b32_e32 v6, v2
	v_mov_b32_e32 v7, v2
	v_mov_b32_e32 v8, v2
	v_mov_b32_e32 v9, v2
	v_mov_b32_e32 v18, v2
	v_mov_b32_e32 v19, v2
	v_mov_b32_e32 v20, v2
	v_mov_b32_e32 v21, v2
	v_mov_b32_e32 v22, v2
	v_mov_b32_e32 v23, v2
	v_mov_b32_e32 v24, v2
	v_mov_b32_e32 v25, v2
	v_mov_b32_e32 v34, v2
	s_waitcnt lgkmcnt(0)
	v_add_u32_e32 v186, 0x10000, v193
	v_add_u32_e32 v187, 0x14000, v193
	v_add_u32_e32 v198, 0x18000, v193
	v_add_u32_e32 v199, 0x1c000, v193
	s_add_u32 s9, s38, 0xfff80080
	s_addc_u32 s10, s39, -1
	s_add_i32 s11, 0, 0x10000
	s_cmp_eq_u32 s8, 28
	s_cselect_b32 s95, s36, s10
	s_cselect_b32 s94, s37, s9
	s_cselect_b32 s47, s4, s7
	s_cselect_b32 s46, s5, s6
	s_add_i32 s9, 0, 0x14000
	ds_read_b128 v[66:69], v186
	ds_read_b128 v[70:73], v186 offset:1024
	ds_read_b128 v[78:81], v186 offset:2048
	ds_read_b128 v[86:89], v186 offset:3072
	ds_read_b128 v[146:149], v187
	ds_read_b128 v[150:153], v187 offset:1024
	ds_read_b128 v[154:157], v187 offset:2048
	ds_read_b128 v[158:161], v187 offset:3072
	s_add_i32 m0, s66, 0xc000
	ds_read_b128 v[162:165], v236
	ds_read_b128 v[166:169], v236 offset:1024
	ds_read_b128 v[170:173], v236 offset:2048
	ds_read_b128 v[174:177], v236 offset:3072
	ds_read_b128 v[178:181], v236 offset:4096
	ds_read_b128 v[182:185], v236 offset:5120
	ds_read_b128 v[216:219], v236 offset:6144
	ds_read_b128 v[220:223], v236 offset:7168
	global_load_lds_dwordx4 v212, s[38:39]
	s_add_i32 m0, s66, 0xe000
	s_nop 0
	global_load_lds_dwordx4 v214, s[38:39]
	s_waitcnt vmcnt(8)
	s_waitcnt lgkmcnt(0)
	s_barrier
	v_mfma_f32_16x16x32_bf16 v[142:145], v[66:69], v[162:165], 0
	v_mfma_f32_16x16x32_bf16 v[138:141], v[78:81], v[162:165], 0
	v_mfma_f32_16x16x32_bf16 v[122:125], v[78:81], v[170:173], 0
	v_mfma_f32_16x16x32_bf16 v[126:129], v[66:69], v[170:173], 0
	v_mfma_f32_16x16x32_bf16 v[110:113], v[66:69], v[178:181], 0
	v_mfma_f32_16x16x32_bf16 v[106:109], v[78:81], v[178:181], 0
	v_mfma_f32_16x16x32_bf16 v[90:93], v[78:81], v[216:219], 0
	v_mfma_f32_16x16x32_bf16 v[94:97], v[66:69], v[216:219], 0
	v_mfma_f32_16x16x32_bf16 v[142:145], v[70:73], v[166:169], v[142:145]
	v_mfma_f32_16x16x32_bf16 v[138:141], v[86:89], v[166:169], v[138:141]
	v_mfma_f32_16x16x32_bf16 v[122:125], v[86:89], v[174:177], v[122:125]
	v_mfma_f32_16x16x32_bf16 v[126:129], v[70:73], v[174:177], v[126:129]
	v_mfma_f32_16x16x32_bf16 v[110:113], v[70:73], v[182:185], v[110:113]
	v_mfma_f32_16x16x32_bf16 v[106:109], v[86:89], v[182:185], v[106:109]
	v_mfma_f32_16x16x32_bf16 v[90:93], v[86:89], v[220:223], v[90:93]
	v_mfma_f32_16x16x32_bf16 v[94:97], v[70:73], v[220:223], v[94:97]
	v_mfma_f32_16x16x32_bf16 v[134:137], v[146:149], v[162:165], 0
	v_mfma_f32_16x16x32_bf16 v[130:133], v[154:157], v[162:165], 0
	v_mfma_f32_16x16x32_bf16 v[114:117], v[154:157], v[170:173], 0
	v_mfma_f32_16x16x32_bf16 v[118:121], v[146:149], v[170:173], 0
	v_mfma_f32_16x16x32_bf16 v[102:105], v[146:149], v[178:181], 0
	v_mfma_f32_16x16x32_bf16 v[98:101], v[154:157], v[178:181], 0
	v_mfma_f32_16x16x32_bf16 v[74:77], v[154:157], v[216:219], 0
	v_mfma_f32_16x16x32_bf16 v[82:85], v[146:149], v[216:219], 0
	v_mfma_f32_16x16x32_bf16 v[134:137], v[150:153], v[166:169], v[134:137]
	v_mfma_f32_16x16x32_bf16 v[130:133], v[158:161], v[166:169], v[130:133]
	v_mfma_f32_16x16x32_bf16 v[114:117], v[158:161], v[174:177], v[114:117]
	v_mfma_f32_16x16x32_bf16 v[118:121], v[150:153], v[174:177], v[118:121]
	v_mfma_f32_16x16x32_bf16 v[102:105], v[150:153], v[182:185], v[102:105]
	v_mfma_f32_16x16x32_bf16 v[98:101], v[158:161], v[182:185], v[98:101]
	v_mfma_f32_16x16x32_bf16 v[74:77], v[158:161], v[220:223], v[74:77]
	v_mfma_f32_16x16x32_bf16 v[82:85], v[150:153], v[220:223], v[82:85]
	s_barrier
	s_add_i32 s10, s11, s25
	s_mov_b32 m0, s10
	ds_read_b128 v[162:165], v236 offset:16384
	ds_read_b128 v[166:169], v236 offset:17408
	ds_read_b128 v[170:173], v236 offset:18432
	ds_read_b128 v[174:177], v236 offset:19456
	ds_read_b128 v[178:181], v236 offset:20480
	ds_read_b128 v[182:185], v236 offset:21504
	ds_read_b128 v[216:219], v236 offset:22528
	ds_read_b128 v[220:223], v236 offset:23552
	global_load_lds_dwordx4 v190, s[46:47]
	s_add_i32 m0, s10, 0x2000
	s_add_u32 s10, s46, 0x20000
	s_addc_u32 s11, s47, 0
	s_add_i32 s9, s9, s25
	global_load_lds_dwordx4 v206, s[46:47]
	s_mov_b32 m0, s9
	s_nop 0
	global_load_lds_dwordx4 v190, s[10:11]
	s_add_i32 m0, s9, 0x2000
	s_nop 0
	global_load_lds_dwordx4 v206, s[10:11]
	s_mov_b32 m0, s66
	s_nop 0
	global_load_lds_dwordx4 v210, s[94:95]
	s_mov_b32 m0, s67
	s_nop 0
	global_load_lds_dwordx4 v208, s[94:95]
	s_waitcnt vmcnt(8)
	s_waitcnt lgkmcnt(0)
	s_barrier
; #define PG8_STAGE(bufoff, gbase, voff) do { _Pragma("unroll") for (int _i = 0; _i < 2; ++_i) \
;         __builtin_amdgcn_global_load_lds((const unsigned*)((const char*)(gbase) + (voff)[_i]), (PG8_LAS unsigned*)(lds + (bufoff) + ldsw + _i * 8192), 16, 0, 0); } while (0)
; #define PG8_LDA(dst, b, h) do { _Pragma("unroll") for (int m = 0; m < 4; ++m) _Pragma("unroll") for (int k = 0; k < 2; ++k) dst[m][k] = *(const PG8_LAS bf16x8*)(lds + PG8_SA(b, h) + aoff + m * 2048 + k * 1024); } while (0)
; #define PG8_LDB(dst, b, h) do { _Pragma("unroll") for (int n = 0; n < 2; ++n) _Pragma("unroll") for (int k = 0; k < 2; ++k) dst[n][k] = *(const PG8_LAS bf16x8*)(lds + PG8_SB(b, h) + boff + n * 2048 + k * 1024); } while (0)
; #define PG8_MMA(ai, bj, At, Bt) do { __builtin_amdgcn_s_setprio(1); _Pragma("unroll") for (int m = 0; m < 4; ++m) _Pragma("unroll") for (int n = 0; n < 2; ++n) _Pragma("unroll") for (int k = 0; k < 2; ++k) \
;         acc[ai][bj][m][n] = __builtin_amdgcn_mfma_f32_16x16x32_bf16(Bt[n][k], At[m][k], acc[ai][bj][m][n], 0, 0, 0); __builtin_amdgcn_s_setprio(0); } while (0)
; #define PG8_WAIT_V(n) asm volatile("s_waitcnt vmcnt(" #n ")" ::: "memory")
; #define PG8_WAIT_L(n) asm volatile("s_waitcnt lgkmcnt(" #n ")" ::: "memory")
; #define PG8_BAR __builtin_amdgcn_s_barrier()
; #define PG8_SCHED __builtin_amdgcn_sched_barrier(0)
; template <class Epi, class Sched, bool ALIGN_EPI = false, bool SP2 = false>
; __device__ __forceinline__ void gemm_phase(PG8_LAS unsigned char* lds, const Gemm g, const Sched& S, const Epi& E) {
;     ...
;             PG8_LDA(At, 0, 1); PG8_STAGE(PG8_SB(0, 0), b2, voffB); PG8_STAGE(PG8_SB(0, 1), b2 + hstepB, voffB); PG8_STAGE(PG8_SA(0, 0), a2, voffA);
;             PG8_WAIT_V(8); PG8_WAIT_L(0); PG8_BAR; PG8_MMA(1, 0, At, B0); PG8_MMA(1, 1, At, B1); PG8_BAR; PG8_SCHED;
;             PG8_LDB(B0, 1, 0); PG8_LDB(B1, 1, 1); PG8_SCHED; PG8_LDA(At, 1, 0); PG8_STAGE(PG8_SA(0, 1), a2 + hstep, voffA);
;             PG8_WAIT_V(8); PG8_WAIT_L(0); PG8_BAR; PG8_MMA(0, 0, At, B0); PG8_MMA(0, 1, At, B1); PG8_BAR; PG8_SCHED;
	v_mfma_f32_16x16x32_bf16 v[62:65], v[66:69], v[162:165], 0
	v_mfma_f32_16x16x32_bf16 v[58:61], v[78:81], v[162:165], 0
	v_mfma_f32_16x16x32_bf16 v[42:45], v[78:81], v[170:173], 0
	v_mfma_f32_16x16x32_bf16 v[46:49], v[66:69], v[170:173], 0
	v_mfma_f32_16x16x32_bf16 v[30:33], v[66:69], v[178:181], 0
	v_mfma_f32_16x16x32_bf16 v[26:29], v[78:81], v[178:181], 0
	v_mfma_f32_16x16x32_bf16 v[10:13], v[78:81], v[216:219], 0
	v_mfma_f32_16x16x32_bf16 v[14:17], v[66:69], v[216:219], 0
	v_mfma_f32_16x16x32_bf16 v[62:65], v[70:73], v[166:169], v[62:65]
	v_mfma_f32_16x16x32_bf16 v[58:61], v[86:89], v[166:169], v[58:61]
	v_mfma_f32_16x16x32_bf16 v[42:45], v[86:89], v[174:177], v[42:45]
	v_mfma_f32_16x16x32_bf16 v[46:49], v[70:73], v[174:177], v[46:49]
	v_mfma_f32_16x16x32_bf16 v[30:33], v[70:73], v[182:185], v[30:33]
	v_mfma_f32_16x16x32_bf16 v[26:29], v[86:89], v[182:185], v[26:29]
	v_mfma_f32_16x16x32_bf16 v[10:13], v[86:89], v[220:223], v[10:13]
	v_mfma_f32_16x16x32_bf16 v[14:17], v[70:73], v[220:223], v[14:17]
	v_mfma_f32_16x16x32_bf16 v[54:57], v[146:149], v[162:165], 0
	v_mfma_f32_16x16x32_bf16 v[50:53], v[154:157], v[162:165], 0
	v_mfma_f32_16x16x32_bf16 v[34:37], v[154:157], v[170:173], 0
	v_mfma_f32_16x16x32_bf16 v[38:41], v[146:149], v[170:173], 0
	v_mfma_f32_16x16x32_bf16 v[22:25], v[146:149], v[178:181], 0
	v_mfma_f32_16x16x32_bf16 v[18:21], v[154:157], v[178:181], 0
	v_mfma_f32_16x16x32_bf16 v[2:5], v[154:157], v[216:219], 0
	v_mfma_f32_16x16x32_bf16 v[6:9], v[146:149], v[216:219], 0
	v_mfma_f32_16x16x32_bf16 v[54:57], v[150:153], v[166:169], v[54:57]
	v_mfma_f32_16x16x32_bf16 v[50:53], v[158:161], v[166:169], v[50:53]
	v_mfma_f32_16x16x32_bf16 v[34:37], v[158:161], v[174:177], v[34:37]
	v_mfma_f32_16x16x32_bf16 v[38:41], v[150:153], v[174:177], v[38:41]
	v_mfma_f32_16x16x32_bf16 v[22:25], v[150:153], v[182:185], v[22:25]
	v_mfma_f32_16x16x32_bf16 v[18:21], v[158:161], v[182:185], v[18:21]
	v_mfma_f32_16x16x32_bf16 v[2:5], v[158:161], v[220:223], v[2:5]
	v_mfma_f32_16x16x32_bf16 v[6:9], v[150:153], v[220:223], v[6:9]
	s_barrier
	s_add_i32 s9, 0, 0x18000
	s_add_i32 s12, 0, 0x1c000
	ds_read_b128 v[66:69], v198
	ds_read_b128 v[70:73], v198 offset:1024
	ds_read_b128 v[78:81], v198 offset:2048
	ds_read_b128 v[86:89], v198 offset:3072
	ds_read_b128 v[146:149], v199
	ds_read_b128 v[150:153], v199 offset:1024
	ds_read_b128 v[154:157], v199 offset:2048
	ds_read_b128 v[158:161], v199 offset:3072
	s_add_u32 s10, s94, 0x80000
	s_addc_u32 s11, s95, 0
	s_mov_b32 m0, s59
	ds_read_b128 v[162:165], v236 offset:32768
	ds_read_b128 v[166:169], v236 offset:33792
	ds_read_b128 v[170:173], v236 offset:34816
	ds_read_b128 v[174:177], v236 offset:35840
	ds_read_b128 v[178:181], v236 offset:36864
	ds_read_b128 v[182:185], v236 offset:37888
	ds_read_b128 v[216:219], v236 offset:38912
	ds_read_b128 v[220:223], v236 offset:39936
	global_load_lds_dwordx4 v210, s[10:11]
	s_mov_b32 m0, s74
	s_nop 0
	global_load_lds_dwordx4 v208, s[10:11]
	s_waitcnt vmcnt(8)
	s_waitcnt lgkmcnt(0)
	s_barrier
	v_mfma_f32_16x16x32_bf16 v[142:145], v[66:69], v[162:165], v[142:145]
	v_mfma_f32_16x16x32_bf16 v[138:141], v[78:81], v[162:165], v[138:141]
	v_mfma_f32_16x16x32_bf16 v[122:125], v[78:81], v[170:173], v[122:125]
	v_mfma_f32_16x16x32_bf16 v[126:129], v[66:69], v[170:173], v[126:129]
	v_mfma_f32_16x16x32_bf16 v[110:113], v[66:69], v[178:181], v[110:113]
	v_mfma_f32_16x16x32_bf16 v[106:109], v[78:81], v[178:181], v[106:109]
	v_mfma_f32_16x16x32_bf16 v[90:93], v[78:81], v[216:219], v[90:93]
	v_mfma_f32_16x16x32_bf16 v[94:97], v[66:69], v[216:219], v[94:97]
	v_mfma_f32_16x16x32_bf16 v[142:145], v[70:73], v[166:169], v[142:145]
	v_mfma_f32_16x16x32_bf16 v[138:141], v[86:89], v[166:169], v[138:141]
	v_mfma_f32_16x16x32_bf16 v[122:125], v[86:89], v[174:177], v[122:125]
	v_mfma_f32_16x16x32_bf16 v[126:129], v[70:73], v[174:177], v[126:129]
	v_mfma_f32_16x16x32_bf16 v[110:113], v[70:73], v[182:185], v[110:113]
	v_mfma_f32_16x16x32_bf16 v[106:109], v[86:89], v[182:185], v[106:109]
	v_mfma_f32_16x16x32_bf16 v[90:93], v[86:89], v[220:223], v[90:93]
	v_mfma_f32_16x16x32_bf16 v[94:97], v[70:73], v[220:223], v[94:97]
	v_mfma_f32_16x16x32_bf16 v[134:137], v[146:149], v[162:165], v[134:137]
	v_mfma_f32_16x16x32_bf16 v[130:133], v[154:157], v[162:165], v[130:133]
	v_mfma_f32_16x16x32_bf16 v[114:117], v[154:157], v[170:173], v[114:117]
	v_mfma_f32_16x16x32_bf16 v[118:121], v[146:149], v[170:173], v[118:121]
	v_mfma_f32_16x16x32_bf16 v[102:105], v[146:149], v[178:181], v[102:105]
	v_mfma_f32_16x16x32_bf16 v[98:101], v[154:157], v[178:181], v[98:101]
	v_mfma_f32_16x16x32_bf16 v[74:77], v[154:157], v[216:219], v[74:77]
	v_mfma_f32_16x16x32_bf16 v[82:85], v[146:149], v[216:219], v[82:85]
	v_mfma_f32_16x16x32_bf16 v[134:137], v[150:153], v[166:169], v[134:137]
	v_mfma_f32_16x16x32_bf16 v[130:133], v[158:161], v[166:169], v[130:133]
	v_mfma_f32_16x16x32_bf16 v[114:117], v[158:161], v[174:177], v[114:117]
	v_mfma_f32_16x16x32_bf16 v[118:121], v[150:153], v[174:177], v[118:121]
	v_mfma_f32_16x16x32_bf16 v[102:105], v[150:153], v[182:185], v[102:105]
	v_mfma_f32_16x16x32_bf16 v[98:101], v[158:161], v[182:185], v[98:101]
	v_mfma_f32_16x16x32_bf16 v[74:77], v[158:161], v[220:223], v[74:77]
	v_mfma_f32_16x16x32_bf16 v[82:85], v[150:153], v[220:223], v[82:85]
	s_barrier
; #define PG8_STAGE(bufoff, gbase, voff) do { _Pragma("unroll") for (int _i = 0; _i < 2; ++_i) \
;         __builtin_amdgcn_global_load_lds((const unsigned*)((const char*)(gbase) + (voff)[_i]), (PG8_LAS unsigned*)(lds + (bufoff) + ldsw + _i * 8192), 16, 0, 0); } while (0)
; #define PG8_LDA(dst, b, h) do { _Pragma("unroll") for (int m = 0; m < 4; ++m) _Pragma("unroll") for (int k = 0; k < 2; ++k) dst[m][k] = *(const PG8_LAS bf16x8*)(lds + PG8_SA(b, h) + aoff + m * 2048 + k * 1024); } while (0)
; #define PG8_LDB(dst, b, h) do { _Pragma("unroll") for (int n = 0; n < 2; ++n) _Pragma("unroll") for (int k = 0; k < 2; ++k) dst[n][k] = *(const PG8_LAS bf16x8*)(lds + PG8_SB(b, h) + boff + n * 2048 + k * 1024); } while (0)
; #define PG8_MMA(ai, bj, At, Bt) do { __builtin_amdgcn_s_setprio(1); _Pragma("unroll") for (int m = 0; m < 4; ++m) _Pragma("unroll") for (int n = 0; n < 2; ++n) _Pragma("unroll") for (int k = 0; k < 2; ++k) \
;         acc[ai][bj][m][n] = __builtin_amdgcn_mfma_f32_16x16x32_bf16(Bt[n][k], At[m][k], acc[ai][bj][m][n], 0, 0, 0); __builtin_amdgcn_s_setprio(0); } while (0)
; #define PG8_WAIT_V(n) asm volatile("s_waitcnt vmcnt(" #n ")" ::: "memory")
; #define PG8_WAIT_L(n) asm volatile("s_waitcnt lgkmcnt(" #n ")" ::: "memory")
; #define PG8_BAR __builtin_amdgcn_s_barrier()
; #define PG8_SCHED __builtin_amdgcn_sched_barrier(0)
; template <class Epi, class Sched, bool ALIGN_EPI = false, bool SP2 = false>
; __device__ __forceinline__ void gemm_phase(PG8_LAS unsigned char* lds, const Gemm g, const Sched& S, const Epi& E) {
;     ...
;             PG8_LDB(B0, 0, 0); PG8_LDB(B1, 0, 1); PG8_SCHED; PG8_LDA(At, 0, 0); PG8_STAGE(PG8_SA(1, 1), a1 + hstep, voffA);
;             PG8_WAIT_V(8); PG8_WAIT_L(0); PG8_BAR; PG8_MMA(0, 0, At, B0); PG8_MMA(0, 1, At, B1); PG8_BAR; PG8_SCHED;
;     ...
;             PG8_LDA(At, 1, 1); PG8_STAGE(PG8_SB(1, 0), b3, voffB); PG8_STAGE(PG8_SB(1, 1), b3 + hstepB, voffB); PG8_STAGE(PG8_SA(1, 0), a3, voffA);
;             PG8_WAIT_V(8); PG8_WAIT_L(0); PG8_BAR; PG8_MMA(1, 0, At, B0); PG8_MMA(1, 1, At, B1); PG8_BAR; PG8_SCHED;
	s_add_i32 s9, s9, s25
	s_mov_b32 m0, s9
	ds_read_b128 v[162:165], v236 offset:49152
	ds_read_b128 v[166:169], v236 offset:50176
	ds_read_b128 v[170:173], v236 offset:51200
	ds_read_b128 v[174:177], v236 offset:52224
	ds_read_b128 v[178:181], v236 offset:53248
	ds_read_b128 v[182:185], v236 offset:54272
	ds_read_b128 v[216:219], v236 offset:55296
	ds_read_b128 v[220:223], v236 offset:56320
	s_add_u32 s100, s46, s60
	s_addc_u32 s101, s47, s61
	global_load_lds_dwordx4 v190, s[100:101]
	s_add_i32 m0, s9, 0x2000
	s_add_u32 s10, s46, 0x20080
	s_addc_u32 s11, s47, 0
	s_add_i32 s9, s12, s25
	global_load_lds_dwordx4 v206, s[100:101]
	s_mov_b32 m0, s9
	s_nop 0
	global_load_lds_dwordx4 v190, s[10:11]
	s_add_i32 m0, s9, 0x2000
	s_nop 0
	global_load_lds_dwordx4 v206, s[10:11]
	s_mov_b32 m0, s75
	s_add_u32 s100, s94, s60
	s_addc_u32 s101, s95, s61
	global_load_lds_dwordx4 v210, s[100:101]
	s_mov_b32 m0, s0
	s_nop 0
	global_load_lds_dwordx4 v208, s[100:101]
	s_waitcnt vmcnt(8)
	s_waitcnt lgkmcnt(0)
	s_barrier
	v_mfma_f32_16x16x32_bf16 v[62:65], v[66:69], v[162:165], v[62:65]
	v_mfma_f32_16x16x32_bf16 v[58:61], v[78:81], v[162:165], v[58:61]
	v_mfma_f32_16x16x32_bf16 v[42:45], v[78:81], v[170:173], v[42:45]
	v_mfma_f32_16x16x32_bf16 v[46:49], v[66:69], v[170:173], v[46:49]
	v_mfma_f32_16x16x32_bf16 v[30:33], v[66:69], v[178:181], v[30:33]
	v_mfma_f32_16x16x32_bf16 v[26:29], v[78:81], v[178:181], v[26:29]
	v_mfma_f32_16x16x32_bf16 v[10:13], v[78:81], v[216:219], v[10:13]
	v_mfma_f32_16x16x32_bf16 v[14:17], v[66:69], v[216:219], v[14:17]
	v_mfma_f32_16x16x32_bf16 v[62:65], v[70:73], v[166:169], v[62:65]
	v_mfma_f32_16x16x32_bf16 v[58:61], v[86:89], v[166:169], v[58:61]
	v_mfma_f32_16x16x32_bf16 v[42:45], v[86:89], v[174:177], v[42:45]
	v_mfma_f32_16x16x32_bf16 v[46:49], v[70:73], v[174:177], v[46:49]
	v_mfma_f32_16x16x32_bf16 v[30:33], v[70:73], v[182:185], v[30:33]
	v_mfma_f32_16x16x32_bf16 v[26:29], v[86:89], v[182:185], v[26:29]
	v_mfma_f32_16x16x32_bf16 v[10:13], v[86:89], v[220:223], v[10:13]
	v_mfma_f32_16x16x32_bf16 v[14:17], v[70:73], v[220:223], v[14:17]
	v_mfma_f32_16x16x32_bf16 v[54:57], v[146:149], v[162:165], v[54:57]
	v_mfma_f32_16x16x32_bf16 v[50:53], v[154:157], v[162:165], v[50:53]
	v_mfma_f32_16x16x32_bf16 v[34:37], v[154:157], v[170:173], v[34:37]
	v_mfma_f32_16x16x32_bf16 v[38:41], v[146:149], v[170:173], v[38:41]
	v_mfma_f32_16x16x32_bf16 v[22:25], v[146:149], v[178:181], v[22:25]
	v_mfma_f32_16x16x32_bf16 v[18:21], v[154:157], v[178:181], v[18:21]
	v_mfma_f32_16x16x32_bf16 v[2:5], v[154:157], v[216:219], v[2:5]
	v_mfma_f32_16x16x32_bf16 v[6:9], v[146:149], v[216:219], v[6:9]
	v_mfma_f32_16x16x32_bf16 v[54:57], v[150:153], v[166:169], v[54:57]
	v_mfma_f32_16x16x32_bf16 v[50:53], v[158:161], v[166:169], v[50:53]
	v_mfma_f32_16x16x32_bf16 v[34:37], v[158:161], v[174:177], v[34:37]
	v_mfma_f32_16x16x32_bf16 v[38:41], v[150:153], v[174:177], v[38:41]
	v_mfma_f32_16x16x32_bf16 v[22:25], v[150:153], v[182:185], v[22:25]
	v_mfma_f32_16x16x32_bf16 v[18:21], v[158:161], v[182:185], v[18:21]
	v_mfma_f32_16x16x32_bf16 v[2:5], v[158:161], v[220:223], v[2:5]
	v_mfma_f32_16x16x32_bf16 v[6:9], v[150:153], v[220:223], v[6:9]
	s_barrier
	s_add_i32 s8, s8, 2
	s_add_u32 s38, s38, 0x100
	s_addc_u32 s39, s39, 0
	s_add_u32 s6, s6, 0x100
	s_addc_u32 s7, s7, 0
	s_cmp_gt_u32 s8, 29
.LBB0_927:
	s_add_u32 s9, s38, 0xfff80080
	s_addc_u32 s10, s39, -1
	s_add_i32 s11, 0, 0x10000
	s_cmp_eq_u32 s8, 28
	s_cselect_b32 s95, s36, s10
	s_cselect_b32 s94, s37, s9
	s_cselect_b32 s47, s4, s7
	s_cselect_b32 s46, s5, s6
	s_add_i32 s9, 0, 0x14000
	ds_read_b128 v[66:69], v186
	ds_read_b128 v[70:73], v186 offset:1024
	ds_read_b128 v[78:81], v186 offset:2048
	ds_read_b128 v[86:89], v186 offset:3072
	ds_read_b128 v[146:149], v187
	ds_read_b128 v[150:153], v187 offset:1024
	ds_read_b128 v[154:157], v187 offset:2048
	ds_read_b128 v[158:161], v187 offset:3072
	s_add_i32 m0, s66, 0xc000
	ds_read_b128 v[162:165], v236
	ds_read_b128 v[166:169], v236 offset:1024
	ds_read_b128 v[170:173], v236 offset:2048
	ds_read_b128 v[174:177], v236 offset:3072
	ds_read_b128 v[178:181], v236 offset:4096
	ds_read_b128 v[182:185], v236 offset:5120
	ds_read_b128 v[216:219], v236 offset:6144
	ds_read_b128 v[220:223], v236 offset:7168
	global_load_lds_dwordx4 v212, s[38:39]
	s_add_i32 m0, s66, 0xe000
	s_nop 0
	global_load_lds_dwordx4 v214, s[38:39]
	s_waitcnt vmcnt(8)
	s_waitcnt lgkmcnt(0)
	s_barrier
	v_mfma_f32_16x16x32_bf16 v[142:145], v[66:69], v[162:165], v[142:145]
	v_mfma_f32_16x16x32_bf16 v[138:141], v[78:81], v[162:165], v[138:141]
	v_mfma_f32_16x16x32_bf16 v[122:125], v[78:81], v[170:173], v[122:125]
	v_mfma_f32_16x16x32_bf16 v[126:129], v[66:69], v[170:173], v[126:129]
	v_mfma_f32_16x16x32_bf16 v[110:113], v[66:69], v[178:181], v[110:113]
	v_mfma_f32_16x16x32_bf16 v[106:109], v[78:81], v[178:181], v[106:109]
	v_mfma_f32_16x16x32_bf16 v[90:93], v[78:81], v[216:219], v[90:93]
	v_mfma_f32_16x16x32_bf16 v[94:97], v[66:69], v[216:219], v[94:97]
	v_mfma_f32_16x16x32_bf16 v[142:145], v[70:73], v[166:169], v[142:145]
	v_mfma_f32_16x16x32_bf16 v[138:141], v[86:89], v[166:169], v[138:141]
	v_mfma_f32_16x16x32_bf16 v[122:125], v[86:89], v[174:177], v[122:125]
	v_mfma_f32_16x16x32_bf16 v[126:129], v[70:73], v[174:177], v[126:129]
	v_mfma_f32_16x16x32_bf16 v[110:113], v[70:73], v[182:185], v[110:113]
	v_mfma_f32_16x16x32_bf16 v[106:109], v[86:89], v[182:185], v[106:109]
	v_mfma_f32_16x16x32_bf16 v[90:93], v[86:89], v[220:223], v[90:93]
	v_mfma_f32_16x16x32_bf16 v[94:97], v[70:73], v[220:223], v[94:97]
	v_mfma_f32_16x16x32_bf16 v[134:137], v[146:149], v[162:165], v[134:137]
	v_mfma_f32_16x16x32_bf16 v[130:133], v[154:157], v[162:165], v[130:133]
	v_mfma_f32_16x16x32_bf16 v[114:117], v[154:157], v[170:173], v[114:117]
	v_mfma_f32_16x16x32_bf16 v[118:121], v[146:149], v[170:173], v[118:121]
	v_mfma_f32_16x16x32_bf16 v[102:105], v[146:149], v[178:181], v[102:105]
	v_mfma_f32_16x16x32_bf16 v[98:101], v[154:157], v[178:181], v[98:101]
	v_mfma_f32_16x16x32_bf16 v[74:77], v[154:157], v[216:219], v[74:77]
	v_mfma_f32_16x16x32_bf16 v[82:85], v[146:149], v[216:219], v[82:85]
	v_mfma_f32_16x16x32_bf16 v[134:137], v[150:153], v[166:169], v[134:137]
	v_mfma_f32_16x16x32_bf16 v[130:133], v[158:161], v[166:169], v[130:133]
	v_mfma_f32_16x16x32_bf16 v[114:117], v[158:161], v[174:177], v[114:117]
	v_mfma_f32_16x16x32_bf16 v[118:121], v[150:153], v[174:177], v[118:121]
	v_mfma_f32_16x16x32_bf16 v[102:105], v[150:153], v[182:185], v[102:105]
	v_mfma_f32_16x16x32_bf16 v[98:101], v[158:161], v[182:185], v[98:101]
	v_mfma_f32_16x16x32_bf16 v[74:77], v[158:161], v[220:223], v[74:77]
	v_mfma_f32_16x16x32_bf16 v[82:85], v[150:153], v[220:223], v[82:85]
	s_barrier
; #define PG8_STAGE(bufoff, gbase, voff) do { _Pragma("unroll") for (int _i = 0; _i < 2; ++_i) \
;         __builtin_amdgcn_global_load_lds((const unsigned*)((const char*)(gbase) + (voff)[_i]), (PG8_LAS unsigned*)(lds + (bufoff) + ldsw + _i * 8192), 16, 0, 0); } while (0)
; #define PG8_LDA(dst, b, h) do { _Pragma("unroll") for (int m = 0; m < 4; ++m) _Pragma("unroll") for (int k = 0; k < 2; ++k) dst[m][k] = *(const PG8_LAS bf16x8*)(lds + PG8_SA(b, h) + aoff + m * 2048 + k * 1024); } while (0)
; #define PG8_LDB(dst, b, h) do { _Pragma("unroll") for (int n = 0; n < 2; ++n) _Pragma("unroll") for (int k = 0; k < 2; ++k) dst[n][k] = *(const PG8_LAS bf16x8*)(lds + PG8_SB(b, h) + boff + n * 2048 + k * 1024); } while (0)
; #define PG8_MMA(ai, bj, At, Bt) do { __builtin_amdgcn_s_setprio(1); _Pragma("unroll") for (int m = 0; m < 4; ++m) _Pragma("unroll") for (int n = 0; n < 2; ++n) _Pragma("unroll") for (int k = 0; k < 2; ++k) \
;         acc[ai][bj][m][n] = __builtin_amdgcn_mfma_f32_16x16x32_bf16(Bt[n][k], At[m][k], acc[ai][bj][m][n], 0, 0, 0); __builtin_amdgcn_s_setprio(0); } while (0)
; #define PG8_WAIT_V(n) asm volatile("s_waitcnt vmcnt(" #n ")" ::: "memory")
; #define PG8_WAIT_L(n) asm volatile("s_waitcnt lgkmcnt(" #n ")" ::: "memory")
; #define PG8_BAR __builtin_amdgcn_s_barrier()
; #define PG8_SCHED __builtin_amdgcn_sched_barrier(0)
; template <class Epi, class Sched, bool ALIGN_EPI = false, bool SP2 = false>
; __device__ __forceinline__ void gemm_phase(PG8_LAS unsigned char* lds, const Gemm g, const Sched& S, const Epi& E) {
;     ...
;             PG8_LDA(At, 0, 1); PG8_STAGE(PG8_SB(0, 0), b2, voffB); PG8_STAGE(PG8_SB(0, 1), b2 + hstepB, voffB); PG8_STAGE(PG8_SA(0, 0), a2, voffA);
;             PG8_WAIT_V(8); PG8_WAIT_L(0); PG8_BAR; PG8_MMA(1, 0, At, B0); PG8_MMA(1, 1, At, B1); PG8_BAR; PG8_SCHED;
;             PG8_LDB(B0, 1, 0); PG8_LDB(B1, 1, 1); PG8_SCHED; PG8_LDA(At, 1, 0); PG8_STAGE(PG8_SA(0, 1), a2 + hstep, voffA);
	s_add_i32 s10, s11, s25
	s_mov_b32 m0, s10
	ds_read_b128 v[162:165], v236 offset:16384
	ds_read_b128 v[166:169], v236 offset:17408
	ds_read_b128 v[170:173], v236 offset:18432
	ds_read_b128 v[174:177], v236 offset:19456
	ds_read_b128 v[178:181], v236 offset:20480
	ds_read_b128 v[182:185], v236 offset:21504
	ds_read_b128 v[216:219], v236 offset:22528
	ds_read_b128 v[220:223], v236 offset:23552
	global_load_lds_dwordx4 v190, s[46:47]
	s_add_i32 m0, s10, 0x2000
	s_add_u32 s10, s46, 0x20000
	s_addc_u32 s11, s47, 0
	s_add_i32 s9, s9, s25
	global_load_lds_dwordx4 v206, s[46:47]
	s_mov_b32 m0, s9
	s_nop 0
	global_load_lds_dwordx4 v190, s[10:11]
	s_add_i32 m0, s9, 0x2000
	s_nop 0
	global_load_lds_dwordx4 v206, s[10:11]
	s_mov_b32 m0, s66
	s_nop 0
	global_load_lds_dwordx4 v210, s[94:95]
	s_mov_b32 m0, s67
	s_nop 0
	global_load_lds_dwordx4 v208, s[94:95]
	s_waitcnt vmcnt(8)
	s_waitcnt lgkmcnt(0)
	s_barrier
	v_mfma_f32_16x16x32_bf16 v[62:65], v[66:69], v[162:165], v[62:65]
	v_mfma_f32_16x16x32_bf16 v[58:61], v[78:81], v[162:165], v[58:61]
	v_mfma_f32_16x16x32_bf16 v[42:45], v[78:81], v[170:173], v[42:45]
	v_mfma_f32_16x16x32_bf16 v[46:49], v[66:69], v[170:173], v[46:49]
	v_mfma_f32_16x16x32_bf16 v[30:33], v[66:69], v[178:181], v[30:33]
	v_mfma_f32_16x16x32_bf16 v[26:29], v[78:81], v[178:181], v[26:29]
	v_mfma_f32_16x16x32_bf16 v[10:13], v[78:81], v[216:219], v[10:13]
	v_mfma_f32_16x16x32_bf16 v[14:17], v[66:69], v[216:219], v[14:17]
	v_mfma_f32_16x16x32_bf16 v[62:65], v[70:73], v[166:169], v[62:65]
	v_mfma_f32_16x16x32_bf16 v[58:61], v[86:89], v[166:169], v[58:61]
	v_mfma_f32_16x16x32_bf16 v[42:45], v[86:89], v[174:177], v[42:45]
	v_mfma_f32_16x16x32_bf16 v[46:49], v[70:73], v[174:177], v[46:49]
	v_mfma_f32_16x16x32_bf16 v[30:33], v[70:73], v[182:185], v[30:33]
	v_mfma_f32_16x16x32_bf16 v[26:29], v[86:89], v[182:185], v[26:29]
	v_mfma_f32_16x16x32_bf16 v[10:13], v[86:89], v[220:223], v[10:13]
	v_mfma_f32_16x16x32_bf16 v[14:17], v[70:73], v[220:223], v[14:17]
	v_mfma_f32_16x16x32_bf16 v[54:57], v[146:149], v[162:165], v[54:57]
	v_mfma_f32_16x16x32_bf16 v[50:53], v[154:157], v[162:165], v[50:53]
	v_mfma_f32_16x16x32_bf16 v[34:37], v[154:157], v[170:173], v[34:37]
	v_mfma_f32_16x16x32_bf16 v[38:41], v[146:149], v[170:173], v[38:41]
	v_mfma_f32_16x16x32_bf16 v[22:25], v[146:149], v[178:181], v[22:25]
	v_mfma_f32_16x16x32_bf16 v[18:21], v[154:157], v[178:181], v[18:21]
	v_mfma_f32_16x16x32_bf16 v[2:5], v[154:157], v[216:219], v[2:5]
	v_mfma_f32_16x16x32_bf16 v[6:9], v[146:149], v[216:219], v[6:9]
	v_mfma_f32_16x16x32_bf16 v[54:57], v[150:153], v[166:169], v[54:57]
	v_mfma_f32_16x16x32_bf16 v[50:53], v[158:161], v[166:169], v[50:53]
	v_mfma_f32_16x16x32_bf16 v[34:37], v[158:161], v[174:177], v[34:37]
	v_mfma_f32_16x16x32_bf16 v[38:41], v[150:153], v[174:177], v[38:41]
	v_mfma_f32_16x16x32_bf16 v[22:25], v[150:153], v[182:185], v[22:25]
	v_mfma_f32_16x16x32_bf16 v[18:21], v[158:161], v[182:185], v[18:21]
	v_mfma_f32_16x16x32_bf16 v[2:5], v[158:161], v[220:223], v[2:5]
	v_mfma_f32_16x16x32_bf16 v[6:9], v[150:153], v[220:223], v[6:9]
	s_barrier
	s_add_i32 s9, 0, 0x18000
	s_add_i32 s12, 0, 0x1c000
	ds_read_b128 v[66:69], v198
	ds_read_b128 v[70:73], v198 offset:1024
	ds_read_b128 v[78:81], v198 offset:2048
	ds_read_b128 v[86:89], v198 offset:3072
	ds_read_b128 v[146:149], v199
	ds_read_b128 v[150:153], v199 offset:1024
	ds_read_b128 v[154:157], v199 offset:2048
	ds_read_b128 v[158:161], v199 offset:3072
	s_add_u32 s10, s94, 0x80000
	s_addc_u32 s11, s95, 0
	s_mov_b32 m0, s59
	ds_read_b128 v[162:165], v236 offset:32768
	ds_read_b128 v[166:169], v236 offset:33792
	ds_read_b128 v[170:173], v236 offset:34816
	ds_read_b128 v[174:177], v236 offset:35840
	ds_read_b128 v[178:181], v236 offset:36864
	ds_read_b128 v[182:185], v236 offset:37888
	ds_read_b128 v[216:219], v236 offset:38912
	ds_read_b128 v[220:223], v236 offset:39936
	global_load_lds_dwordx4 v210, s[10:11]
	s_mov_b32 m0, s74
	s_nop 0
	global_load_lds_dwordx4 v208, s[10:11]
	s_waitcnt vmcnt(8)
	s_waitcnt lgkmcnt(0)
	s_barrier
; #define PG8_STAGE(bufoff, gbase, voff) do { _Pragma("unroll") for (int _i = 0; _i < 2; ++_i) \
;         __builtin_amdgcn_global_load_lds((const unsigned*)((const char*)(gbase) + (voff)[_i]), (PG8_LAS unsigned*)(lds + (bufoff) + ldsw + _i * 8192), 16, 0, 0); } while (0)
; #define PG8_LDA(dst, b, h) do { _Pragma("unroll") for (int m = 0; m < 4; ++m) _Pragma("unroll") for (int k = 0; k < 2; ++k) dst[m][k] = *(const PG8_LAS bf16x8*)(lds + PG8_SA(b, h) + aoff + m * 2048 + k * 1024); } while (0)
; #define PG8_MMA(ai, bj, At, Bt) do { __builtin_amdgcn_s_setprio(1); _Pragma("unroll") for (int m = 0; m < 4; ++m) _Pragma("unroll") for (int n = 0; n < 2; ++n) _Pragma("unroll") for (int k = 0; k < 2; ++k) \
;         acc[ai][bj][m][n] = __builtin_amdgcn_mfma_f32_16x16x32_bf16(Bt[n][k], At[m][k], acc[ai][bj][m][n], 0, 0, 0); __builtin_amdgcn_s_setprio(0); } while (0)
; #define PG8_WAIT_V(n) asm volatile("s_waitcnt vmcnt(" #n ")" ::: "memory")
; #define PG8_WAIT_L(n) asm volatile("s_waitcnt lgkmcnt(" #n ")" ::: "memory")
; #define PG8_BAR __builtin_amdgcn_s_barrier()
; #define PG8_SCHED __builtin_amdgcn_sched_barrier(0)
; template <class Epi, class Sched, bool ALIGN_EPI = false, bool SP2 = false>
; __device__ __forceinline__ void gemm_phase(PG8_LAS unsigned char* lds, const Gemm g, const Sched& S, const Epi& E) {
;     ...
;             PG8_WAIT_V(8); PG8_WAIT_L(0); PG8_BAR; PG8_MMA(0, 0, At, B0); PG8_MMA(0, 1, At, B1); PG8_BAR; PG8_SCHED;
;             PG8_LDA(At, 1, 1); PG8_STAGE(PG8_SB(1, 0), b3, voffB); PG8_STAGE(PG8_SB(1, 1), b3 + hstepB, voffB); PG8_STAGE(PG8_SA(1, 0), a3, voffA);
;             PG8_WAIT_V(8); PG8_WAIT_L(0); PG8_BAR; PG8_MMA(1, 0, At, B0); PG8_MMA(1, 1, At, B1); PG8_BAR; PG8_SCHED;
;     ...
;         if constexpr (ALIGN_EPI) { if (wr == 0) PG8_BAR; }
;         if constexpr (!Epi::AFTER_DRAIN) { E(acc, cur, wr, wc, fr, fq, ui); S.done(cur); }
;         if (!has_next) break;
	v_mfma_f32_16x16x32_bf16 v[142:145], v[66:69], v[162:165], v[142:145]
	v_mfma_f32_16x16x32_bf16 v[138:141], v[78:81], v[162:165], v[138:141]
	v_mfma_f32_16x16x32_bf16 v[122:125], v[78:81], v[170:173], v[122:125]
	v_mfma_f32_16x16x32_bf16 v[126:129], v[66:69], v[170:173], v[126:129]
	v_mfma_f32_16x16x32_bf16 v[110:113], v[66:69], v[178:181], v[110:113]
	v_mfma_f32_16x16x32_bf16 v[106:109], v[78:81], v[178:181], v[106:109]
	v_mfma_f32_16x16x32_bf16 v[90:93], v[78:81], v[216:219], v[90:93]
	v_mfma_f32_16x16x32_bf16 v[94:97], v[66:69], v[216:219], v[94:97]
	v_mfma_f32_16x16x32_bf16 v[142:145], v[70:73], v[166:169], v[142:145]
	v_mfma_f32_16x16x32_bf16 v[138:141], v[86:89], v[166:169], v[138:141]
	v_mfma_f32_16x16x32_bf16 v[122:125], v[86:89], v[174:177], v[122:125]
	v_mfma_f32_16x16x32_bf16 v[126:129], v[70:73], v[174:177], v[126:129]
	v_mfma_f32_16x16x32_bf16 v[110:113], v[70:73], v[182:185], v[110:113]
	v_mfma_f32_16x16x32_bf16 v[106:109], v[86:89], v[182:185], v[106:109]
	v_mfma_f32_16x16x32_bf16 v[90:93], v[86:89], v[220:223], v[90:93]
	v_mfma_f32_16x16x32_bf16 v[94:97], v[70:73], v[220:223], v[94:97]
	v_mfma_f32_16x16x32_bf16 v[134:137], v[146:149], v[162:165], v[134:137]
	v_mfma_f32_16x16x32_bf16 v[130:133], v[154:157], v[162:165], v[130:133]
	v_mfma_f32_16x16x32_bf16 v[114:117], v[154:157], v[170:173], v[114:117]
	v_mfma_f32_16x16x32_bf16 v[118:121], v[146:149], v[170:173], v[118:121]
	v_mfma_f32_16x16x32_bf16 v[102:105], v[146:149], v[178:181], v[102:105]
	v_mfma_f32_16x16x32_bf16 v[98:101], v[154:157], v[178:181], v[98:101]
	v_mfma_f32_16x16x32_bf16 v[74:77], v[154:157], v[216:219], v[74:77]
	v_mfma_f32_16x16x32_bf16 v[82:85], v[146:149], v[216:219], v[82:85]
	v_mfma_f32_16x16x32_bf16 v[134:137], v[150:153], v[166:169], v[134:137]
	v_mfma_f32_16x16x32_bf16 v[130:133], v[158:161], v[166:169], v[130:133]
	v_mfma_f32_16x16x32_bf16 v[114:117], v[158:161], v[174:177], v[114:117]
	v_mfma_f32_16x16x32_bf16 v[118:121], v[150:153], v[174:177], v[118:121]
	v_mfma_f32_16x16x32_bf16 v[102:105], v[150:153], v[182:185], v[102:105]
	v_mfma_f32_16x16x32_bf16 v[98:101], v[158:161], v[182:185], v[98:101]
	v_mfma_f32_16x16x32_bf16 v[74:77], v[158:161], v[220:223], v[74:77]
	v_mfma_f32_16x16x32_bf16 v[82:85], v[150:153], v[220:223], v[82:85]
	s_barrier
	s_add_i32 s9, s9, s25
	s_mov_b32 m0, s9
	ds_read_b128 v[162:165], v236 offset:49152
	ds_read_b128 v[166:169], v236 offset:50176
	ds_read_b128 v[170:173], v236 offset:51200
	ds_read_b128 v[174:177], v236 offset:52224
	ds_read_b128 v[178:181], v236 offset:53248
	ds_read_b128 v[182:185], v236 offset:54272
	ds_read_b128 v[216:219], v236 offset:55296
	ds_read_b128 v[220:223], v236 offset:56320
	s_add_u32 s100, s46, s60
	s_addc_u32 s101, s47, s61
	global_load_lds_dwordx4 v190, s[100:101]
	s_add_i32 m0, s9, 0x2000
	s_add_u32 s10, s46, 0x20080
	s_addc_u32 s11, s47, 0
	s_add_i32 s9, s12, s25
	global_load_lds_dwordx4 v206, s[100:101]
	s_mov_b32 m0, s9
	s_nop 0
	global_load_lds_dwordx4 v190, s[10:11]
	s_add_i32 m0, s9, 0x2000
	s_nop 0
	global_load_lds_dwordx4 v206, s[10:11]
	s_mov_b32 m0, s75
	s_add_u32 s100, s94, s60
	s_addc_u32 s101, s95, s61
	global_load_lds_dwordx4 v210, s[100:101]
	s_mov_b32 m0, s0
	s_nop 0
	global_load_lds_dwordx4 v208, s[100:101]
	s_waitcnt vmcnt(8)
	s_waitcnt lgkmcnt(0)
	s_barrier
	v_mfma_f32_16x16x32_bf16 v[62:65], v[66:69], v[162:165], v[62:65]
	v_mfma_f32_16x16x32_bf16 v[58:61], v[78:81], v[162:165], v[58:61]
	v_mfma_f32_16x16x32_bf16 v[42:45], v[78:81], v[170:173], v[42:45]
	v_mfma_f32_16x16x32_bf16 v[46:49], v[66:69], v[170:173], v[46:49]
	v_mfma_f32_16x16x32_bf16 v[30:33], v[66:69], v[178:181], v[30:33]
	v_mfma_f32_16x16x32_bf16 v[26:29], v[78:81], v[178:181], v[26:29]
	v_mfma_f32_16x16x32_bf16 v[10:13], v[78:81], v[216:219], v[10:13]
	v_mfma_f32_16x16x32_bf16 v[14:17], v[66:69], v[216:219], v[14:17]
	v_mfma_f32_16x16x32_bf16 v[62:65], v[70:73], v[166:169], v[62:65]
	v_mfma_f32_16x16x32_bf16 v[58:61], v[86:89], v[166:169], v[58:61]
	v_mfma_f32_16x16x32_bf16 v[42:45], v[86:89], v[174:177], v[42:45]
	v_mfma_f32_16x16x32_bf16 v[46:49], v[70:73], v[174:177], v[46:49]
	v_mfma_f32_16x16x32_bf16 v[30:33], v[70:73], v[182:185], v[30:33]
	v_mfma_f32_16x16x32_bf16 v[26:29], v[86:89], v[182:185], v[26:29]
	v_mfma_f32_16x16x32_bf16 v[10:13], v[86:89], v[220:223], v[10:13]
	v_mfma_f32_16x16x32_bf16 v[14:17], v[70:73], v[220:223], v[14:17]
	v_mfma_f32_16x16x32_bf16 v[54:57], v[146:149], v[162:165], v[54:57]
	v_mfma_f32_16x16x32_bf16 v[50:53], v[154:157], v[162:165], v[50:53]
	v_mfma_f32_16x16x32_bf16 v[34:37], v[154:157], v[170:173], v[34:37]
	v_mfma_f32_16x16x32_bf16 v[38:41], v[146:149], v[170:173], v[38:41]
	v_mfma_f32_16x16x32_bf16 v[22:25], v[146:149], v[178:181], v[22:25]
	v_mfma_f32_16x16x32_bf16 v[18:21], v[154:157], v[178:181], v[18:21]
	v_mfma_f32_16x16x32_bf16 v[2:5], v[154:157], v[216:219], v[2:5]
	v_mfma_f32_16x16x32_bf16 v[6:9], v[146:149], v[216:219], v[6:9]
	v_mfma_f32_16x16x32_bf16 v[54:57], v[150:153], v[166:169], v[54:57]
	v_mfma_f32_16x16x32_bf16 v[50:53], v[158:161], v[166:169], v[50:53]
	v_mfma_f32_16x16x32_bf16 v[34:37], v[158:161], v[174:177], v[34:37]
	v_mfma_f32_16x16x32_bf16 v[38:41], v[150:153], v[174:177], v[38:41]
	v_mfma_f32_16x16x32_bf16 v[22:25], v[150:153], v[182:185], v[22:25]
	v_mfma_f32_16x16x32_bf16 v[18:21], v[158:161], v[182:185], v[18:21]
	v_mfma_f32_16x16x32_bf16 v[2:5], v[158:161], v[220:223], v[2:5]
	v_mfma_f32_16x16x32_bf16 v[6:9], v[150:153], v[220:223], v[6:9]
	s_barrier
	s_add_i32 s8, s8, 2
	s_add_u32 s38, s38, 0x100
	s_addc_u32 s39, s39, 0
	s_add_u32 s6, s6, 0x100
	s_addc_u32 s7, s7, 0
	s_cmp_gt_u32 s8, 29
	s_cbranch_scc0 .LBB0_927
	s_and_b64 vcc, exec, s[70:71]
	s_cbranch_vccz .LBB0_930
	s_barrier

; #define PG8_STAGE(bufoff, gbase, voff) do { _Pragma("unroll") for (int _i = 0; _i < 2; ++_i) \
;         __builtin_amdgcn_global_load_lds((const unsigned*)((const char*)(gbase) + (voff)[_i]), (PG8_LAS unsigned*)(lds + (bufoff) + ldsw + _i * 8192), 16, 0, 0); } while (0)
; #define PG8_LDA(dst, b, h) do { _Pragma("unroll") for (int m = 0; m < 4; ++m) _Pragma("unroll") for (int k = 0; k < 2; ++k) dst[m][k] = *(const PG8_LAS bf16x8*)(lds + PG8_SA(b, h) + aoff + m * 2048 + k * 1024); } while (0)
; #define PG8_LDB(dst, b, h) do { _Pragma("unroll") for (int n = 0; n < 2; ++n) _Pragma("unroll") for (int k = 0; k < 2; ++k) dst[n][k] = *(const PG8_LAS bf16x8*)(lds + PG8_SB(b, h) + boff + n * 2048 + k * 1024); } while (0)
; #define PG8_WAIT_V(n) asm volatile("s_waitcnt vmcnt(" #n ")" ::: "memory")
; #define PG8_WAIT_L(n) asm volatile("s_waitcnt lgkmcnt(" #n ")" ::: "memory")
; #define PG8_BAR __builtin_amdgcn_s_barrier()
; #define PG8_SCHED __builtin_amdgcn_sched_barrier(0)
; template <class Epi, class Sched, bool ALIGN_EPI = false, bool SP2 = false>
; __device__ __forceinline__ void gemm_phase(PG8_LAS unsigned char* lds, const Gemm g, const Sched& S, const Epi& E) {
;     ...
;         const bool has_next = S.next(ui + 1, nxt);
;         const char* nA = has_next ? (const char*)g.A + (size_t)nxt.pm * tstep : cA; const char* nB = has_next ? (const char*)g.Bt + (size_t)nxt.pn * tstep : cB;
;         for (int t = 0; t < nt; t += 2) {
;             const bool last = (t == nt - 2);
;             const char* a1 = cA + (size_t)(t + 1) * kstep;
;             const char* a2 = last ? nA : cA + (size_t)(t + 2) * kstep; const char* b2 = last ? nB : cB + (size_t)(t + 2) * kstep;
;             const char* a3 = a2 + kstep; const char* b3 = b2 + kstep;
;             if (last && has_next) S.a_ready(nxt);
;             if constexpr (SP2) {
;             PG8_LDB(B0, 0, 0); PG8_LDB(B1, 0, 1); PG8_SCHED; PG8_LDA(At, 0, 0); PG8_STAGE(PG8_SA(1, 1), a1 + hstep, voffA);
;             PG8_WAIT_V(8); PG8_WAIT_L(0); PG8_BAR; PG8_MMA(0, 0, At, B0); PG8_MMA(0, 1, At, B1); PG8_BAR; PG8_SCHED;
;             PG8_LDA(At, 0, 1); PG8_STAGE(PG8_SB(0, 0), b2, voffB); PG8_STAGE(PG8_SB(0, 1), b2 + hstepB, voffB); PG8_STAGE(PG8_SA(0, 0), a2, voffA);
;             PG8_WAIT_V(8); PG8_WAIT_L(0); PG8_BAR; PG8_MMA(1, 0, At, B0); PG8_MMA(1, 1, At, B1); PG8_BAR; PG8_SCHED;
.LBB0_1070:
	s_ashr_i32 s97, s96, 31
	s_lshl_b64 s[4:5], s[96:97], 22
	s_add_u32 s26, s0, s4
	s_addc_u32 s27, s1, s5
	s_and_b64 s[4:5], s[92:93], exec
	s_cselect_b32 s97, s27, s39
	s_cselect_b32 s4, s26, s38
	s_ashr_i32 s85, s84, 31
	s_lshl_b64 s[6:7], s[84:85], 22
	s_add_u32 s94, s56, s6
	s_addc_u32 s95, s57, s7
	s_and_b64 s[6:7], s[92:93], exec
	s_cselect_b32 s5, s95, s47
	s_cselect_b32 s6, s94, s46
	s_add_u32 s38, s38, 0x200080
	s_addc_u32 s39, s39, 0
	s_add_u32 s7, s46, 0x100
	s_addc_u32 s8, s47, 0
	s_mov_b32 s9, -2
	s_waitcnt lgkmcnt(0)
	v_add_u32_e32 v186, 0x10000, v164
	v_add_u32_e32 v187, 0x14000, v164
	v_add_u32_e32 v198, 0x18000, v164
	v_add_u32_e32 v199, 0x1c000, v164
	s_add_u32 s10, s38, 0xffe00080
	s_addc_u32 s11, s39, -1
	s_add_i32 s12, 0, 0x10000
	s_cmpk_eq_i32 s9, 0x7c
	s_cselect_b32 vcc_hi, s97, s11
	s_cselect_b32 vcc_lo, s4, s10
	s_cselect_b32 s47, s5, s8
	s_cselect_b32 s46, s6, s7
	s_add_i32 s13, 0, 0x14000
	ds_read_b128 v[130:133], v186
	ds_read_b128 v[134:137], v186 offset:1024
	ds_read_b128 v[138:141], v186 offset:2048
	ds_read_b128 v[152:155], v186 offset:3072
	ds_read_b128 v[156:159], v187
	ds_read_b128 v[160:163], v187 offset:1024
	ds_read_b128 v[168:171], v187 offset:2048
	ds_read_b128 v[172:175], v187 offset:3072
	s_add_i32 m0, s74, 0xc000
	ds_read_b128 v[176:179], v166
	ds_read_b128 v[180:183], v166 offset:1024
	ds_read_b128 v[206:209], v166 offset:2048
	ds_read_b128 v[210:213], v166 offset:3072
	ds_read_b128 v[214:217], v166 offset:4096
	ds_read_b128 v[218:221], v166 offset:5120
	ds_read_b128 v[236:239], v166 offset:6144
	ds_read_b128 v[240:243], v166 offset:7168
	global_load_lds_dwordx4 v148, s[38:39]
	s_add_i32 m0, s74, 0xe000
	s_nop 0
	global_load_lds_dwordx4 v150, s[38:39]
	s_waitcnt vmcnt(8)
	s_waitcnt lgkmcnt(0)
	s_barrier
	v_mfma_f32_16x16x32_bf16 v[126:129], v[130:133], v[176:179], 0
	v_mfma_f32_16x16x32_bf16 v[122:125], v[138:141], v[176:179], 0
	v_mfma_f32_16x16x32_bf16 v[106:109], v[138:141], v[206:209], 0
	v_mfma_f32_16x16x32_bf16 v[110:113], v[130:133], v[206:209], 0
	v_mfma_f32_16x16x32_bf16 v[94:97], v[130:133], v[214:217], 0
	v_mfma_f32_16x16x32_bf16 v[90:93], v[138:141], v[214:217], 0
	v_mfma_f32_16x16x32_bf16 v[74:77], v[138:141], v[236:239], 0
	v_mfma_f32_16x16x32_bf16 v[78:81], v[130:133], v[236:239], 0
	v_mfma_f32_16x16x32_bf16 v[126:129], v[134:137], v[180:183], v[126:129]
	v_mfma_f32_16x16x32_bf16 v[122:125], v[152:155], v[180:183], v[122:125]
	v_mfma_f32_16x16x32_bf16 v[106:109], v[152:155], v[210:213], v[106:109]
	v_mfma_f32_16x16x32_bf16 v[110:113], v[134:137], v[210:213], v[110:113]
	v_mfma_f32_16x16x32_bf16 v[94:97], v[134:137], v[218:221], v[94:97]
	v_mfma_f32_16x16x32_bf16 v[90:93], v[152:155], v[218:221], v[90:93]
	v_mfma_f32_16x16x32_bf16 v[74:77], v[152:155], v[240:243], v[74:77]
	v_mfma_f32_16x16x32_bf16 v[78:81], v[134:137], v[240:243], v[78:81]
	v_mfma_f32_16x16x32_bf16 v[118:121], v[156:159], v[176:179], 0
	v_mfma_f32_16x16x32_bf16 v[114:117], v[168:171], v[176:179], 0
	v_mfma_f32_16x16x32_bf16 v[98:101], v[168:171], v[206:209], 0
	v_mfma_f32_16x16x32_bf16 v[102:105], v[156:159], v[206:209], 0
	v_mfma_f32_16x16x32_bf16 v[86:89], v[156:159], v[214:217], 0
	v_mfma_f32_16x16x32_bf16 v[82:85], v[168:171], v[214:217], 0
	v_mfma_f32_16x16x32_bf16 v[66:69], v[168:171], v[236:239], 0
	v_mfma_f32_16x16x32_bf16 v[70:73], v[156:159], v[236:239], 0
	v_mfma_f32_16x16x32_bf16 v[118:121], v[160:163], v[180:183], v[118:121]
	v_mfma_f32_16x16x32_bf16 v[114:117], v[172:175], v[180:183], v[114:117]
	v_mfma_f32_16x16x32_bf16 v[98:101], v[172:175], v[210:213], v[98:101]
	v_mfma_f32_16x16x32_bf16 v[102:105], v[160:163], v[210:213], v[102:105]
	v_mfma_f32_16x16x32_bf16 v[86:89], v[160:163], v[218:221], v[86:89]
	v_mfma_f32_16x16x32_bf16 v[82:85], v[172:175], v[218:221], v[82:85]
	v_mfma_f32_16x16x32_bf16 v[66:69], v[172:175], v[240:243], v[66:69]
	v_mfma_f32_16x16x32_bf16 v[70:73], v[160:163], v[240:243], v[70:73]
	s_barrier
	s_add_i32 s10, s12, s67
	s_mov_b32 m0, s10
	ds_read_b128 v[176:179], v166 offset:16384
	ds_read_b128 v[180:183], v166 offset:17408
	ds_read_b128 v[206:209], v166 offset:18432
	ds_read_b128 v[210:213], v166 offset:19456
	ds_read_b128 v[214:217], v166 offset:20480
	ds_read_b128 v[218:221], v166 offset:21504
	ds_read_b128 v[236:239], v166 offset:22528
	ds_read_b128 v[240:243], v166 offset:23552
	global_load_lds_dwordx4 v146, s[46:47]
	s_add_i32 m0, s10, 0x2000
	s_add_u32 s10, s46, 0x80000
	s_addc_u32 s11, s47, 0
	s_add_i32 s12, s13, s67
	global_load_lds_dwordx4 v142, s[46:47]
	s_mov_b32 m0, s12
	s_nop 0
	global_load_lds_dwordx4 v146, s[10:11]
	s_add_i32 m0, s12, 0x2000
	s_nop 0
	global_load_lds_dwordx4 v142, s[10:11]
	s_mov_b32 m0, s74
	s_nop 0
	global_load_lds_dwordx4 v190, vcc
	s_mov_b32 m0, s75
	s_nop 0
	global_load_lds_dwordx4 v144, vcc
	s_waitcnt vmcnt(8)
	s_waitcnt lgkmcnt(0)
	s_barrier
; #define PG8_STAGE(bufoff, gbase, voff) do { _Pragma("unroll") for (int _i = 0; _i < 2; ++_i) \
;         __builtin_amdgcn_global_load_lds((const unsigned*)((const char*)(gbase) + (voff)[_i]), (PG8_LAS unsigned*)(lds + (bufoff) + ldsw + _i * 8192), 16, 0, 0); } while (0)
; #define PG8_LDA(dst, b, h) do { _Pragma("unroll") for (int m = 0; m < 4; ++m) _Pragma("unroll") for (int k = 0; k < 2; ++k) dst[m][k] = *(const PG8_LAS bf16x8*)(lds + PG8_SA(b, h) + aoff + m * 2048 + k * 1024); } while (0)
; #define PG8_LDB(dst, b, h) do { _Pragma("unroll") for (int n = 0; n < 2; ++n) _Pragma("unroll") for (int k = 0; k < 2; ++k) dst[n][k] = *(const PG8_LAS bf16x8*)(lds + PG8_SB(b, h) + boff + n * 2048 + k * 1024); } while (0)
; #define PG8_MMA(ai, bj, At, Bt) do { __builtin_amdgcn_s_setprio(1); _Pragma("unroll") for (int m = 0; m < 4; ++m) _Pragma("unroll") for (int n = 0; n < 2; ++n) _Pragma("unroll") for (int k = 0; k < 2; ++k) \
;         acc[ai][bj][m][n] = __builtin_amdgcn_mfma_f32_16x16x32_bf16(Bt[n][k], At[m][k], acc[ai][bj][m][n], 0, 0, 0); __builtin_amdgcn_s_setprio(0); } while (0)
; #define PG8_WAIT_V(n) asm volatile("s_waitcnt vmcnt(" #n ")" ::: "memory")
; template <class Epi, class Sched, bool ALIGN_EPI = false, bool SP2 = false>
; __device__ __forceinline__ void gemm_phase(PG8_LAS unsigned char* lds, const Gemm g, const Sched& S, const Epi& E) {
;     ...
;             PG8_LDB(B0, 0, 0); PG8_LDB(B1, 0, 1); PG8_SCHED; PG8_LDA(At, 0, 0); PG8_STAGE(PG8_SA(1, 1), a1 + hstep, voffA);
;             PG8_WAIT_V(8); PG8_WAIT_L(0); PG8_BAR; PG8_MMA(0, 0, At, B0); PG8_MMA(0, 1, At, B1); PG8_BAR; PG8_SCHED;
;             PG8_LDA(At, 0, 1); PG8_STAGE(PG8_SB(0, 0), b2, voffB); PG8_STAGE(PG8_SB(0, 1), b2 + hstepB, voffB); PG8_STAGE(PG8_SA(0, 0), a2, voffA);
;             PG8_WAIT_V(8); PG8_WAIT_L(0); PG8_BAR; PG8_MMA(1, 0, At, B0); PG8_MMA(1, 1, At, B1); PG8_BAR; PG8_SCHED;
;             PG8_LDB(B0, 1, 0); PG8_LDB(B1, 1, 1); PG8_SCHED; PG8_LDA(At, 1, 0); PG8_STAGE(PG8_SA(0, 1), a2 + hstep, voffA);
;             PG8_WAIT_V(8); PG8_WAIT_L(0); PG8_BAR; PG8_MMA(0, 0, At, B0); PG8_MMA(0, 1, At, B1); PG8_BAR; PG8_SCHED;
;             PG8_LDA(At, 1, 1); PG8_STAGE(PG8_SB(1, 0), b3, voffB); PG8_STAGE(PG8_SB(1, 1), b3 + hstepB, voffB); PG8_STAGE(PG8_SA(1, 0), a3, voffA);
;             PG8_WAIT_V(8); PG8_WAIT_L(0); PG8_BAR; PG8_MMA(1, 0, At, B0); PG8_MMA(1, 1, At, B1); PG8_BAR; PG8_SCHED;
	v_mfma_f32_16x16x32_bf16 v[62:65], v[130:133], v[176:179], 0
	v_mfma_f32_16x16x32_bf16 v[58:61], v[138:141], v[176:179], 0
	v_mfma_f32_16x16x32_bf16 v[42:45], v[138:141], v[206:209], 0
	v_mfma_f32_16x16x32_bf16 v[46:49], v[130:133], v[206:209], 0
	v_mfma_f32_16x16x32_bf16 v[30:33], v[130:133], v[214:217], 0
	v_mfma_f32_16x16x32_bf16 v[26:29], v[138:141], v[214:217], 0
	v_mfma_f32_16x16x32_bf16 v[10:13], v[138:141], v[236:239], 0
	v_mfma_f32_16x16x32_bf16 v[14:17], v[130:133], v[236:239], 0
	v_mfma_f32_16x16x32_bf16 v[62:65], v[134:137], v[180:183], v[62:65]
	v_mfma_f32_16x16x32_bf16 v[58:61], v[152:155], v[180:183], v[58:61]
	v_mfma_f32_16x16x32_bf16 v[42:45], v[152:155], v[210:213], v[42:45]
	v_mfma_f32_16x16x32_bf16 v[46:49], v[134:137], v[210:213], v[46:49]
	v_mfma_f32_16x16x32_bf16 v[30:33], v[134:137], v[218:221], v[30:33]
	v_mfma_f32_16x16x32_bf16 v[26:29], v[152:155], v[218:221], v[26:29]
	v_mfma_f32_16x16x32_bf16 v[10:13], v[152:155], v[240:243], v[10:13]
	v_mfma_f32_16x16x32_bf16 v[14:17], v[134:137], v[240:243], v[14:17]
	v_mfma_f32_16x16x32_bf16 v[54:57], v[156:159], v[176:179], 0
	v_mfma_f32_16x16x32_bf16 v[50:53], v[168:171], v[176:179], 0
	v_mfma_f32_16x16x32_bf16 v[34:37], v[168:171], v[206:209], 0
	v_mfma_f32_16x16x32_bf16 v[38:41], v[156:159], v[206:209], 0
	v_mfma_f32_16x16x32_bf16 v[22:25], v[156:159], v[214:217], 0
	v_mfma_f32_16x16x32_bf16 v[18:21], v[168:171], v[214:217], 0
	v_mfma_f32_16x16x32_bf16 v[2:5], v[168:171], v[236:239], 0
	v_mfma_f32_16x16x32_bf16 v[6:9], v[156:159], v[236:239], 0
	v_mfma_f32_16x16x32_bf16 v[54:57], v[160:163], v[180:183], v[54:57]
	v_mfma_f32_16x16x32_bf16 v[50:53], v[172:175], v[180:183], v[50:53]
	v_mfma_f32_16x16x32_bf16 v[34:37], v[172:175], v[210:213], v[34:37]
	v_mfma_f32_16x16x32_bf16 v[38:41], v[160:163], v[210:213], v[38:41]
	v_mfma_f32_16x16x32_bf16 v[22:25], v[160:163], v[218:221], v[22:25]
	v_mfma_f32_16x16x32_bf16 v[18:21], v[172:175], v[218:221], v[18:21]
	v_mfma_f32_16x16x32_bf16 v[2:5], v[172:175], v[240:243], v[2:5]
	v_mfma_f32_16x16x32_bf16 v[6:9], v[160:163], v[240:243], v[6:9]
	s_barrier
	s_add_i32 s12, 0, 0x18000
	s_add_i32 s13, 0, 0x1c000
	ds_read_b128 v[130:133], v198
	ds_read_b128 v[134:137], v198 offset:1024
	ds_read_b128 v[138:141], v198 offset:2048
	ds_read_b128 v[152:155], v198 offset:3072
	ds_read_b128 v[156:159], v199
	ds_read_b128 v[160:163], v199 offset:1024
	ds_read_b128 v[168:171], v199 offset:2048
	ds_read_b128 v[172:175], v199 offset:3072
	s_add_u32 s10, vcc_lo, 0x200000
	s_addc_u32 s11, vcc_hi, 0
	s_mov_b32 m0, s86
	ds_read_b128 v[176:179], v166 offset:32768
	ds_read_b128 v[180:183], v166 offset:33792
	ds_read_b128 v[206:209], v166 offset:34816
	ds_read_b128 v[210:213], v166 offset:35840
	ds_read_b128 v[214:217], v166 offset:36864
	ds_read_b128 v[218:221], v166 offset:37888
	ds_read_b128 v[236:239], v166 offset:38912
	ds_read_b128 v[240:243], v166 offset:39936
	global_load_lds_dwordx4 v190, s[10:11]
	s_mov_b32 m0, s87
	s_nop 0
	global_load_lds_dwordx4 v144, s[10:11]
	s_waitcnt vmcnt(8)
	s_waitcnt lgkmcnt(0)
	s_barrier
	v_mfma_f32_16x16x32_bf16 v[126:129], v[130:133], v[176:179], v[126:129]
	v_mfma_f32_16x16x32_bf16 v[122:125], v[138:141], v[176:179], v[122:125]
	v_mfma_f32_16x16x32_bf16 v[106:109], v[138:141], v[206:209], v[106:109]
	v_mfma_f32_16x16x32_bf16 v[110:113], v[130:133], v[206:209], v[110:113]
	v_mfma_f32_16x16x32_bf16 v[94:97], v[130:133], v[214:217], v[94:97]
	v_mfma_f32_16x16x32_bf16 v[90:93], v[138:141], v[214:217], v[90:93]
	v_mfma_f32_16x16x32_bf16 v[74:77], v[138:141], v[236:239], v[74:77]
	v_mfma_f32_16x16x32_bf16 v[78:81], v[130:133], v[236:239], v[78:81]
	v_mfma_f32_16x16x32_bf16 v[126:129], v[134:137], v[180:183], v[126:129]
	v_mfma_f32_16x16x32_bf16 v[122:125], v[152:155], v[180:183], v[122:125]
	v_mfma_f32_16x16x32_bf16 v[106:109], v[152:155], v[210:213], v[106:109]
	v_mfma_f32_16x16x32_bf16 v[110:113], v[134:137], v[210:213], v[110:113]
	v_mfma_f32_16x16x32_bf16 v[94:97], v[134:137], v[218:221], v[94:97]
	v_mfma_f32_16x16x32_bf16 v[90:93], v[152:155], v[218:221], v[90:93]
	v_mfma_f32_16x16x32_bf16 v[74:77], v[152:155], v[240:243], v[74:77]
	v_mfma_f32_16x16x32_bf16 v[78:81], v[134:137], v[240:243], v[78:81]
	v_mfma_f32_16x16x32_bf16 v[118:121], v[156:159], v[176:179], v[118:121]
	v_mfma_f32_16x16x32_bf16 v[114:117], v[168:171], v[176:179], v[114:117]
	v_mfma_f32_16x16x32_bf16 v[98:101], v[168:171], v[206:209], v[98:101]
	v_mfma_f32_16x16x32_bf16 v[102:105], v[156:159], v[206:209], v[102:105]
	v_mfma_f32_16x16x32_bf16 v[86:89], v[156:159], v[214:217], v[86:89]
	v_mfma_f32_16x16x32_bf16 v[82:85], v[168:171], v[214:217], v[82:85]
	v_mfma_f32_16x16x32_bf16 v[66:69], v[168:171], v[236:239], v[66:69]
	v_mfma_f32_16x16x32_bf16 v[70:73], v[156:159], v[236:239], v[70:73]
	v_mfma_f32_16x16x32_bf16 v[118:121], v[160:163], v[180:183], v[118:121]
	v_mfma_f32_16x16x32_bf16 v[114:117], v[172:175], v[180:183], v[114:117]
	v_mfma_f32_16x16x32_bf16 v[98:101], v[172:175], v[210:213], v[98:101]
	v_mfma_f32_16x16x32_bf16 v[102:105], v[160:163], v[210:213], v[102:105]
	v_mfma_f32_16x16x32_bf16 v[86:89], v[160:163], v[218:221], v[86:89]
	v_mfma_f32_16x16x32_bf16 v[82:85], v[172:175], v[218:221], v[82:85]
	v_mfma_f32_16x16x32_bf16 v[66:69], v[172:175], v[240:243], v[66:69]
	v_mfma_f32_16x16x32_bf16 v[70:73], v[160:163], v[240:243], v[70:73]
	s_barrier
; #define PG8_STAGE(bufoff, gbase, voff) do { _Pragma("unroll") for (int _i = 0; _i < 2; ++_i) \
;         __builtin_amdgcn_global_load_lds((const unsigned*)((const char*)(gbase) + (voff)[_i]), (PG8_LAS unsigned*)(lds + (bufoff) + ldsw + _i * 8192), 16, 0, 0); } while (0)
; #define PG8_LDA(dst, b, h) do { _Pragma("unroll") for (int m = 0; m < 4; ++m) _Pragma("unroll") for (int k = 0; k < 2; ++k) dst[m][k] = *(const PG8_LAS bf16x8*)(lds + PG8_SA(b, h) + aoff + m * 2048 + k * 1024); } while (0)
; #define PG8_LDB(dst, b, h) do { _Pragma("unroll") for (int n = 0; n < 2; ++n) _Pragma("unroll") for (int k = 0; k < 2; ++k) dst[n][k] = *(const PG8_LAS bf16x8*)(lds + PG8_SB(b, h) + boff + n * 2048 + k * 1024); } while (0)
; #define PG8_BAR __builtin_amdgcn_s_barrier()
; template <class Epi, class Sched, bool ALIGN_EPI = false, bool SP2 = false>
; __device__ __forceinline__ void gemm_phase(PG8_LAS unsigned char* lds, const Gemm g, const Sched& S, const Epi& E) {
;     ...
;             const bool last = (t == nt - 2);
;             const char* a1 = cA + (size_t)(t + 1) * kstep;
;             const char* a2 = last ? nA : cA + (size_t)(t + 2) * kstep; const char* b2 = last ? nB : cB + (size_t)(t + 2) * kstep;
;             const char* a3 = a2 + kstep; const char* b3 = b2 + kstep;
;             if (last && has_next) S.a_ready(nxt);
;             if constexpr (SP2) {
;             PG8_LDB(B0, 0, 0); PG8_LDB(B1, 0, 1); PG8_SCHED; PG8_LDA(At, 0, 0); PG8_STAGE(PG8_SA(1, 1), a1 + hstep, voffA);
;             PG8_WAIT_V(8); PG8_WAIT_L(0); PG8_BAR; PG8_MMA(0, 0, At, B0); PG8_MMA(0, 1, At, B1); PG8_BAR; PG8_SCHED;
;             PG8_LDA(At, 0, 1); PG8_STAGE(PG8_SB(0, 0), b2, voffB); PG8_STAGE(PG8_SB(0, 1), b2 + hstepB, voffB); PG8_STAGE(PG8_SA(0, 0), a2, voffA);
;             PG8_WAIT_V(8); PG8_WAIT_L(0); PG8_BAR; PG8_MMA(1, 0, At, B0); PG8_MMA(1, 1, At, B1); PG8_BAR; PG8_SCHED;
;             PG8_LDB(B0, 1, 0); PG8_LDB(B1, 1, 1); PG8_SCHED; PG8_LDA(At, 1, 0); PG8_STAGE(PG8_SA(0, 1), a2 + hstep, voffA);
;             PG8_WAIT_V(8); PG8_WAIT_L(0); PG8_BAR; PG8_MMA(0, 0, At, B0); PG8_MMA(0, 1, At, B1); PG8_BAR; PG8_SCHED;
;             PG8_LDA(At, 1, 1); PG8_STAGE(PG8_SB(1, 0), b3, voffB); PG8_STAGE(PG8_SB(1, 1), b3 + hstepB, voffB); PG8_STAGE(PG8_SA(1, 0), a3, voffA);
;             PG8_WAIT_V(8); PG8_WAIT_L(0); PG8_BAR; PG8_MMA(1, 0, At, B0); PG8_MMA(1, 1, At, B1); PG8_BAR; PG8_SCHED;
	s_add_i32 s10, s12, s67
	s_mov_b32 m0, s10
	ds_read_b128 v[176:179], v166 offset:49152
	ds_read_b128 v[180:183], v166 offset:50176
	ds_read_b128 v[206:209], v166 offset:51200
	ds_read_b128 v[210:213], v166 offset:52224
	ds_read_b128 v[214:217], v166 offset:53248
	ds_read_b128 v[218:221], v166 offset:54272
	ds_read_b128 v[236:239], v166 offset:55296
	ds_read_b128 v[240:243], v166 offset:56320
	s_add_u32 s100, s46, s60
	s_addc_u32 s101, s47, s61
	global_load_lds_dwordx4 v146, s[100:101]
	s_add_i32 m0, s10, 0x2000
	s_add_u32 s10, s46, 0x80080
	s_addc_u32 s11, s47, 0
	s_add_i32 s12, s13, s67
	global_load_lds_dwordx4 v142, s[100:101]
	s_mov_b32 m0, s12
	s_nop 0
	global_load_lds_dwordx4 v146, s[10:11]
	s_add_i32 m0, s12, 0x2000
	s_nop 0
	global_load_lds_dwordx4 v142, s[10:11]
	s_mov_b32 m0, s82
	s_add_u32 s100, vcc_lo, s60
	s_addc_u32 s101, vcc_hi, s61
	global_load_lds_dwordx4 v190, s[100:101]
	s_mov_b32 m0, s42
	s_nop 0
	global_load_lds_dwordx4 v144, s[100:101]
	s_waitcnt vmcnt(8)
	s_waitcnt lgkmcnt(0)
	s_barrier
	v_mfma_f32_16x16x32_bf16 v[62:65], v[130:133], v[176:179], v[62:65]
	v_mfma_f32_16x16x32_bf16 v[58:61], v[138:141], v[176:179], v[58:61]
	v_mfma_f32_16x16x32_bf16 v[42:45], v[138:141], v[206:209], v[42:45]
	v_mfma_f32_16x16x32_bf16 v[46:49], v[130:133], v[206:209], v[46:49]
	v_mfma_f32_16x16x32_bf16 v[30:33], v[130:133], v[214:217], v[30:33]
	v_mfma_f32_16x16x32_bf16 v[26:29], v[138:141], v[214:217], v[26:29]
	v_mfma_f32_16x16x32_bf16 v[10:13], v[138:141], v[236:239], v[10:13]
	v_mfma_f32_16x16x32_bf16 v[14:17], v[130:133], v[236:239], v[14:17]
	v_mfma_f32_16x16x32_bf16 v[62:65], v[134:137], v[180:183], v[62:65]
	v_mfma_f32_16x16x32_bf16 v[58:61], v[152:155], v[180:183], v[58:61]
	v_mfma_f32_16x16x32_bf16 v[42:45], v[152:155], v[210:213], v[42:45]
	v_mfma_f32_16x16x32_bf16 v[46:49], v[134:137], v[210:213], v[46:49]
	v_mfma_f32_16x16x32_bf16 v[30:33], v[134:137], v[218:221], v[30:33]
	v_mfma_f32_16x16x32_bf16 v[26:29], v[152:155], v[218:221], v[26:29]
	v_mfma_f32_16x16x32_bf16 v[10:13], v[152:155], v[240:243], v[10:13]
	v_mfma_f32_16x16x32_bf16 v[14:17], v[134:137], v[240:243], v[14:17]
	v_mfma_f32_16x16x32_bf16 v[54:57], v[156:159], v[176:179], v[54:57]
	v_mfma_f32_16x16x32_bf16 v[50:53], v[168:171], v[176:179], v[50:53]
	v_mfma_f32_16x16x32_bf16 v[34:37], v[168:171], v[206:209], v[34:37]
	v_mfma_f32_16x16x32_bf16 v[38:41], v[156:159], v[206:209], v[38:41]
	v_mfma_f32_16x16x32_bf16 v[22:25], v[156:159], v[214:217], v[22:25]
	v_mfma_f32_16x16x32_bf16 v[18:21], v[168:171], v[214:217], v[18:21]
	v_mfma_f32_16x16x32_bf16 v[2:5], v[168:171], v[236:239], v[2:5]
	v_mfma_f32_16x16x32_bf16 v[6:9], v[156:159], v[236:239], v[6:9]
	v_mfma_f32_16x16x32_bf16 v[54:57], v[160:163], v[180:183], v[54:57]
	v_mfma_f32_16x16x32_bf16 v[50:53], v[172:175], v[180:183], v[50:53]
	v_mfma_f32_16x16x32_bf16 v[34:37], v[172:175], v[210:213], v[34:37]
	v_mfma_f32_16x16x32_bf16 v[38:41], v[160:163], v[210:213], v[38:41]
	v_mfma_f32_16x16x32_bf16 v[22:25], v[160:163], v[218:221], v[22:25]
	v_mfma_f32_16x16x32_bf16 v[18:21], v[172:175], v[218:221], v[18:21]
	v_mfma_f32_16x16x32_bf16 v[2:5], v[172:175], v[240:243], v[2:5]
	v_mfma_f32_16x16x32_bf16 v[6:9], v[160:163], v[240:243], v[6:9]
	s_barrier
	s_add_i32 s9, s9, 2
	s_add_u32 s38, s38, 0x100
	s_addc_u32 s39, s39, 0
	s_add_u32 s7, s7, 0x100
	s_addc_u32 s8, s8, 0
	s_cmpk_gt_u32 s9, 0x7d
.LBB0_1071:
	s_add_u32 s10, s38, 0xffe00080
	s_addc_u32 s11, s39, -1
	s_add_i32 s12, 0, 0x10000
	s_cmpk_eq_i32 s9, 0x7c
	s_cselect_b32 vcc_hi, s97, s11
	s_cselect_b32 vcc_lo, s4, s10
	s_cselect_b32 s47, s5, s8
	s_cselect_b32 s46, s6, s7
	s_add_i32 s13, 0, 0x14000
	ds_read_b128 v[130:133], v186
	ds_read_b128 v[134:137], v186 offset:1024
	ds_read_b128 v[138:141], v186 offset:2048
	ds_read_b128 v[152:155], v186 offset:3072
	ds_read_b128 v[156:159], v187
	ds_read_b128 v[160:163], v187 offset:1024
	ds_read_b128 v[168:171], v187 offset:2048
	ds_read_b128 v[172:175], v187 offset:3072
	s_add_i32 m0, s74, 0xc000
	ds_read_b128 v[176:179], v166
	ds_read_b128 v[180:183], v166 offset:1024
	ds_read_b128 v[206:209], v166 offset:2048
	ds_read_b128 v[210:213], v166 offset:3072
	ds_read_b128 v[214:217], v166 offset:4096
	ds_read_b128 v[218:221], v166 offset:5120
	ds_read_b128 v[236:239], v166 offset:6144
	ds_read_b128 v[240:243], v166 offset:7168
	global_load_lds_dwordx4 v148, s[38:39]
	s_add_i32 m0, s74, 0xe000
	s_nop 0
	global_load_lds_dwordx4 v150, s[38:39]
	s_waitcnt vmcnt(8)
	s_waitcnt lgkmcnt(0)
	s_barrier
	v_mfma_f32_16x16x32_bf16 v[126:129], v[130:133], v[176:179], v[126:129]
	v_mfma_f32_16x16x32_bf16 v[122:125], v[138:141], v[176:179], v[122:125]
	v_mfma_f32_16x16x32_bf16 v[106:109], v[138:141], v[206:209], v[106:109]
	v_mfma_f32_16x16x32_bf16 v[110:113], v[130:133], v[206:209], v[110:113]
	v_mfma_f32_16x16x32_bf16 v[94:97], v[130:133], v[214:217], v[94:97]
	v_mfma_f32_16x16x32_bf16 v[90:93], v[138:141], v[214:217], v[90:93]
	v_mfma_f32_16x16x32_bf16 v[74:77], v[138:141], v[236:239], v[74:77]
	v_mfma_f32_16x16x32_bf16 v[78:81], v[130:133], v[236:239], v[78:81]
	v_mfma_f32_16x16x32_bf16 v[126:129], v[134:137], v[180:183], v[126:129]
	v_mfma_f32_16x16x32_bf16 v[122:125], v[152:155], v[180:183], v[122:125]
	v_mfma_f32_16x16x32_bf16 v[106:109], v[152:155], v[210:213], v[106:109]
	v_mfma_f32_16x16x32_bf16 v[110:113], v[134:137], v[210:213], v[110:113]
	v_mfma_f32_16x16x32_bf16 v[94:97], v[134:137], v[218:221], v[94:97]
	v_mfma_f32_16x16x32_bf16 v[90:93], v[152:155], v[218:221], v[90:93]
	v_mfma_f32_16x16x32_bf16 v[74:77], v[152:155], v[240:243], v[74:77]
	v_mfma_f32_16x16x32_bf16 v[78:81], v[134:137], v[240:243], v[78:81]
	v_mfma_f32_16x16x32_bf16 v[118:121], v[156:159], v[176:179], v[118:121]
	v_mfma_f32_16x16x32_bf16 v[114:117], v[168:171], v[176:179], v[114:117]
	v_mfma_f32_16x16x32_bf16 v[98:101], v[168:171], v[206:209], v[98:101]
	v_mfma_f32_16x16x32_bf16 v[102:105], v[156:159], v[206:209], v[102:105]
	v_mfma_f32_16x16x32_bf16 v[86:89], v[156:159], v[214:217], v[86:89]
	v_mfma_f32_16x16x32_bf16 v[82:85], v[168:171], v[214:217], v[82:85]
	v_mfma_f32_16x16x32_bf16 v[66:69], v[168:171], v[236:239], v[66:69]
	v_mfma_f32_16x16x32_bf16 v[70:73], v[156:159], v[236:239], v[70:73]
	v_mfma_f32_16x16x32_bf16 v[118:121], v[160:163], v[180:183], v[118:121]
	v_mfma_f32_16x16x32_bf16 v[114:117], v[172:175], v[180:183], v[114:117]
	v_mfma_f32_16x16x32_bf16 v[98:101], v[172:175], v[210:213], v[98:101]
	v_mfma_f32_16x16x32_bf16 v[102:105], v[160:163], v[210:213], v[102:105]
	v_mfma_f32_16x16x32_bf16 v[86:89], v[160:163], v[218:221], v[86:89]
	v_mfma_f32_16x16x32_bf16 v[82:85], v[172:175], v[218:221], v[82:85]
	v_mfma_f32_16x16x32_bf16 v[66:69], v[172:175], v[240:243], v[66:69]
	v_mfma_f32_16x16x32_bf16 v[70:73], v[160:163], v[240:243], v[70:73]
	s_barrier
; #define PG8_STAGE(bufoff, gbase, voff) do { _Pragma("unroll") for (int _i = 0; _i < 2; ++_i) \
;         __builtin_amdgcn_global_load_lds((const unsigned*)((const char*)(gbase) + (voff)[_i]), (PG8_LAS unsigned*)(lds + (bufoff) + ldsw + _i * 8192), 16, 0, 0); } while (0)
; #define PG8_LDA(dst, b, h) do { _Pragma("unroll") for (int m = 0; m < 4; ++m) _Pragma("unroll") for (int k = 0; k < 2; ++k) dst[m][k] = *(const PG8_LAS bf16x8*)(lds + PG8_SA(b, h) + aoff + m * 2048 + k * 1024); } while (0)
; #define PG8_LDB(dst, b, h) do { _Pragma("unroll") for (int n = 0; n < 2; ++n) _Pragma("unroll") for (int k = 0; k < 2; ++k) dst[n][k] = *(const PG8_LAS bf16x8*)(lds + PG8_SB(b, h) + boff + n * 2048 + k * 1024); } while (0)
; #define PG8_MMA(ai, bj, At, Bt) do { __builtin_amdgcn_s_setprio(1); _Pragma("unroll") for (int m = 0; m < 4; ++m) _Pragma("unroll") for (int n = 0; n < 2; ++n) _Pragma("unroll") for (int k = 0; k < 2; ++k) \
;         acc[ai][bj][m][n] = __builtin_amdgcn_mfma_f32_16x16x32_bf16(Bt[n][k], At[m][k], acc[ai][bj][m][n], 0, 0, 0); __builtin_amdgcn_s_setprio(0); } while (0)
; #define PG8_WAIT_V(n) asm volatile("s_waitcnt vmcnt(" #n ")" ::: "memory")
; #define PG8_WAIT_L(n) asm volatile("s_waitcnt lgkmcnt(" #n ")" ::: "memory")
; #define PG8_BAR __builtin_amdgcn_s_barrier()
; #define PG8_SCHED __builtin_amdgcn_sched_barrier(0)
; template <class Epi, class Sched, bool ALIGN_EPI = false, bool SP2 = false>
; __device__ __forceinline__ void gemm_phase(PG8_LAS unsigned char* lds, const Gemm g, const Sched& S, const Epi& E) {
;     ...
;             PG8_LDA(At, 0, 1); PG8_STAGE(PG8_SB(0, 0), b2, voffB); PG8_STAGE(PG8_SB(0, 1), b2 + hstepB, voffB); PG8_STAGE(PG8_SA(0, 0), a2, voffA);
;             PG8_WAIT_V(8); PG8_WAIT_L(0); PG8_BAR; PG8_MMA(1, 0, At, B0); PG8_MMA(1, 1, At, B1); PG8_BAR; PG8_SCHED;
;             PG8_LDB(B0, 1, 0); PG8_LDB(B1, 1, 1); PG8_SCHED; PG8_LDA(At, 1, 0); PG8_STAGE(PG8_SA(0, 1), a2 + hstep, voffA);
	s_add_i32 s10, s12, s67
	s_mov_b32 m0, s10
	ds_read_b128 v[176:179], v166 offset:16384
	ds_read_b128 v[180:183], v166 offset:17408
	ds_read_b128 v[206:209], v166 offset:18432
	ds_read_b128 v[210:213], v166 offset:19456
	ds_read_b128 v[214:217], v166 offset:20480
	ds_read_b128 v[218:221], v166 offset:21504
	ds_read_b128 v[236:239], v166 offset:22528
	ds_read_b128 v[240:243], v166 offset:23552
	global_load_lds_dwordx4 v146, s[46:47]
	s_add_i32 m0, s10, 0x2000
	s_add_u32 s10, s46, 0x80000
	s_addc_u32 s11, s47, 0
	s_add_i32 s12, s13, s67
	global_load_lds_dwordx4 v142, s[46:47]
	s_mov_b32 m0, s12
	s_nop 0
	global_load_lds_dwordx4 v146, s[10:11]
	s_add_i32 m0, s12, 0x2000
	s_nop 0
	global_load_lds_dwordx4 v142, s[10:11]
	s_mov_b32 m0, s74
	s_nop 0
	global_load_lds_dwordx4 v190, vcc
	s_mov_b32 m0, s75
	s_nop 0
	global_load_lds_dwordx4 v144, vcc
	s_waitcnt vmcnt(8)
	s_waitcnt lgkmcnt(0)
	s_barrier
	v_mfma_f32_16x16x32_bf16 v[62:65], v[130:133], v[176:179], v[62:65]
	v_mfma_f32_16x16x32_bf16 v[58:61], v[138:141], v[176:179], v[58:61]
	v_mfma_f32_16x16x32_bf16 v[42:45], v[138:141], v[206:209], v[42:45]
	v_mfma_f32_16x16x32_bf16 v[46:49], v[130:133], v[206:209], v[46:49]
	v_mfma_f32_16x16x32_bf16 v[30:33], v[130:133], v[214:217], v[30:33]
	v_mfma_f32_16x16x32_bf16 v[26:29], v[138:141], v[214:217], v[26:29]
	v_mfma_f32_16x16x32_bf16 v[10:13], v[138:141], v[236:239], v[10:13]
	v_mfma_f32_16x16x32_bf16 v[14:17], v[130:133], v[236:239], v[14:17]
	v_mfma_f32_16x16x32_bf16 v[62:65], v[134:137], v[180:183], v[62:65]
	v_mfma_f32_16x16x32_bf16 v[58:61], v[152:155], v[180:183], v[58:61]
	v_mfma_f32_16x16x32_bf16 v[42:45], v[152:155], v[210:213], v[42:45]
	v_mfma_f32_16x16x32_bf16 v[46:49], v[134:137], v[210:213], v[46:49]
	v_mfma_f32_16x16x32_bf16 v[30:33], v[134:137], v[218:221], v[30:33]
	v_mfma_f32_16x16x32_bf16 v[26:29], v[152:155], v[218:221], v[26:29]
	v_mfma_f32_16x16x32_bf16 v[10:13], v[152:155], v[240:243], v[10:13]
	v_mfma_f32_16x16x32_bf16 v[14:17], v[134:137], v[240:243], v[14:17]
	v_mfma_f32_16x16x32_bf16 v[54:57], v[156:159], v[176:179], v[54:57]
	v_mfma_f32_16x16x32_bf16 v[50:53], v[168:171], v[176:179], v[50:53]
	v_mfma_f32_16x16x32_bf16 v[34:37], v[168:171], v[206:209], v[34:37]
	v_mfma_f32_16x16x32_bf16 v[38:41], v[156:159], v[206:209], v[38:41]
	v_mfma_f32_16x16x32_bf16 v[22:25], v[156:159], v[214:217], v[22:25]
	v_mfma_f32_16x16x32_bf16 v[18:21], v[168:171], v[214:217], v[18:21]
	v_mfma_f32_16x16x32_bf16 v[2:5], v[168:171], v[236:239], v[2:5]
	v_mfma_f32_16x16x32_bf16 v[6:9], v[156:159], v[236:239], v[6:9]
	v_mfma_f32_16x16x32_bf16 v[54:57], v[160:163], v[180:183], v[54:57]
	v_mfma_f32_16x16x32_bf16 v[50:53], v[172:175], v[180:183], v[50:53]
	v_mfma_f32_16x16x32_bf16 v[34:37], v[172:175], v[210:213], v[34:37]
	v_mfma_f32_16x16x32_bf16 v[38:41], v[160:163], v[210:213], v[38:41]
	v_mfma_f32_16x16x32_bf16 v[22:25], v[160:163], v[218:221], v[22:25]
	v_mfma_f32_16x16x32_bf16 v[18:21], v[172:175], v[218:221], v[18:21]
	v_mfma_f32_16x16x32_bf16 v[2:5], v[172:175], v[240:243], v[2:5]
	v_mfma_f32_16x16x32_bf16 v[6:9], v[160:163], v[240:243], v[6:9]
	s_barrier
	s_add_i32 s12, 0, 0x18000
	s_add_i32 s13, 0, 0x1c000
	ds_read_b128 v[130:133], v198
	ds_read_b128 v[134:137], v198 offset:1024
	ds_read_b128 v[138:141], v198 offset:2048
	ds_read_b128 v[152:155], v198 offset:3072
	ds_read_b128 v[156:159], v199
	ds_read_b128 v[160:163], v199 offset:1024
	ds_read_b128 v[168:171], v199 offset:2048
	ds_read_b128 v[172:175], v199 offset:3072
	s_add_u32 s10, vcc_lo, 0x200000
	s_addc_u32 s11, vcc_hi, 0
	s_mov_b32 m0, s86
	ds_read_b128 v[176:179], v166 offset:32768
	ds_read_b128 v[180:183], v166 offset:33792
	ds_read_b128 v[206:209], v166 offset:34816
	ds_read_b128 v[210:213], v166 offset:35840
	ds_read_b128 v[214:217], v166 offset:36864
	ds_read_b128 v[218:221], v166 offset:37888
	ds_read_b128 v[236:239], v166 offset:38912
	ds_read_b128 v[240:243], v166 offset:39936
	global_load_lds_dwordx4 v190, s[10:11]
	s_mov_b32 m0, s87
	s_nop 0
	global_load_lds_dwordx4 v144, s[10:11]
	s_waitcnt vmcnt(8)
	s_waitcnt lgkmcnt(0)
	s_barrier
; #define PG8_STAGE(bufoff, gbase, voff) do { _Pragma("unroll") for (int _i = 0; _i < 2; ++_i) \
;         __builtin_amdgcn_global_load_lds((const unsigned*)((const char*)(gbase) + (voff)[_i]), (PG8_LAS unsigned*)(lds + (bufoff) + ldsw + _i * 8192), 16, 0, 0); } while (0)
; #define PG8_LDA(dst, b, h) do { _Pragma("unroll") for (int m = 0; m < 4; ++m) _Pragma("unroll") for (int k = 0; k < 2; ++k) dst[m][k] = *(const PG8_LAS bf16x8*)(lds + PG8_SA(b, h) + aoff + m * 2048 + k * 1024); } while (0)
; #define PG8_MMA(ai, bj, At, Bt) do { __builtin_amdgcn_s_setprio(1); _Pragma("unroll") for (int m = 0; m < 4; ++m) _Pragma("unroll") for (int n = 0; n < 2; ++n) _Pragma("unroll") for (int k = 0; k < 2; ++k) \
;         acc[ai][bj][m][n] = __builtin_amdgcn_mfma_f32_16x16x32_bf16(Bt[n][k], At[m][k], acc[ai][bj][m][n], 0, 0, 0); __builtin_amdgcn_s_setprio(0); } while (0)
; #define PG8_WAIT_V(n) asm volatile("s_waitcnt vmcnt(" #n ")" ::: "memory")
; #define PG8_WAIT_L(n) asm volatile("s_waitcnt lgkmcnt(" #n ")" ::: "memory")
; #define PG8_BAR __builtin_amdgcn_s_barrier()
; #define PG8_SCHED __builtin_amdgcn_sched_barrier(0)
; template <class Epi, class Sched, bool ALIGN_EPI = false, bool SP2 = false>
; __device__ __forceinline__ void gemm_phase(PG8_LAS unsigned char* lds, const Gemm g, const Sched& S, const Epi& E) {
;     ...
;             PG8_WAIT_V(8); PG8_WAIT_L(0); PG8_BAR; PG8_MMA(0, 0, At, B0); PG8_MMA(0, 1, At, B1); PG8_BAR; PG8_SCHED;
;             PG8_LDA(At, 1, 1); PG8_STAGE(PG8_SB(1, 0), b3, voffB); PG8_STAGE(PG8_SB(1, 1), b3 + hstepB, voffB); PG8_STAGE(PG8_SA(1, 0), a3, voffA);
;             PG8_WAIT_V(8); PG8_WAIT_L(0); PG8_BAR; PG8_MMA(1, 0, At, B0); PG8_MMA(1, 1, At, B1); PG8_BAR; PG8_SCHED;
;     ...
;         if constexpr (ALIGN_EPI) { if (wr == 0) PG8_BAR; }
	v_mfma_f32_16x16x32_bf16 v[126:129], v[130:133], v[176:179], v[126:129]
	v_mfma_f32_16x16x32_bf16 v[122:125], v[138:141], v[176:179], v[122:125]
	v_mfma_f32_16x16x32_bf16 v[106:109], v[138:141], v[206:209], v[106:109]
	v_mfma_f32_16x16x32_bf16 v[110:113], v[130:133], v[206:209], v[110:113]
	v_mfma_f32_16x16x32_bf16 v[94:97], v[130:133], v[214:217], v[94:97]
	v_mfma_f32_16x16x32_bf16 v[90:93], v[138:141], v[214:217], v[90:93]
	v_mfma_f32_16x16x32_bf16 v[74:77], v[138:141], v[236:239], v[74:77]
	v_mfma_f32_16x16x32_bf16 v[78:81], v[130:133], v[236:239], v[78:81]
	v_mfma_f32_16x16x32_bf16 v[126:129], v[134:137], v[180:183], v[126:129]
	v_mfma_f32_16x16x32_bf16 v[122:125], v[152:155], v[180:183], v[122:125]
	v_mfma_f32_16x16x32_bf16 v[106:109], v[152:155], v[210:213], v[106:109]
	v_mfma_f32_16x16x32_bf16 v[110:113], v[134:137], v[210:213], v[110:113]
	v_mfma_f32_16x16x32_bf16 v[94:97], v[134:137], v[218:221], v[94:97]
	v_mfma_f32_16x16x32_bf16 v[90:93], v[152:155], v[218:221], v[90:93]
	v_mfma_f32_16x16x32_bf16 v[74:77], v[152:155], v[240:243], v[74:77]
	v_mfma_f32_16x16x32_bf16 v[78:81], v[134:137], v[240:243], v[78:81]
	v_mfma_f32_16x16x32_bf16 v[118:121], v[156:159], v[176:179], v[118:121]
	v_mfma_f32_16x16x32_bf16 v[114:117], v[168:171], v[176:179], v[114:117]
	v_mfma_f32_16x16x32_bf16 v[98:101], v[168:171], v[206:209], v[98:101]
	v_mfma_f32_16x16x32_bf16 v[102:105], v[156:159], v[206:209], v[102:105]
	v_mfma_f32_16x16x32_bf16 v[86:89], v[156:159], v[214:217], v[86:89]
	v_mfma_f32_16x16x32_bf16 v[82:85], v[168:171], v[214:217], v[82:85]
	v_mfma_f32_16x16x32_bf16 v[66:69], v[168:171], v[236:239], v[66:69]
	v_mfma_f32_16x16x32_bf16 v[70:73], v[156:159], v[236:239], v[70:73]
	v_mfma_f32_16x16x32_bf16 v[118:121], v[160:163], v[180:183], v[118:121]
	v_mfma_f32_16x16x32_bf16 v[114:117], v[172:175], v[180:183], v[114:117]
	v_mfma_f32_16x16x32_bf16 v[98:101], v[172:175], v[210:213], v[98:101]
	v_mfma_f32_16x16x32_bf16 v[102:105], v[160:163], v[210:213], v[102:105]
	v_mfma_f32_16x16x32_bf16 v[86:89], v[160:163], v[218:221], v[86:89]
	v_mfma_f32_16x16x32_bf16 v[82:85], v[172:175], v[218:221], v[82:85]
	v_mfma_f32_16x16x32_bf16 v[66:69], v[172:175], v[240:243], v[66:69]
	v_mfma_f32_16x16x32_bf16 v[70:73], v[160:163], v[240:243], v[70:73]
	s_barrier
	s_add_i32 s10, s12, s67
	s_mov_b32 m0, s10
	ds_read_b128 v[176:179], v166 offset:49152
	ds_read_b128 v[180:183], v166 offset:50176
	ds_read_b128 v[206:209], v166 offset:51200
	ds_read_b128 v[210:213], v166 offset:52224
	ds_read_b128 v[214:217], v166 offset:53248
	ds_read_b128 v[218:221], v166 offset:54272
	ds_read_b128 v[236:239], v166 offset:55296
	ds_read_b128 v[240:243], v166 offset:56320
	s_add_u32 s100, s46, s60
	s_addc_u32 s101, s47, s61
	global_load_lds_dwordx4 v146, s[100:101]
	s_add_i32 m0, s10, 0x2000
	s_add_u32 s10, s46, 0x80080
	s_addc_u32 s11, s47, 0
	s_add_i32 s12, s13, s67
	global_load_lds_dwordx4 v142, s[100:101]
	s_mov_b32 m0, s12
	s_nop 0
	global_load_lds_dwordx4 v146, s[10:11]
	s_add_i32 m0, s12, 0x2000
	s_nop 0
	global_load_lds_dwordx4 v142, s[10:11]
	s_mov_b32 m0, s82
	s_add_u32 s100, vcc_lo, s60
	s_addc_u32 s101, vcc_hi, s61
	global_load_lds_dwordx4 v190, s[100:101]
	s_mov_b32 m0, s42
	s_nop 0
	global_load_lds_dwordx4 v144, s[100:101]
	s_waitcnt vmcnt(8)
	s_waitcnt lgkmcnt(0)
	s_barrier
	v_mfma_f32_16x16x32_bf16 v[62:65], v[130:133], v[176:179], v[62:65]
	v_mfma_f32_16x16x32_bf16 v[58:61], v[138:141], v[176:179], v[58:61]
	v_mfma_f32_16x16x32_bf16 v[42:45], v[138:141], v[206:209], v[42:45]
	v_mfma_f32_16x16x32_bf16 v[46:49], v[130:133], v[206:209], v[46:49]
	v_mfma_f32_16x16x32_bf16 v[30:33], v[130:133], v[214:217], v[30:33]
	v_mfma_f32_16x16x32_bf16 v[26:29], v[138:141], v[214:217], v[26:29]
	v_mfma_f32_16x16x32_bf16 v[10:13], v[138:141], v[236:239], v[10:13]
	v_mfma_f32_16x16x32_bf16 v[14:17], v[130:133], v[236:239], v[14:17]
	v_mfma_f32_16x16x32_bf16 v[62:65], v[134:137], v[180:183], v[62:65]
	v_mfma_f32_16x16x32_bf16 v[58:61], v[152:155], v[180:183], v[58:61]
	v_mfma_f32_16x16x32_bf16 v[42:45], v[152:155], v[210:213], v[42:45]
	v_mfma_f32_16x16x32_bf16 v[46:49], v[134:137], v[210:213], v[46:49]
	v_mfma_f32_16x16x32_bf16 v[30:33], v[134:137], v[218:221], v[30:33]
	v_mfma_f32_16x16x32_bf16 v[26:29], v[152:155], v[218:221], v[26:29]
	v_mfma_f32_16x16x32_bf16 v[10:13], v[152:155], v[240:243], v[10:13]
	v_mfma_f32_16x16x32_bf16 v[14:17], v[134:137], v[240:243], v[14:17]
	v_mfma_f32_16x16x32_bf16 v[54:57], v[156:159], v[176:179], v[54:57]
	v_mfma_f32_16x16x32_bf16 v[50:53], v[168:171], v[176:179], v[50:53]
	v_mfma_f32_16x16x32_bf16 v[34:37], v[168:171], v[206:209], v[34:37]
	v_mfma_f32_16x16x32_bf16 v[38:41], v[156:159], v[206:209], v[38:41]
	v_mfma_f32_16x16x32_bf16 v[22:25], v[156:159], v[214:217], v[22:25]
	v_mfma_f32_16x16x32_bf16 v[18:21], v[168:171], v[214:217], v[18:21]
	v_mfma_f32_16x16x32_bf16 v[2:5], v[168:171], v[236:239], v[2:5]
	v_mfma_f32_16x16x32_bf16 v[6:9], v[156:159], v[236:239], v[6:9]
	v_mfma_f32_16x16x32_bf16 v[54:57], v[160:163], v[180:183], v[54:57]
	v_mfma_f32_16x16x32_bf16 v[50:53], v[172:175], v[180:183], v[50:53]
	v_mfma_f32_16x16x32_bf16 v[34:37], v[172:175], v[210:213], v[34:37]
	v_mfma_f32_16x16x32_bf16 v[38:41], v[160:163], v[210:213], v[38:41]
	v_mfma_f32_16x16x32_bf16 v[22:25], v[160:163], v[218:221], v[22:25]
	v_mfma_f32_16x16x32_bf16 v[18:21], v[172:175], v[218:221], v[18:21]
	v_mfma_f32_16x16x32_bf16 v[2:5], v[172:175], v[240:243], v[2:5]
	v_mfma_f32_16x16x32_bf16 v[6:9], v[160:163], v[240:243], v[6:9]
	s_barrier
	s_add_i32 s9, s9, 2
	s_add_u32 s38, s38, 0x100
	s_addc_u32 s39, s39, 0
	s_add_u32 s7, s7, 0x100
	s_addc_u32 s8, s8, 0
	s_cmpk_gt_u32 s9, 0x7d
	s_cbranch_scc0 .LBB0_1071
	s_and_b64 vcc, exec, s[72:73]
	s_cbranch_vccz .LBB0_1074
	s_barrier

; #define PG8_STAGE(bufoff, gbase, voff) do { _Pragma("unroll") for (int _i = 0; _i < 2; ++_i) \
;         __builtin_amdgcn_global_load_lds((const unsigned*)((const char*)(gbase) + (voff)[_i]), (PG8_LAS unsigned*)(lds + (bufoff) + ldsw + _i * 8192), 16, 0, 0); } while (0)
; #define PG8_LDA(dst, b, h) do { _Pragma("unroll") for (int m = 0; m < 4; ++m) _Pragma("unroll") for (int k = 0; k < 2; ++k) dst[m][k] = *(const PG8_LAS bf16x8*)(lds + PG8_SA(b, h) + aoff + m * 2048 + k * 1024); } while (0)
; #define PG8_LDB(dst, b, h) do { _Pragma("unroll") for (int n = 0; n < 2; ++n) _Pragma("unroll") for (int k = 0; k < 2; ++k) dst[n][k] = *(const PG8_LAS bf16x8*)(lds + PG8_SB(b, h) + boff + n * 2048 + k * 1024); } while (0)
; #define PG8_MMA(ai, bj, At, Bt) do { __builtin_amdgcn_s_setprio(1); _Pragma("unroll") for (int m = 0; m < 4; ++m) _Pragma("unroll") for (int n = 0; n < 2; ++n) _Pragma("unroll") for (int k = 0; k < 2; ++k) \
;         acc[ai][bj][m][n] = __builtin_amdgcn_mfma_f32_16x16x32_bf16(Bt[n][k], At[m][k], acc[ai][bj][m][n], 0, 0, 0); __builtin_amdgcn_s_setprio(0); } while (0)
; #define PG8_BAR __builtin_amdgcn_s_barrier()
; template <class Epi, class Sched, bool ALIGN_EPI = false, bool SP2 = false>
; __device__ __forceinline__ void gemm_phase(PG8_LAS unsigned char* lds, const Gemm g, const Sched& S, const Epi& E) {
;     ...
;         const bool has_next = S.next(ui + 1, nxt);
;         const char* nA = has_next ? (const char*)g.A + (size_t)nxt.pm * tstep : cA; const char* nB = has_next ? (const char*)g.Bt + (size_t)nxt.pn * tstep : cB;
;         for (int t = 0; t < nt; t += 2) {
;             const bool last = (t == nt - 2);
;             const char* a1 = cA + (size_t)(t + 1) * kstep;
;             const char* a2 = last ? nA : cA + (size_t)(t + 2) * kstep; const char* b2 = last ? nB : cB + (size_t)(t + 2) * kstep;
;             const char* a3 = a2 + kstep; const char* b3 = b2 + kstep;
;             if (last && has_next) S.a_ready(nxt);
;             if constexpr (SP2) {
;             PG8_LDB(B0, 0, 0); PG8_LDB(B1, 0, 1); PG8_SCHED; PG8_LDA(At, 0, 0); PG8_STAGE(PG8_SA(1, 1), a1 + hstep, voffA);
;             PG8_WAIT_V(8); PG8_WAIT_L(0); PG8_BAR; PG8_MMA(0, 0, At, B0); PG8_MMA(0, 1, At, B1); PG8_BAR; PG8_SCHED;
;             PG8_LDA(At, 0, 1); PG8_STAGE(PG8_SB(0, 0), b2, voffB); PG8_STAGE(PG8_SB(0, 1), b2 + hstepB, voffB); PG8_STAGE(PG8_SA(0, 0), a2, voffA);
.LBB0_1232:
	s_add_u32 s36, s80, 0x100
	s_addc_u32 s37, s81, 0
	s_ashr_i32 s73, s72, 31
	s_lshl_b64 s[4:5], s[72:73], 20
	s_add_u32 s78, s0, s4
	s_addc_u32 s79, s1, s5
	s_and_b64 s[4:5], s[46:47], exec
	s_cselect_b32 s4, s79, s69
	s_cselect_b32 s5, s78, s68
	s_ashr_i32 s71, s70, 31
	s_lshl_b64 s[6:7], s[70:71], 20
	s_add_u32 s76, s34, s6
	s_addc_u32 s77, s35, s7
	s_and_b64 s[6:7], s[46:47], exec
	s_cselect_b32 s6, s77, s81
	s_cselect_b32 s7, s76, s80
	s_add_u32 s8, s68, 0x80080
	s_addc_u32 s9, s69, 0
	v_lshl_add_u64 v[140:141], s[8:9], 0, v[136:137]
	v_lshl_add_u64 v[142:143], s[8:9], 0, v[138:139]
	s_mov_b32 s8, -2
	s_mov_b64 s[80:81], 0
	v_add_u32_e32 v186, 0x10000, v145
	v_add_u32_e32 v187, 0x14000, v145
	v_add_u32_e32 v198, 0x18000, v145
	v_add_u32_e32 v199, 0x1c000, v145
	s_add_u32 s9, s68, s80
	s_addc_u32 s10, s69, s81
	s_add_u32 s9, s9, 0x100
	s_addc_u32 s10, s10, 0
	s_add_u32 s100, s9, 0x7ff80
	s_addc_u32 s101, s10, 0
	s_add_u32 s11, s36, s80
	s_addc_u32 s12, s37, s81
	s_add_i32 s13, 0, 0x10000
	s_cmpk_eq_i32 s80, 0xf00
	s_cselect_b32 s93, s4, s10
	s_cselect_b32 s92, s5, s9
	s_cselect_b32 s85, s6, s12
	s_cselect_b32 s84, s7, s11
	s_add_i32 s9, 0, 0x14000
	ds_read_b128 v[152:155], v186
	ds_read_b128 v[156:159], v186 offset:1024
	ds_read_b128 v[160:163], v186 offset:2048
	ds_read_b128 v[164:167], v186 offset:3072
	ds_read_b128 v[168:171], v187
	ds_read_b128 v[172:175], v187 offset:1024
	ds_read_b128 v[176:179], v187 offset:2048
	ds_read_b128 v[180:183], v187 offset:3072
	s_add_i32 m0, s51, 0xc000
	ds_read_b128 v[206:209], v151
	ds_read_b128 v[210:213], v151 offset:1024
	ds_read_b128 v[214:217], v151 offset:2048
	ds_read_b128 v[218:221], v151 offset:3072
	ds_read_b128 v[236:239], v151 offset:4096
	ds_read_b128 v[240:243], v151 offset:5120
	ds_read_b128 v[244:247], v151 offset:6144
	ds_read_b128 v[194:197], v151 offset:7168
	global_load_lds_dwordx4 v136, s[100:101]
	s_add_i32 m0, s51, 0xe000
	s_nop 0
	global_load_lds_dwordx4 v138, s[100:101]
	s_waitcnt vmcnt(8)
	s_waitcnt lgkmcnt(0)
	s_barrier
	v_mfma_f32_16x16x32_bf16 v[126:129], v[152:155], v[206:209], 0
	v_mfma_f32_16x16x32_bf16 v[122:125], v[160:163], v[206:209], 0
	v_mfma_f32_16x16x32_bf16 v[114:117], v[160:163], v[214:217], 0
	v_mfma_f32_16x16x32_bf16 v[118:121], v[152:155], v[214:217], 0
	v_mfma_f32_16x16x32_bf16 v[110:113], v[152:155], v[236:239], 0
	v_mfma_f32_16x16x32_bf16 v[106:109], v[160:163], v[236:239], 0
	v_mfma_f32_16x16x32_bf16 v[98:101], v[160:163], v[244:247], 0
	v_mfma_f32_16x16x32_bf16 v[102:105], v[152:155], v[244:247], 0
	v_mfma_f32_16x16x32_bf16 v[126:129], v[156:159], v[210:213], v[126:129]
	v_mfma_f32_16x16x32_bf16 v[122:125], v[164:167], v[210:213], v[122:125]
	v_mfma_f32_16x16x32_bf16 v[114:117], v[164:167], v[218:221], v[114:117]
	v_mfma_f32_16x16x32_bf16 v[118:121], v[156:159], v[218:221], v[118:121]
	v_mfma_f32_16x16x32_bf16 v[110:113], v[156:159], v[240:243], v[110:113]
	v_mfma_f32_16x16x32_bf16 v[106:109], v[164:167], v[240:243], v[106:109]
	v_mfma_f32_16x16x32_bf16 v[98:101], v[164:167], v[194:197], v[98:101]
	v_mfma_f32_16x16x32_bf16 v[102:105], v[156:159], v[194:197], v[102:105]
	v_mfma_f32_16x16x32_bf16 v[94:97], v[168:171], v[206:209], 0
	v_mfma_f32_16x16x32_bf16 v[90:93], v[176:179], v[206:209], 0
	v_mfma_f32_16x16x32_bf16 v[82:85], v[176:179], v[214:217], 0
	v_mfma_f32_16x16x32_bf16 v[86:89], v[168:171], v[214:217], 0
	v_mfma_f32_16x16x32_bf16 v[78:81], v[168:171], v[236:239], 0
	v_mfma_f32_16x16x32_bf16 v[74:77], v[176:179], v[236:239], 0
	v_mfma_f32_16x16x32_bf16 v[66:69], v[176:179], v[244:247], 0
	v_mfma_f32_16x16x32_bf16 v[70:73], v[168:171], v[244:247], 0
	v_mfma_f32_16x16x32_bf16 v[94:97], v[172:175], v[210:213], v[94:97]
	v_mfma_f32_16x16x32_bf16 v[90:93], v[180:183], v[210:213], v[90:93]
	v_mfma_f32_16x16x32_bf16 v[82:85], v[180:183], v[218:221], v[82:85]
	v_mfma_f32_16x16x32_bf16 v[86:89], v[172:175], v[218:221], v[86:89]
	v_mfma_f32_16x16x32_bf16 v[78:81], v[172:175], v[240:243], v[78:81]
	v_mfma_f32_16x16x32_bf16 v[74:77], v[180:183], v[240:243], v[74:77]
	v_mfma_f32_16x16x32_bf16 v[66:69], v[180:183], v[194:197], v[66:69]
	v_mfma_f32_16x16x32_bf16 v[70:73], v[172:175], v[194:197], v[70:73]
	s_barrier
	s_add_i32 s10, s13, s42
	s_mov_b32 m0, s10
	ds_read_b128 v[194:197], v151 offset:16384
	ds_read_b128 v[206:209], v151 offset:17408
	ds_read_b128 v[210:213], v151 offset:18432
	ds_read_b128 v[214:217], v151 offset:19456
	ds_read_b128 v[218:221], v151 offset:20480
	ds_read_b128 v[236:239], v151 offset:21504
	ds_read_b128 v[240:243], v151 offset:22528
	ds_read_b128 v[244:247], v151 offset:23552
	global_load_lds_dwordx4 v130, s[84:85]
	s_add_i32 m0, s10, 0x2000
	s_add_u32 s10, s84, 0x20000
	s_addc_u32 s11, s85, 0
	s_add_i32 s9, s9, s42
	global_load_lds_dwordx4 v134, s[84:85]
	s_mov_b32 m0, s9
	s_nop 0
	global_load_lds_dwordx4 v130, s[10:11]
	s_add_i32 m0, s9, 0x2000
	s_nop 0
	global_load_lds_dwordx4 v134, s[10:11]
	s_mov_b32 m0, s51
	s_nop 0
	global_load_lds_dwordx4 v190, s[92:93]
	s_mov_b32 m0, s67
	s_nop 0
	global_load_lds_dwordx4 v132, s[92:93]
	s_waitcnt vmcnt(8)
	s_waitcnt lgkmcnt(0)
	s_barrier
; #define PG8_STAGE(bufoff, gbase, voff) do { _Pragma("unroll") for (int _i = 0; _i < 2; ++_i) \
;         __builtin_amdgcn_global_load_lds((const unsigned*)((const char*)(gbase) + (voff)[_i]), (PG8_LAS unsigned*)(lds + (bufoff) + ldsw + _i * 8192), 16, 0, 0); } while (0)
; #define PG8_LDA(dst, b, h) do { _Pragma("unroll") for (int m = 0; m < 4; ++m) _Pragma("unroll") for (int k = 0; k < 2; ++k) dst[m][k] = *(const PG8_LAS bf16x8*)(lds + PG8_SA(b, h) + aoff + m * 2048 + k * 1024); } while (0)
; #define PG8_LDB(dst, b, h) do { _Pragma("unroll") for (int n = 0; n < 2; ++n) _Pragma("unroll") for (int k = 0; k < 2; ++k) dst[n][k] = *(const PG8_LAS bf16x8*)(lds + PG8_SB(b, h) + boff + n * 2048 + k * 1024); } while (0)
; #define PG8_MMA(ai, bj, At, Bt) do { __builtin_amdgcn_s_setprio(1); _Pragma("unroll") for (int m = 0; m < 4; ++m) _Pragma("unroll") for (int n = 0; n < 2; ++n) _Pragma("unroll") for (int k = 0; k < 2; ++k) \
;         acc[ai][bj][m][n] = __builtin_amdgcn_mfma_f32_16x16x32_bf16(Bt[n][k], At[m][k], acc[ai][bj][m][n], 0, 0, 0); __builtin_amdgcn_s_setprio(0); } while (0)
; #define PG8_WAIT_V(n) asm volatile("s_waitcnt vmcnt(" #n ")" ::: "memory")
; #define PG8_WAIT_L(n) asm volatile("s_waitcnt lgkmcnt(" #n ")" ::: "memory")
; #define PG8_BAR __builtin_amdgcn_s_barrier()
; #define PG8_SCHED __builtin_amdgcn_sched_barrier(0)
; template <class Epi, class Sched, bool ALIGN_EPI = false, bool SP2 = false>
; __device__ __forceinline__ void gemm_phase(PG8_LAS unsigned char* lds, const Gemm g, const Sched& S, const Epi& E) {
;     ...
;             PG8_WAIT_V(8); PG8_WAIT_L(0); PG8_BAR; PG8_MMA(1, 0, At, B0); PG8_MMA(1, 1, At, B1); PG8_BAR; PG8_SCHED;
;             PG8_LDB(B0, 1, 0); PG8_LDB(B1, 1, 1); PG8_SCHED; PG8_LDA(At, 1, 0); PG8_STAGE(PG8_SA(0, 1), a2 + hstep, voffA);
;             PG8_WAIT_V(8); PG8_WAIT_L(0); PG8_BAR; PG8_MMA(0, 0, At, B0); PG8_MMA(0, 1, At, B1); PG8_BAR; PG8_SCHED;
	v_mfma_f32_16x16x32_bf16 v[62:65], v[152:155], v[194:197], 0
	v_mfma_f32_16x16x32_bf16 v[58:61], v[160:163], v[194:197], 0
	v_mfma_f32_16x16x32_bf16 v[50:53], v[160:163], v[210:213], 0
	v_mfma_f32_16x16x32_bf16 v[54:57], v[152:155], v[210:213], 0
	v_mfma_f32_16x16x32_bf16 v[46:49], v[152:155], v[218:221], 0
	v_mfma_f32_16x16x32_bf16 v[42:45], v[160:163], v[218:221], 0
	v_mfma_f32_16x16x32_bf16 v[34:37], v[160:163], v[240:243], 0
	v_mfma_f32_16x16x32_bf16 v[38:41], v[152:155], v[240:243], 0
	v_mfma_f32_16x16x32_bf16 v[62:65], v[156:159], v[206:209], v[62:65]
	v_mfma_f32_16x16x32_bf16 v[58:61], v[164:167], v[206:209], v[58:61]
	v_mfma_f32_16x16x32_bf16 v[50:53], v[164:167], v[214:217], v[50:53]
	v_mfma_f32_16x16x32_bf16 v[54:57], v[156:159], v[214:217], v[54:57]
	v_mfma_f32_16x16x32_bf16 v[46:49], v[156:159], v[236:239], v[46:49]
	v_mfma_f32_16x16x32_bf16 v[42:45], v[164:167], v[236:239], v[42:45]
	v_mfma_f32_16x16x32_bf16 v[34:37], v[164:167], v[244:247], v[34:37]
	v_mfma_f32_16x16x32_bf16 v[38:41], v[156:159], v[244:247], v[38:41]
	v_mfma_f32_16x16x32_bf16 v[30:33], v[168:171], v[194:197], 0
	v_mfma_f32_16x16x32_bf16 v[26:29], v[176:179], v[194:197], 0
	v_mfma_f32_16x16x32_bf16 v[18:21], v[176:179], v[210:213], 0
	v_mfma_f32_16x16x32_bf16 v[22:25], v[168:171], v[210:213], 0
	v_mfma_f32_16x16x32_bf16 v[14:17], v[168:171], v[218:221], 0
	v_mfma_f32_16x16x32_bf16 v[10:13], v[176:179], v[218:221], 0
	v_mfma_f32_16x16x32_bf16 v[2:5], v[176:179], v[240:243], 0
	v_mfma_f32_16x16x32_bf16 v[6:9], v[168:171], v[240:243], 0
	v_mfma_f32_16x16x32_bf16 v[30:33], v[172:175], v[206:209], v[30:33]
	v_mfma_f32_16x16x32_bf16 v[26:29], v[180:183], v[206:209], v[26:29]
	v_mfma_f32_16x16x32_bf16 v[18:21], v[180:183], v[214:217], v[18:21]
	v_mfma_f32_16x16x32_bf16 v[22:25], v[172:175], v[214:217], v[22:25]
	v_mfma_f32_16x16x32_bf16 v[14:17], v[172:175], v[236:239], v[14:17]
	v_mfma_f32_16x16x32_bf16 v[10:13], v[180:183], v[236:239], v[10:13]
	v_mfma_f32_16x16x32_bf16 v[2:5], v[180:183], v[244:247], v[2:5]
	v_mfma_f32_16x16x32_bf16 v[6:9], v[172:175], v[244:247], v[6:9]
	s_barrier
	s_add_i32 s9, 0, 0x18000
	s_add_i32 s12, 0, 0x1c000
	ds_read_b128 v[152:155], v198
	ds_read_b128 v[156:159], v198 offset:1024
	ds_read_b128 v[160:163], v198 offset:2048
	ds_read_b128 v[164:167], v198 offset:3072
	ds_read_b128 v[168:171], v199
	ds_read_b128 v[172:175], v199 offset:1024
	ds_read_b128 v[176:179], v199 offset:2048
	ds_read_b128 v[180:183], v199 offset:3072
	s_add_u32 s10, s92, 0x80000
	s_addc_u32 s11, s93, 0
	s_mov_b32 m0, s74
	ds_read_b128 v[194:197], v151 offset:32768
	ds_read_b128 v[206:209], v151 offset:33792
	ds_read_b128 v[210:213], v151 offset:34816
	ds_read_b128 v[214:217], v151 offset:35840
	ds_read_b128 v[218:221], v151 offset:36864
	ds_read_b128 v[236:239], v151 offset:37888
	ds_read_b128 v[240:243], v151 offset:38912
	ds_read_b128 v[244:247], v151 offset:39936
	global_load_lds_dwordx4 v190, s[10:11]
	s_mov_b32 m0, s75
	s_nop 0
	global_load_lds_dwordx4 v132, s[10:11]
	s_waitcnt vmcnt(8)
	s_waitcnt lgkmcnt(0)
	s_barrier
	v_mfma_f32_16x16x32_bf16 v[126:129], v[152:155], v[194:197], v[126:129]
	v_mfma_f32_16x16x32_bf16 v[122:125], v[160:163], v[194:197], v[122:125]
	v_mfma_f32_16x16x32_bf16 v[114:117], v[160:163], v[210:213], v[114:117]
	v_mfma_f32_16x16x32_bf16 v[118:121], v[152:155], v[210:213], v[118:121]
	v_mfma_f32_16x16x32_bf16 v[110:113], v[152:155], v[218:221], v[110:113]
	v_mfma_f32_16x16x32_bf16 v[106:109], v[160:163], v[218:221], v[106:109]
	v_mfma_f32_16x16x32_bf16 v[98:101], v[160:163], v[240:243], v[98:101]
	v_mfma_f32_16x16x32_bf16 v[102:105], v[152:155], v[240:243], v[102:105]
	v_mfma_f32_16x16x32_bf16 v[126:129], v[156:159], v[206:209], v[126:129]
	v_mfma_f32_16x16x32_bf16 v[122:125], v[164:167], v[206:209], v[122:125]
	v_mfma_f32_16x16x32_bf16 v[114:117], v[164:167], v[214:217], v[114:117]
	v_mfma_f32_16x16x32_bf16 v[118:121], v[156:159], v[214:217], v[118:121]
	v_mfma_f32_16x16x32_bf16 v[110:113], v[156:159], v[236:239], v[110:113]
	v_mfma_f32_16x16x32_bf16 v[106:109], v[164:167], v[236:239], v[106:109]
	v_mfma_f32_16x16x32_bf16 v[98:101], v[164:167], v[244:247], v[98:101]
	v_mfma_f32_16x16x32_bf16 v[102:105], v[156:159], v[244:247], v[102:105]
	v_mfma_f32_16x16x32_bf16 v[94:97], v[168:171], v[194:197], v[94:97]
	v_mfma_f32_16x16x32_bf16 v[90:93], v[176:179], v[194:197], v[90:93]
	v_mfma_f32_16x16x32_bf16 v[82:85], v[176:179], v[210:213], v[82:85]
	v_mfma_f32_16x16x32_bf16 v[86:89], v[168:171], v[210:213], v[86:89]
	v_mfma_f32_16x16x32_bf16 v[78:81], v[168:171], v[218:221], v[78:81]
	v_mfma_f32_16x16x32_bf16 v[74:77], v[176:179], v[218:221], v[74:77]
	v_mfma_f32_16x16x32_bf16 v[66:69], v[176:179], v[240:243], v[66:69]
	v_mfma_f32_16x16x32_bf16 v[70:73], v[168:171], v[240:243], v[70:73]
	v_mfma_f32_16x16x32_bf16 v[94:97], v[172:175], v[206:209], v[94:97]
	v_mfma_f32_16x16x32_bf16 v[90:93], v[180:183], v[206:209], v[90:93]
	v_mfma_f32_16x16x32_bf16 v[82:85], v[180:183], v[214:217], v[82:85]
	v_mfma_f32_16x16x32_bf16 v[86:89], v[172:175], v[214:217], v[86:89]
	v_mfma_f32_16x16x32_bf16 v[78:81], v[172:175], v[236:239], v[78:81]
	v_mfma_f32_16x16x32_bf16 v[74:77], v[180:183], v[236:239], v[74:77]
	v_mfma_f32_16x16x32_bf16 v[66:69], v[180:183], v[244:247], v[66:69]
	v_mfma_f32_16x16x32_bf16 v[70:73], v[172:175], v[244:247], v[70:73]
	s_barrier
; #define PG8_STAGE(bufoff, gbase, voff) do { _Pragma("unroll") for (int _i = 0; _i < 2; ++_i) \
;         __builtin_amdgcn_global_load_lds((const unsigned*)((const char*)(gbase) + (voff)[_i]), (PG8_LAS unsigned*)(lds + (bufoff) + ldsw + _i * 8192), 16, 0, 0); } while (0)
; #define PG8_LDA(dst, b, h) do { _Pragma("unroll") for (int m = 0; m < 4; ++m) _Pragma("unroll") for (int k = 0; k < 2; ++k) dst[m][k] = *(const PG8_LAS bf16x8*)(lds + PG8_SA(b, h) + aoff + m * 2048 + k * 1024); } while (0)
; #define PG8_LDB(dst, b, h) do { _Pragma("unroll") for (int n = 0; n < 2; ++n) _Pragma("unroll") for (int k = 0; k < 2; ++k) dst[n][k] = *(const PG8_LAS bf16x8*)(lds + PG8_SB(b, h) + boff + n * 2048 + k * 1024); } while (0)
; template <class Epi, class Sched, bool ALIGN_EPI = false, bool SP2 = false>
; __device__ __forceinline__ void gemm_phase(PG8_LAS unsigned char* lds, const Gemm g, const Sched& S, const Epi& E) {
;     ...
;         for (int t = 0; t < nt; t += 2) {
;             const bool last = (t == nt - 2);
;             const char* a1 = cA + (size_t)(t + 1) * kstep;
;             const char* a2 = last ? nA : cA + (size_t)(t + 2) * kstep; const char* b2 = last ? nB : cB + (size_t)(t + 2) * kstep;
;             const char* a3 = a2 + kstep; const char* b3 = b2 + kstep;
;             if (last && has_next) S.a_ready(nxt);
;             if constexpr (SP2) {
;             PG8_LDB(B0, 0, 0); PG8_LDB(B1, 0, 1); PG8_SCHED; PG8_LDA(At, 0, 0); PG8_STAGE(PG8_SA(1, 1), a1 + hstep, voffA);
;             PG8_WAIT_V(8); PG8_WAIT_L(0); PG8_BAR; PG8_MMA(0, 0, At, B0); PG8_MMA(0, 1, At, B1); PG8_BAR; PG8_SCHED;
;             PG8_LDA(At, 0, 1); PG8_STAGE(PG8_SB(0, 0), b2, voffB); PG8_STAGE(PG8_SB(0, 1), b2 + hstepB, voffB); PG8_STAGE(PG8_SA(0, 0), a2, voffA);
;             PG8_WAIT_V(8); PG8_WAIT_L(0); PG8_BAR; PG8_MMA(1, 0, At, B0); PG8_MMA(1, 1, At, B1); PG8_BAR; PG8_SCHED;
;             PG8_LDB(B0, 1, 0); PG8_LDB(B1, 1, 1); PG8_SCHED; PG8_LDA(At, 1, 0); PG8_STAGE(PG8_SA(0, 1), a2 + hstep, voffA);
;             PG8_WAIT_V(8); PG8_WAIT_L(0); PG8_BAR; PG8_MMA(0, 0, At, B0); PG8_MMA(0, 1, At, B1); PG8_BAR; PG8_SCHED;
;             PG8_LDA(At, 1, 1); PG8_STAGE(PG8_SB(1, 0), b3, voffB); PG8_STAGE(PG8_SB(1, 1), b3 + hstepB, voffB); PG8_STAGE(PG8_SA(1, 0), a3, voffA);
;             PG8_WAIT_V(8); PG8_WAIT_L(0); PG8_BAR; PG8_MMA(1, 0, At, B0); PG8_MMA(1, 1, At, B1); PG8_BAR; PG8_SCHED;
	s_add_i32 s9, s9, s42
	s_mov_b32 m0, s9
	ds_read_b128 v[194:197], v151 offset:49152
	ds_read_b128 v[206:209], v151 offset:50176
	ds_read_b128 v[210:213], v151 offset:51200
	ds_read_b128 v[214:217], v151 offset:52224
	ds_read_b128 v[218:221], v151 offset:53248
	ds_read_b128 v[236:239], v151 offset:54272
	ds_read_b128 v[240:243], v151 offset:55296
	ds_read_b128 v[244:247], v151 offset:56320
	s_add_u32 s100, s84, s60
	s_addc_u32 s101, s85, s61
	global_load_lds_dwordx4 v130, s[100:101]
	s_add_i32 m0, s9, 0x2000
	s_add_u32 s10, s84, 0x20080
	s_addc_u32 s11, s85, 0
	s_add_i32 s9, s12, s42
	global_load_lds_dwordx4 v134, s[100:101]
	s_mov_b32 m0, s9
	s_nop 0
	global_load_lds_dwordx4 v130, s[10:11]
	s_add_i32 m0, s9, 0x2000
	s_nop 0
	global_load_lds_dwordx4 v134, s[10:11]
	s_mov_b32 m0, s82
	s_add_u32 s100, s92, s60
	s_addc_u32 s101, s93, s61
	global_load_lds_dwordx4 v190, s[100:101]
	s_mov_b32 m0, s86
	s_nop 0
	global_load_lds_dwordx4 v132, s[100:101]
	s_waitcnt vmcnt(8)
	s_waitcnt lgkmcnt(0)
	s_barrier
	v_mfma_f32_16x16x32_bf16 v[62:65], v[152:155], v[194:197], v[62:65]
	v_mfma_f32_16x16x32_bf16 v[58:61], v[160:163], v[194:197], v[58:61]
	v_mfma_f32_16x16x32_bf16 v[50:53], v[160:163], v[210:213], v[50:53]
	v_mfma_f32_16x16x32_bf16 v[54:57], v[152:155], v[210:213], v[54:57]
	v_mfma_f32_16x16x32_bf16 v[46:49], v[152:155], v[218:221], v[46:49]
	v_mfma_f32_16x16x32_bf16 v[42:45], v[160:163], v[218:221], v[42:45]
	v_mfma_f32_16x16x32_bf16 v[34:37], v[160:163], v[240:243], v[34:37]
	v_mfma_f32_16x16x32_bf16 v[38:41], v[152:155], v[240:243], v[38:41]
	v_mfma_f32_16x16x32_bf16 v[62:65], v[156:159], v[206:209], v[62:65]
	v_mfma_f32_16x16x32_bf16 v[58:61], v[164:167], v[206:209], v[58:61]
	v_mfma_f32_16x16x32_bf16 v[50:53], v[164:167], v[214:217], v[50:53]
	v_mfma_f32_16x16x32_bf16 v[54:57], v[156:159], v[214:217], v[54:57]
	v_mfma_f32_16x16x32_bf16 v[46:49], v[156:159], v[236:239], v[46:49]
	v_mfma_f32_16x16x32_bf16 v[42:45], v[164:167], v[236:239], v[42:45]
	v_mfma_f32_16x16x32_bf16 v[34:37], v[164:167], v[244:247], v[34:37]
	v_mfma_f32_16x16x32_bf16 v[38:41], v[156:159], v[244:247], v[38:41]
	v_mfma_f32_16x16x32_bf16 v[30:33], v[168:171], v[194:197], v[30:33]
	v_mfma_f32_16x16x32_bf16 v[26:29], v[176:179], v[194:197], v[26:29]
	v_mfma_f32_16x16x32_bf16 v[18:21], v[176:179], v[210:213], v[18:21]
	v_mfma_f32_16x16x32_bf16 v[22:25], v[168:171], v[210:213], v[22:25]
	v_mfma_f32_16x16x32_bf16 v[14:17], v[168:171], v[218:221], v[14:17]
	v_mfma_f32_16x16x32_bf16 v[10:13], v[176:179], v[218:221], v[10:13]
	v_mfma_f32_16x16x32_bf16 v[2:5], v[176:179], v[240:243], v[2:5]
	v_mfma_f32_16x16x32_bf16 v[6:9], v[168:171], v[240:243], v[6:9]
	v_mfma_f32_16x16x32_bf16 v[30:33], v[172:175], v[206:209], v[30:33]
	v_mfma_f32_16x16x32_bf16 v[26:29], v[180:183], v[206:209], v[26:29]
	v_mfma_f32_16x16x32_bf16 v[18:21], v[180:183], v[214:217], v[18:21]
	v_mfma_f32_16x16x32_bf16 v[22:25], v[172:175], v[214:217], v[22:25]
	v_mfma_f32_16x16x32_bf16 v[14:17], v[172:175], v[236:239], v[14:17]
	v_mfma_f32_16x16x32_bf16 v[10:13], v[180:183], v[236:239], v[10:13]
	v_mfma_f32_16x16x32_bf16 v[2:5], v[180:183], v[244:247], v[2:5]
	v_mfma_f32_16x16x32_bf16 v[6:9], v[172:175], v[244:247], v[6:9]
	s_barrier
	s_add_i32 s8, s8, 2
	s_add_u32 s80, s80, 0x100
	s_addc_u32 s81, s81, 0
	s_cmp_gt_u32 s8, 29
.LBB0_1233:
	s_add_u32 s9, s68, s80
	s_addc_u32 s10, s69, s81
	s_add_u32 s9, s9, 0x100
	s_addc_u32 s10, s10, 0
	s_add_u32 s100, s9, 0x7ff80
	s_addc_u32 s101, s10, 0
	s_add_u32 s11, s36, s80
	s_addc_u32 s12, s37, s81
	s_add_i32 s13, 0, 0x10000
	s_cmpk_eq_i32 s80, 0xf00
	s_cselect_b32 s93, s4, s10
	s_cselect_b32 s92, s5, s9
	s_cselect_b32 s85, s6, s12
	s_cselect_b32 s84, s7, s11
	s_add_i32 s9, 0, 0x14000
	ds_read_b128 v[152:155], v186
	ds_read_b128 v[156:159], v186 offset:1024
	ds_read_b128 v[160:163], v186 offset:2048
	ds_read_b128 v[164:167], v186 offset:3072
	ds_read_b128 v[168:171], v187
	ds_read_b128 v[172:175], v187 offset:1024
	ds_read_b128 v[176:179], v187 offset:2048
	ds_read_b128 v[180:183], v187 offset:3072
	s_add_i32 m0, s51, 0xc000
	ds_read_b128 v[206:209], v151
	ds_read_b128 v[210:213], v151 offset:1024
	ds_read_b128 v[214:217], v151 offset:2048
	ds_read_b128 v[218:221], v151 offset:3072
	ds_read_b128 v[236:239], v151 offset:4096
	ds_read_b128 v[240:243], v151 offset:5120
	ds_read_b128 v[244:247], v151 offset:6144
	ds_read_b128 v[194:197], v151 offset:7168
	global_load_lds_dwordx4 v136, s[100:101]
	s_add_i32 m0, s51, 0xe000
	s_nop 0
	global_load_lds_dwordx4 v138, s[100:101]
	s_waitcnt vmcnt(8)
	s_waitcnt lgkmcnt(0)
	s_barrier
; #define PG8_STAGE(bufoff, gbase, voff) do { _Pragma("unroll") for (int _i = 0; _i < 2; ++_i) \
;         __builtin_amdgcn_global_load_lds((const unsigned*)((const char*)(gbase) + (voff)[_i]), (PG8_LAS unsigned*)(lds + (bufoff) + ldsw + _i * 8192), 16, 0, 0); } while (0)
; #define PG8_LDA(dst, b, h) do { _Pragma("unroll") for (int m = 0; m < 4; ++m) _Pragma("unroll") for (int k = 0; k < 2; ++k) dst[m][k] = *(const PG8_LAS bf16x8*)(lds + PG8_SA(b, h) + aoff + m * 2048 + k * 1024); } while (0)
; #define PG8_MMA(ai, bj, At, Bt) do { __builtin_amdgcn_s_setprio(1); _Pragma("unroll") for (int m = 0; m < 4; ++m) _Pragma("unroll") for (int n = 0; n < 2; ++n) _Pragma("unroll") for (int k = 0; k < 2; ++k) \
;         acc[ai][bj][m][n] = __builtin_amdgcn_mfma_f32_16x16x32_bf16(Bt[n][k], At[m][k], acc[ai][bj][m][n], 0, 0, 0); __builtin_amdgcn_s_setprio(0); } while (0)
; #define PG8_WAIT_V(n) asm volatile("s_waitcnt vmcnt(" #n ")" ::: "memory")
; #define PG8_WAIT_L(n) asm volatile("s_waitcnt lgkmcnt(" #n ")" ::: "memory")
; #define PG8_BAR __builtin_amdgcn_s_barrier()
; #define PG8_SCHED __builtin_amdgcn_sched_barrier(0)
; template <class Epi, class Sched, bool ALIGN_EPI = false, bool SP2 = false>
; __device__ __forceinline__ void gemm_phase(PG8_LAS unsigned char* lds, const Gemm g, const Sched& S, const Epi& E) {
;     ...
;             PG8_WAIT_V(8); PG8_WAIT_L(0); PG8_BAR; PG8_MMA(0, 0, At, B0); PG8_MMA(0, 1, At, B1); PG8_BAR; PG8_SCHED;
;             PG8_LDA(At, 0, 1); PG8_STAGE(PG8_SB(0, 0), b2, voffB); PG8_STAGE(PG8_SB(0, 1), b2 + hstepB, voffB); PG8_STAGE(PG8_SA(0, 0), a2, voffA);
;             PG8_WAIT_V(8); PG8_WAIT_L(0); PG8_BAR; PG8_MMA(1, 0, At, B0); PG8_MMA(1, 1, At, B1); PG8_BAR; PG8_SCHED;
	v_mfma_f32_16x16x32_bf16 v[126:129], v[152:155], v[206:209], v[126:129]
	v_mfma_f32_16x16x32_bf16 v[122:125], v[160:163], v[206:209], v[122:125]
	v_mfma_f32_16x16x32_bf16 v[114:117], v[160:163], v[214:217], v[114:117]
	v_mfma_f32_16x16x32_bf16 v[118:121], v[152:155], v[214:217], v[118:121]
	v_mfma_f32_16x16x32_bf16 v[110:113], v[152:155], v[236:239], v[110:113]
	v_mfma_f32_16x16x32_bf16 v[106:109], v[160:163], v[236:239], v[106:109]
	v_mfma_f32_16x16x32_bf16 v[98:101], v[160:163], v[244:247], v[98:101]
	v_mfma_f32_16x16x32_bf16 v[102:105], v[152:155], v[244:247], v[102:105]
	v_mfma_f32_16x16x32_bf16 v[126:129], v[156:159], v[210:213], v[126:129]
	v_mfma_f32_16x16x32_bf16 v[122:125], v[164:167], v[210:213], v[122:125]
	v_mfma_f32_16x16x32_bf16 v[114:117], v[164:167], v[218:221], v[114:117]
	v_mfma_f32_16x16x32_bf16 v[118:121], v[156:159], v[218:221], v[118:121]
	v_mfma_f32_16x16x32_bf16 v[110:113], v[156:159], v[240:243], v[110:113]
	v_mfma_f32_16x16x32_bf16 v[106:109], v[164:167], v[240:243], v[106:109]
	v_mfma_f32_16x16x32_bf16 v[98:101], v[164:167], v[194:197], v[98:101]
	v_mfma_f32_16x16x32_bf16 v[102:105], v[156:159], v[194:197], v[102:105]
	v_mfma_f32_16x16x32_bf16 v[94:97], v[168:171], v[206:209], v[94:97]
	v_mfma_f32_16x16x32_bf16 v[90:93], v[176:179], v[206:209], v[90:93]
	v_mfma_f32_16x16x32_bf16 v[82:85], v[176:179], v[214:217], v[82:85]
	v_mfma_f32_16x16x32_bf16 v[86:89], v[168:171], v[214:217], v[86:89]
	v_mfma_f32_16x16x32_bf16 v[78:81], v[168:171], v[236:239], v[78:81]
	v_mfma_f32_16x16x32_bf16 v[74:77], v[176:179], v[236:239], v[74:77]
	v_mfma_f32_16x16x32_bf16 v[66:69], v[176:179], v[244:247], v[66:69]
	v_mfma_f32_16x16x32_bf16 v[70:73], v[168:171], v[244:247], v[70:73]
	v_mfma_f32_16x16x32_bf16 v[94:97], v[172:175], v[210:213], v[94:97]
	v_mfma_f32_16x16x32_bf16 v[90:93], v[180:183], v[210:213], v[90:93]
	v_mfma_f32_16x16x32_bf16 v[82:85], v[180:183], v[218:221], v[82:85]
	v_mfma_f32_16x16x32_bf16 v[86:89], v[172:175], v[218:221], v[86:89]
	v_mfma_f32_16x16x32_bf16 v[78:81], v[172:175], v[240:243], v[78:81]
	v_mfma_f32_16x16x32_bf16 v[74:77], v[180:183], v[240:243], v[74:77]
	v_mfma_f32_16x16x32_bf16 v[66:69], v[180:183], v[194:197], v[66:69]
	v_mfma_f32_16x16x32_bf16 v[70:73], v[172:175], v[194:197], v[70:73]
	s_barrier
	s_add_i32 s10, s13, s42
	s_mov_b32 m0, s10
	ds_read_b128 v[194:197], v151 offset:16384
	ds_read_b128 v[206:209], v151 offset:17408
	ds_read_b128 v[210:213], v151 offset:18432
	ds_read_b128 v[214:217], v151 offset:19456
	ds_read_b128 v[218:221], v151 offset:20480
	ds_read_b128 v[236:239], v151 offset:21504
	ds_read_b128 v[240:243], v151 offset:22528
	ds_read_b128 v[244:247], v151 offset:23552
	global_load_lds_dwordx4 v130, s[84:85]
	s_add_i32 m0, s10, 0x2000
	s_add_u32 s10, s84, 0x20000
	s_addc_u32 s11, s85, 0
	s_add_i32 s9, s9, s42
	global_load_lds_dwordx4 v134, s[84:85]
	s_mov_b32 m0, s9
	s_nop 0
	global_load_lds_dwordx4 v130, s[10:11]
	s_add_i32 m0, s9, 0x2000
	s_nop 0
	global_load_lds_dwordx4 v134, s[10:11]
	s_mov_b32 m0, s51
	s_nop 0
	global_load_lds_dwordx4 v190, s[92:93]
	s_mov_b32 m0, s67
	s_nop 0
	global_load_lds_dwordx4 v132, s[92:93]
	s_waitcnt vmcnt(8)
	s_waitcnt lgkmcnt(0)
	s_barrier
	v_mfma_f32_16x16x32_bf16 v[62:65], v[152:155], v[194:197], v[62:65]
	v_mfma_f32_16x16x32_bf16 v[58:61], v[160:163], v[194:197], v[58:61]
	v_mfma_f32_16x16x32_bf16 v[50:53], v[160:163], v[210:213], v[50:53]
	v_mfma_f32_16x16x32_bf16 v[54:57], v[152:155], v[210:213], v[54:57]
	v_mfma_f32_16x16x32_bf16 v[46:49], v[152:155], v[218:221], v[46:49]
	v_mfma_f32_16x16x32_bf16 v[42:45], v[160:163], v[218:221], v[42:45]
	v_mfma_f32_16x16x32_bf16 v[34:37], v[160:163], v[240:243], v[34:37]
	v_mfma_f32_16x16x32_bf16 v[38:41], v[152:155], v[240:243], v[38:41]
	v_mfma_f32_16x16x32_bf16 v[62:65], v[156:159], v[206:209], v[62:65]
	v_mfma_f32_16x16x32_bf16 v[58:61], v[164:167], v[206:209], v[58:61]
	v_mfma_f32_16x16x32_bf16 v[50:53], v[164:167], v[214:217], v[50:53]
	v_mfma_f32_16x16x32_bf16 v[54:57], v[156:159], v[214:217], v[54:57]
	v_mfma_f32_16x16x32_bf16 v[46:49], v[156:159], v[236:239], v[46:49]
	v_mfma_f32_16x16x32_bf16 v[42:45], v[164:167], v[236:239], v[42:45]
	v_mfma_f32_16x16x32_bf16 v[34:37], v[164:167], v[244:247], v[34:37]
	v_mfma_f32_16x16x32_bf16 v[38:41], v[156:159], v[244:247], v[38:41]
	v_mfma_f32_16x16x32_bf16 v[30:33], v[168:171], v[194:197], v[30:33]
	v_mfma_f32_16x16x32_bf16 v[26:29], v[176:179], v[194:197], v[26:29]
	v_mfma_f32_16x16x32_bf16 v[18:21], v[176:179], v[210:213], v[18:21]
	v_mfma_f32_16x16x32_bf16 v[22:25], v[168:171], v[210:213], v[22:25]
	v_mfma_f32_16x16x32_bf16 v[14:17], v[168:171], v[218:221], v[14:17]
	v_mfma_f32_16x16x32_bf16 v[10:13], v[176:179], v[218:221], v[10:13]
	v_mfma_f32_16x16x32_bf16 v[2:5], v[176:179], v[240:243], v[2:5]
	v_mfma_f32_16x16x32_bf16 v[6:9], v[168:171], v[240:243], v[6:9]
	v_mfma_f32_16x16x32_bf16 v[30:33], v[172:175], v[206:209], v[30:33]
	v_mfma_f32_16x16x32_bf16 v[26:29], v[180:183], v[206:209], v[26:29]
	v_mfma_f32_16x16x32_bf16 v[18:21], v[180:183], v[214:217], v[18:21]
	v_mfma_f32_16x16x32_bf16 v[22:25], v[172:175], v[214:217], v[22:25]
	v_mfma_f32_16x16x32_bf16 v[14:17], v[172:175], v[236:239], v[14:17]
	v_mfma_f32_16x16x32_bf16 v[10:13], v[180:183], v[236:239], v[10:13]
	v_mfma_f32_16x16x32_bf16 v[2:5], v[180:183], v[244:247], v[2:5]
	v_mfma_f32_16x16x32_bf16 v[6:9], v[172:175], v[244:247], v[6:9]
	s_barrier
; #define PG8_STAGE(bufoff, gbase, voff) do { _Pragma("unroll") for (int _i = 0; _i < 2; ++_i) \
;         __builtin_amdgcn_global_load_lds((const unsigned*)((const char*)(gbase) + (voff)[_i]), (PG8_LAS unsigned*)(lds + (bufoff) + ldsw + _i * 8192), 16, 0, 0); } while (0)
; #define PG8_LDA(dst, b, h) do { _Pragma("unroll") for (int m = 0; m < 4; ++m) _Pragma("unroll") for (int k = 0; k < 2; ++k) dst[m][k] = *(const PG8_LAS bf16x8*)(lds + PG8_SA(b, h) + aoff + m * 2048 + k * 1024); } while (0)
; #define PG8_LDB(dst, b, h) do { _Pragma("unroll") for (int n = 0; n < 2; ++n) _Pragma("unroll") for (int k = 0; k < 2; ++k) dst[n][k] = *(const PG8_LAS bf16x8*)(lds + PG8_SB(b, h) + boff + n * 2048 + k * 1024); } while (0)
; #define PG8_MMA(ai, bj, At, Bt) do { __builtin_amdgcn_s_setprio(1); _Pragma("unroll") for (int m = 0; m < 4; ++m) _Pragma("unroll") for (int n = 0; n < 2; ++n) _Pragma("unroll") for (int k = 0; k < 2; ++k) \
;         acc[ai][bj][m][n] = __builtin_amdgcn_mfma_f32_16x16x32_bf16(Bt[n][k], At[m][k], acc[ai][bj][m][n], 0, 0, 0); __builtin_amdgcn_s_setprio(0); } while (0)
; #define PG8_WAIT_V(n) asm volatile("s_waitcnt vmcnt(" #n ")" ::: "memory")
; #define PG8_WAIT_L(n) asm volatile("s_waitcnt lgkmcnt(" #n ")" ::: "memory")
; #define PG8_BAR __builtin_amdgcn_s_barrier()
; #define PG8_SCHED __builtin_amdgcn_sched_barrier(0)
; template <class Epi, class Sched, bool ALIGN_EPI = false, bool SP2 = false>
; __device__ __forceinline__ void gemm_phase(PG8_LAS unsigned char* lds, const Gemm g, const Sched& S, const Epi& E) {
;     ...
;             PG8_LDB(B0, 1, 0); PG8_LDB(B1, 1, 1); PG8_SCHED; PG8_LDA(At, 1, 0); PG8_STAGE(PG8_SA(0, 1), a2 + hstep, voffA);
;             PG8_WAIT_V(8); PG8_WAIT_L(0); PG8_BAR; PG8_MMA(0, 0, At, B0); PG8_MMA(0, 1, At, B1); PG8_BAR; PG8_SCHED;
;             PG8_LDA(At, 1, 1); PG8_STAGE(PG8_SB(1, 0), b3, voffB); PG8_STAGE(PG8_SB(1, 1), b3 + hstepB, voffB); PG8_STAGE(PG8_SA(1, 0), a3, voffA);
;             PG8_WAIT_V(8); PG8_WAIT_L(0); PG8_BAR; PG8_MMA(1, 0, At, B0); PG8_MMA(1, 1, At, B1); PG8_BAR; PG8_SCHED;
;     ...
;         if constexpr (ALIGN_EPI) { if (wr == 0) PG8_BAR; }
	s_add_i32 s9, 0, 0x18000
	s_add_i32 s12, 0, 0x1c000
	ds_read_b128 v[152:155], v198
	ds_read_b128 v[156:159], v198 offset:1024
	ds_read_b128 v[160:163], v198 offset:2048
	ds_read_b128 v[164:167], v198 offset:3072
	ds_read_b128 v[168:171], v199
	ds_read_b128 v[172:175], v199 offset:1024
	ds_read_b128 v[176:179], v199 offset:2048
	ds_read_b128 v[180:183], v199 offset:3072
	s_add_u32 s10, s92, 0x80000
	s_addc_u32 s11, s93, 0
	s_mov_b32 m0, s74
	ds_read_b128 v[194:197], v151 offset:32768
	ds_read_b128 v[206:209], v151 offset:33792
	ds_read_b128 v[210:213], v151 offset:34816
	ds_read_b128 v[214:217], v151 offset:35840
	ds_read_b128 v[218:221], v151 offset:36864
	ds_read_b128 v[236:239], v151 offset:37888
	ds_read_b128 v[240:243], v151 offset:38912
	ds_read_b128 v[244:247], v151 offset:39936
	global_load_lds_dwordx4 v190, s[10:11]
	s_mov_b32 m0, s75
	s_nop 0
	global_load_lds_dwordx4 v132, s[10:11]
	s_waitcnt vmcnt(8)
	s_waitcnt lgkmcnt(0)
	s_barrier
	v_mfma_f32_16x16x32_bf16 v[126:129], v[152:155], v[194:197], v[126:129]
	v_mfma_f32_16x16x32_bf16 v[122:125], v[160:163], v[194:197], v[122:125]
	v_mfma_f32_16x16x32_bf16 v[114:117], v[160:163], v[210:213], v[114:117]
	v_mfma_f32_16x16x32_bf16 v[118:121], v[152:155], v[210:213], v[118:121]
	v_mfma_f32_16x16x32_bf16 v[110:113], v[152:155], v[218:221], v[110:113]
	v_mfma_f32_16x16x32_bf16 v[106:109], v[160:163], v[218:221], v[106:109]
	v_mfma_f32_16x16x32_bf16 v[98:101], v[160:163], v[240:243], v[98:101]
	v_mfma_f32_16x16x32_bf16 v[102:105], v[152:155], v[240:243], v[102:105]
	v_mfma_f32_16x16x32_bf16 v[126:129], v[156:159], v[206:209], v[126:129]
	v_mfma_f32_16x16x32_bf16 v[122:125], v[164:167], v[206:209], v[122:125]
	v_mfma_f32_16x16x32_bf16 v[114:117], v[164:167], v[214:217], v[114:117]
	v_mfma_f32_16x16x32_bf16 v[118:121], v[156:159], v[214:217], v[118:121]
	v_mfma_f32_16x16x32_bf16 v[110:113], v[156:159], v[236:239], v[110:113]
	v_mfma_f32_16x16x32_bf16 v[106:109], v[164:167], v[236:239], v[106:109]
	v_mfma_f32_16x16x32_bf16 v[98:101], v[164:167], v[244:247], v[98:101]
	v_mfma_f32_16x16x32_bf16 v[102:105], v[156:159], v[244:247], v[102:105]
	v_mfma_f32_16x16x32_bf16 v[94:97], v[168:171], v[194:197], v[94:97]
	v_mfma_f32_16x16x32_bf16 v[90:93], v[176:179], v[194:197], v[90:93]
	v_mfma_f32_16x16x32_bf16 v[82:85], v[176:179], v[210:213], v[82:85]
	v_mfma_f32_16x16x32_bf16 v[86:89], v[168:171], v[210:213], v[86:89]
	v_mfma_f32_16x16x32_bf16 v[78:81], v[168:171], v[218:221], v[78:81]
	v_mfma_f32_16x16x32_bf16 v[74:77], v[176:179], v[218:221], v[74:77]
	v_mfma_f32_16x16x32_bf16 v[66:69], v[176:179], v[240:243], v[66:69]
	v_mfma_f32_16x16x32_bf16 v[70:73], v[168:171], v[240:243], v[70:73]
	v_mfma_f32_16x16x32_bf16 v[94:97], v[172:175], v[206:209], v[94:97]
	v_mfma_f32_16x16x32_bf16 v[90:93], v[180:183], v[206:209], v[90:93]
	v_mfma_f32_16x16x32_bf16 v[82:85], v[180:183], v[214:217], v[82:85]
	v_mfma_f32_16x16x32_bf16 v[86:89], v[172:175], v[214:217], v[86:89]
	v_mfma_f32_16x16x32_bf16 v[78:81], v[172:175], v[236:239], v[78:81]
	v_mfma_f32_16x16x32_bf16 v[74:77], v[180:183], v[236:239], v[74:77]
	v_mfma_f32_16x16x32_bf16 v[66:69], v[180:183], v[244:247], v[66:69]
	v_mfma_f32_16x16x32_bf16 v[70:73], v[172:175], v[244:247], v[70:73]
	s_barrier
	s_add_i32 s9, s9, s42
	s_mov_b32 m0, s9
	ds_read_b128 v[194:197], v151 offset:49152
	ds_read_b128 v[206:209], v151 offset:50176
	ds_read_b128 v[210:213], v151 offset:51200
	ds_read_b128 v[214:217], v151 offset:52224
	ds_read_b128 v[218:221], v151 offset:53248
	ds_read_b128 v[236:239], v151 offset:54272
	ds_read_b128 v[240:243], v151 offset:55296
	ds_read_b128 v[244:247], v151 offset:56320
	s_add_u32 s100, s84, s60
	s_addc_u32 s101, s85, s61
	global_load_lds_dwordx4 v130, s[100:101]
	s_add_i32 m0, s9, 0x2000
	s_add_u32 s10, s84, 0x20080
	s_addc_u32 s11, s85, 0
	s_add_i32 s9, s12, s42
	global_load_lds_dwordx4 v134, s[100:101]
	s_mov_b32 m0, s9
	s_nop 0
	global_load_lds_dwordx4 v130, s[10:11]
	s_add_i32 m0, s9, 0x2000
	s_nop 0
	global_load_lds_dwordx4 v134, s[10:11]
	s_mov_b32 m0, s82
	s_add_u32 s100, s92, s60
	s_addc_u32 s101, s93, s61
	global_load_lds_dwordx4 v190, s[100:101]
	s_mov_b32 m0, s86
	s_nop 0
	global_load_lds_dwordx4 v132, s[100:101]
	s_waitcnt vmcnt(8)
	s_waitcnt lgkmcnt(0)
	s_barrier
	v_mfma_f32_16x16x32_bf16 v[62:65], v[152:155], v[194:197], v[62:65]
	v_mfma_f32_16x16x32_bf16 v[58:61], v[160:163], v[194:197], v[58:61]
	v_mfma_f32_16x16x32_bf16 v[50:53], v[160:163], v[210:213], v[50:53]
	v_mfma_f32_16x16x32_bf16 v[54:57], v[152:155], v[210:213], v[54:57]
	v_mfma_f32_16x16x32_bf16 v[46:49], v[152:155], v[218:221], v[46:49]
	v_mfma_f32_16x16x32_bf16 v[42:45], v[160:163], v[218:221], v[42:45]
	v_mfma_f32_16x16x32_bf16 v[34:37], v[160:163], v[240:243], v[34:37]
	v_mfma_f32_16x16x32_bf16 v[38:41], v[152:155], v[240:243], v[38:41]
	v_mfma_f32_16x16x32_bf16 v[62:65], v[156:159], v[206:209], v[62:65]
	v_mfma_f32_16x16x32_bf16 v[58:61], v[164:167], v[206:209], v[58:61]
	v_mfma_f32_16x16x32_bf16 v[50:53], v[164:167], v[214:217], v[50:53]
	v_mfma_f32_16x16x32_bf16 v[54:57], v[156:159], v[214:217], v[54:57]
	v_mfma_f32_16x16x32_bf16 v[46:49], v[156:159], v[236:239], v[46:49]
	v_mfma_f32_16x16x32_bf16 v[42:45], v[164:167], v[236:239], v[42:45]
	v_mfma_f32_16x16x32_bf16 v[34:37], v[164:167], v[244:247], v[34:37]
	v_mfma_f32_16x16x32_bf16 v[38:41], v[156:159], v[244:247], v[38:41]
	v_mfma_f32_16x16x32_bf16 v[30:33], v[168:171], v[194:197], v[30:33]
	v_mfma_f32_16x16x32_bf16 v[26:29], v[176:179], v[194:197], v[26:29]
	v_mfma_f32_16x16x32_bf16 v[18:21], v[176:179], v[210:213], v[18:21]
	v_mfma_f32_16x16x32_bf16 v[22:25], v[168:171], v[210:213], v[22:25]
	v_mfma_f32_16x16x32_bf16 v[14:17], v[168:171], v[218:221], v[14:17]
	v_mfma_f32_16x16x32_bf16 v[10:13], v[176:179], v[218:221], v[10:13]
	v_mfma_f32_16x16x32_bf16 v[2:5], v[176:179], v[240:243], v[2:5]
	v_mfma_f32_16x16x32_bf16 v[6:9], v[168:171], v[240:243], v[6:9]
	v_mfma_f32_16x16x32_bf16 v[30:33], v[172:175], v[206:209], v[30:33]
	v_mfma_f32_16x16x32_bf16 v[26:29], v[180:183], v[206:209], v[26:29]
	v_mfma_f32_16x16x32_bf16 v[18:21], v[180:183], v[214:217], v[18:21]
	v_mfma_f32_16x16x32_bf16 v[22:25], v[172:175], v[214:217], v[22:25]
	v_mfma_f32_16x16x32_bf16 v[14:17], v[172:175], v[236:239], v[14:17]
	v_mfma_f32_16x16x32_bf16 v[10:13], v[180:183], v[236:239], v[10:13]
	v_mfma_f32_16x16x32_bf16 v[2:5], v[180:183], v[244:247], v[2:5]
	v_mfma_f32_16x16x32_bf16 v[6:9], v[172:175], v[244:247], v[6:9]
	s_barrier
	s_add_i32 s8, s8, 2
	s_add_u32 s80, s80, 0x100
	s_addc_u32 s81, s81, 0
	s_cmp_gt_u32 s8, 29
	s_cbranch_scc0 .LBB0_1233
	s_and_b64 vcc, exec, s[62:63]
	s_cbranch_vccz .LBB0_1236
	s_barrier
